# A/B: extra s_setprio 0/1 flip after every 8 MFMAs in the GEMM MFMA blocks; on top of v37
# speedup vs baseline: 1.0032x; 1.0032x over previous
; #define PG8_STAGE(bufoff, gbase, voff) do { _Pragma("unroll") for (int _i = 0; _i < 2; ++_i) \
;         __builtin_amdgcn_global_load_lds((const unsigned*)((const char*)(gbase) + (voff)[_i]), (PG8_LAS unsigned*)(lds + (bufoff) + ldsw + _i * 8192), 16, 0, 0); } while (0)
; #define PG8_LDA(dst, b, h) do { _Pragma("unroll") for (int m = 0; m < 4; ++m) _Pragma("unroll") for (int k = 0; k < 2; ++k) dst[m][k] = *(const PG8_LAS bf16x8*)(lds + PG8_SA(b, h) + aoff + m * 2048 + k * 1024); } while (0)
; #define PG8_LDB(dst, b, h) do { _Pragma("unroll") for (int n = 0; n < 2; ++n) _Pragma("unroll") for (int k = 0; k < 2; ++k) dst[n][k] = *(const PG8_LAS bf16x8*)(lds + PG8_SB(b, h) + boff + n * 2048 + k * 1024); } while (0)
; template <class Epi, class Sched, bool ALIGN_EPI = false, bool SP2 = false>
; __device__ __forceinline__ void gemm_phase(PG8_LAS unsigned char* lds, const Gemm g, const Sched& S, const Epi& E) {
;     ...
;         for (int t = 0; t < nt; t += 2) {
;             const bool last = (t == nt - 2);
;             const char* a1 = cA + (size_t)(t + 1) * kstep;
;             const char* a2 = last ? nA : cA + (size_t)(t + 2) * kstep; const char* b2 = last ? nB : cB + (size_t)(t + 2) * kstep;
;             const char* a3 = a2 + kstep; const char* b3 = b2 + kstep;
;             if (last && has_next) S.a_ready(nxt);
;             if constexpr (SP2) {
;             PG8_LDB(B0, 0, 0); PG8_LDB(B1, 0, 1); PG8_SCHED; PG8_LDA(At, 0, 0); PG8_STAGE(PG8_SA(1, 1), a1 + hstepA, voffA);
;             PG8_WAIT_V(8); PG8_WAIT_L(0); PG8_BAR; PG8_MMA(0, 0, At, B0); PG8_MMA(0, 1, At, B1); PG8_BAR; PG8_SCHED;
;             PG8_LDA(At, 0, 1); PG8_STAGE(PG8_SB(0, 0), b2, voffB); PG8_STAGE(PG8_SB(0, 1), b2 + hstepB, voffB); PG8_STAGE(PG8_SA(0, 0), a2, voffA);
;             PG8_WAIT_V(8); PG8_WAIT_L(0); PG8_BAR; PG8_MMA(1, 0, At, B0); PG8_MMA(1, 1, At, B1); PG8_BAR; PG8_SCHED;
;             PG8_LDB(B0, 1, 0); PG8_LDB(B1, 1, 1); PG8_SCHED; PG8_LDA(At, 1, 0); PG8_STAGE(PG8_SA(0, 1), a2 + hstepA, voffA);
;             PG8_WAIT_V(8); PG8_WAIT_L(0); PG8_BAR; PG8_MMA(0, 0, At, B0); PG8_MMA(0, 1, At, B1); PG8_BAR; PG8_SCHED;
;             PG8_LDA(At, 1, 1); PG8_STAGE(PG8_SB(1, 0), b3, voffB); PG8_STAGE(PG8_SB(1, 1), b3 + hstepB, voffB); PG8_STAGE(PG8_SA(1, 0), a3, voffA);
;             PG8_WAIT_V(8); PG8_WAIT_L(0); PG8_BAR; PG8_MMA(1, 0, At, B0); PG8_MMA(1, 1, At, B1); PG8_BAR; PG8_SCHED;
.LBB0_254:
	s_add_u32 s28, s26, 0xfffc0080
	s_addc_u32 s29, s27, -1
	s_add_i32 s53, 0, 0x10000
	s_cmp_eq_u32 s52, 12
	s_cselect_b32 s31, s7, s29
	s_cselect_b32 s30, s9, s28
	v_add_u32_e32 v150, s53, v153
	s_cselect_b32 s29, s19, s51
	s_cselect_b32 s28, s21, s50
	s_add_i32 s56, 0, 0x14000
	ds_read_b128 v[142:145], v150
	ds_read_b128 v[146:149], v150 offset:1024
	ds_read_b128 v[158:161], v150 offset:2048
	ds_read_b128 v[162:165], v150 offset:3072
	v_add_u32_e32 v150, s56, v153
	ds_read_b128 v[166:169], v150
	ds_read_b128 v[170:173], v150 offset:1024
	ds_read_b128 v[174:177], v150 offset:2048
	ds_read_b128 v[178:181], v150 offset:3072
	s_add_i32 m0, s40, 0xc000
	ds_read_b128 v[182:185], v156
	ds_read_b128 v[202:205], v156 offset:1024
	ds_read_b128 v[206:209], v156 offset:2048
	ds_read_b128 v[210:213], v156 offset:3072
	ds_read_b128 v[232:235], v156 offset:4096
	ds_read_b128 v[236:239], v156 offset:5120
	ds_read_b128 v[240:243], v156 offset:6144
	ds_read_b128 v[244:247], v156 offset:7168
	global_load_lds_dwordx4 v138, s[26:27]
	s_add_i32 m0, s40, 0xe000
	s_nop 0
	global_load_lds_dwordx4 v140, s[26:27]
	s_waitcnt vmcnt(8)
	s_waitcnt lgkmcnt(0)
	s_barrier
	s_setprio 1
	s_waitcnt lgkmcnt(0)
	v_mfma_f32_16x16x32_bf16 v[126:129], v[142:145], v[182:185], v[126:129]
	v_mfma_f32_16x16x32_bf16 v[122:125], v[158:161], v[182:185], v[122:125]
	v_mfma_f32_16x16x32_bf16 v[110:113], v[142:145], v[206:209], v[110:113]
	v_mfma_f32_16x16x32_bf16 v[106:109], v[158:161], v[206:209], v[106:109]
	v_mfma_f32_16x16x32_bf16 v[94:97], v[142:145], v[232:235], v[94:97]
	v_mfma_f32_16x16x32_bf16 v[90:93], v[158:161], v[232:235], v[90:93]
	v_mfma_f32_16x16x32_bf16 v[78:81], v[142:145], v[240:243], v[78:81]
	v_mfma_f32_16x16x32_bf16 v[74:77], v[158:161], v[240:243], v[74:77]
	s_setprio 0
	s_setprio 1
	v_mfma_f32_16x16x32_bf16 v[126:129], v[146:149], v[202:205], v[126:129]
	v_mfma_f32_16x16x32_bf16 v[122:125], v[162:165], v[202:205], v[122:125]
	v_mfma_f32_16x16x32_bf16 v[110:113], v[146:149], v[210:213], v[110:113]
	v_mfma_f32_16x16x32_bf16 v[106:109], v[162:165], v[210:213], v[106:109]
	v_mfma_f32_16x16x32_bf16 v[94:97], v[146:149], v[236:239], v[94:97]
	v_mfma_f32_16x16x32_bf16 v[90:93], v[162:165], v[236:239], v[90:93]
	v_mfma_f32_16x16x32_bf16 v[78:81], v[146:149], v[244:247], v[78:81]
	v_mfma_f32_16x16x32_bf16 v[74:77], v[162:165], v[244:247], v[74:77]
	s_setprio 0
	s_setprio 1
	v_mfma_f32_16x16x32_bf16 v[118:121], v[166:169], v[182:185], v[118:121]
	v_mfma_f32_16x16x32_bf16 v[114:117], v[174:177], v[182:185], v[114:117]
	v_mfma_f32_16x16x32_bf16 v[102:105], v[166:169], v[206:209], v[102:105]
	v_mfma_f32_16x16x32_bf16 v[98:101], v[174:177], v[206:209], v[98:101]
	v_mfma_f32_16x16x32_bf16 v[86:89], v[166:169], v[232:235], v[86:89]
	v_mfma_f32_16x16x32_bf16 v[82:85], v[174:177], v[232:235], v[82:85]
	v_mfma_f32_16x16x32_bf16 v[70:73], v[166:169], v[240:243], v[70:73]
	v_mfma_f32_16x16x32_bf16 v[66:69], v[174:177], v[240:243], v[66:69]
	s_setprio 0
	s_setprio 1
	v_mfma_f32_16x16x32_bf16 v[118:121], v[170:173], v[202:205], v[118:121]
	v_mfma_f32_16x16x32_bf16 v[114:117], v[178:181], v[202:205], v[114:117]
	v_mfma_f32_16x16x32_bf16 v[102:105], v[170:173], v[210:213], v[102:105]
	v_mfma_f32_16x16x32_bf16 v[98:101], v[178:181], v[210:213], v[98:101]
	v_mfma_f32_16x16x32_bf16 v[86:89], v[170:173], v[236:239], v[86:89]
	v_mfma_f32_16x16x32_bf16 v[82:85], v[178:181], v[236:239], v[82:85]
	v_mfma_f32_16x16x32_bf16 v[70:73], v[170:173], v[244:247], v[70:73]
	v_mfma_f32_16x16x32_bf16 v[66:69], v[178:181], v[244:247], v[66:69]
	s_setprio 0
	s_barrier
	s_add_i32 s53, s53, s39
	s_mov_b32 m0, s53
	ds_read_b128 v[182:185], v156 offset:16384
	ds_read_b128 v[202:205], v156 offset:17408
	ds_read_b128 v[206:209], v156 offset:18432
	ds_read_b128 v[210:213], v156 offset:19456
	ds_read_b128 v[232:235], v156 offset:20480
	ds_read_b128 v[236:239], v156 offset:21504
	ds_read_b128 v[240:243], v156 offset:22528
	ds_read_b128 v[244:247], v156 offset:23552
	s_add_u32 s60, s28, 0x80
	s_addc_u32 s61, s29, 0
	s_add_u32 s62, s30, 0x80
	s_addc_u32 s63, s31, 0
	global_load_lds_dwordx4 v132, s[28:29]
	s_add_i32 m0, s53, 0x2000
	s_add_u32 s54, s28, 0x40000
	s_addc_u32 s55, s29, 0
	s_add_i32 s53, s56, s39
	global_load_lds_dwordx4 v136, s[28:29]
	s_mov_b32 m0, s53
	s_nop 0
	global_load_lds_dwordx4 v132, s[54:55]
	s_add_i32 m0, s53, 0x2000
	s_nop 0
	global_load_lds_dwordx4 v136, s[54:55]
	s_mov_b32 m0, s40
	s_nop 0
	global_load_lds_dwordx4 v130, s[30:31]
	s_mov_b32 m0, s41
	s_nop 0
	global_load_lds_dwordx4 v134, s[30:31]
	s_waitcnt vmcnt(8)
	s_waitcnt lgkmcnt(0)
	s_barrier
; #define PG8_STAGE(bufoff, gbase, voff) do { _Pragma("unroll") for (int _i = 0; _i < 2; ++_i) \
;         __builtin_amdgcn_global_load_lds((const unsigned*)((const char*)(gbase) + (voff)[_i]), (PG8_LAS unsigned*)(lds + (bufoff) + ldsw + _i * 8192), 16, 0, 0); } while (0)
; #define PG8_LDA(dst, b, h) do { _Pragma("unroll") for (int m = 0; m < 4; ++m) _Pragma("unroll") for (int k = 0; k < 2; ++k) dst[m][k] = *(const PG8_LAS bf16x8*)(lds + PG8_SA(b, h) + aoff + m * 2048 + k * 1024); } while (0)
; #define PG8_LDB(dst, b, h) do { _Pragma("unroll") for (int n = 0; n < 2; ++n) _Pragma("unroll") for (int k = 0; k < 2; ++k) dst[n][k] = *(const PG8_LAS bf16x8*)(lds + PG8_SB(b, h) + boff + n * 2048 + k * 1024); } while (0)
; #define PG8_MMA(ai, bj, At, Bt) do { __builtin_amdgcn_s_setprio(1); _Pragma("unroll") for (int m = 0; m < 4; ++m) _Pragma("unroll") for (int n = 0; n < 2; ++n) _Pragma("unroll") for (int k = 0; k < 2; ++k) \
;         acc[ai][bj][m][n] = __builtin_amdgcn_mfma_f32_16x16x32_bf16(Bt[n][k], At[m][k], acc[ai][bj][m][n], 0, 0, 0); __builtin_amdgcn_s_setprio(0); } while (0)
; #define PG8_WAIT_V(n) asm volatile("s_waitcnt vmcnt(" #n ")" ::: "memory")
; template <class Epi, class Sched, bool ALIGN_EPI = false, bool SP2 = false>
; __device__ __forceinline__ void gemm_phase(PG8_LAS unsigned char* lds, const Gemm g, const Sched& S, const Epi& E) {
;     ...
;             PG8_LDB(B0, 0, 0); PG8_LDB(B1, 0, 1); PG8_SCHED; PG8_LDA(At, 0, 0); PG8_STAGE(PG8_SA(1, 1), a1 + hstepA, voffA);
;             PG8_WAIT_V(8); PG8_WAIT_L(0); PG8_BAR; PG8_MMA(0, 0, At, B0); PG8_MMA(0, 1, At, B1); PG8_BAR; PG8_SCHED;
;             PG8_LDA(At, 0, 1); PG8_STAGE(PG8_SB(0, 0), b2, voffB); PG8_STAGE(PG8_SB(0, 1), b2 + hstepB, voffB); PG8_STAGE(PG8_SA(0, 0), a2, voffA);
;             PG8_WAIT_V(8); PG8_WAIT_L(0); PG8_BAR; PG8_MMA(1, 0, At, B0); PG8_MMA(1, 1, At, B1); PG8_BAR; PG8_SCHED;
;             PG8_LDB(B0, 1, 0); PG8_LDB(B1, 1, 1); PG8_SCHED; PG8_LDA(At, 1, 0); PG8_STAGE(PG8_SA(0, 1), a2 + hstepA, voffA);
;             PG8_WAIT_V(8); PG8_WAIT_L(0); PG8_BAR; PG8_MMA(0, 0, At, B0); PG8_MMA(0, 1, At, B1); PG8_BAR; PG8_SCHED;
;             PG8_LDA(At, 1, 1); PG8_STAGE(PG8_SB(1, 0), b3, voffB); PG8_STAGE(PG8_SB(1, 1), b3 + hstepB, voffB); PG8_STAGE(PG8_SA(1, 0), a3, voffA);
;             PG8_WAIT_V(8); PG8_WAIT_L(0); PG8_BAR; PG8_MMA(1, 0, At, B0); PG8_MMA(1, 1, At, B1); PG8_BAR; PG8_SCHED;
	s_setprio 1
	s_waitcnt lgkmcnt(0)
	v_mfma_f32_16x16x32_bf16 v[62:65], v[142:145], v[182:185], v[62:65]
	v_mfma_f32_16x16x32_bf16 v[58:61], v[158:161], v[182:185], v[58:61]
	v_mfma_f32_16x16x32_bf16 v[46:49], v[142:145], v[206:209], v[46:49]
	v_mfma_f32_16x16x32_bf16 v[42:45], v[158:161], v[206:209], v[42:45]
	v_mfma_f32_16x16x32_bf16 v[30:33], v[142:145], v[232:235], v[30:33]
	v_mfma_f32_16x16x32_bf16 v[26:29], v[158:161], v[232:235], v[26:29]
	v_mfma_f32_16x16x32_bf16 v[14:17], v[142:145], v[240:243], v[14:17]
	v_mfma_f32_16x16x32_bf16 v[10:13], v[158:161], v[240:243], v[10:13]
	s_setprio 0
	s_setprio 1
	v_mfma_f32_16x16x32_bf16 v[62:65], v[146:149], v[202:205], v[62:65]
	v_mfma_f32_16x16x32_bf16 v[58:61], v[162:165], v[202:205], v[58:61]
	v_mfma_f32_16x16x32_bf16 v[46:49], v[146:149], v[210:213], v[46:49]
	v_mfma_f32_16x16x32_bf16 v[42:45], v[162:165], v[210:213], v[42:45]
	v_mfma_f32_16x16x32_bf16 v[30:33], v[146:149], v[236:239], v[30:33]
	v_mfma_f32_16x16x32_bf16 v[26:29], v[162:165], v[236:239], v[26:29]
	v_mfma_f32_16x16x32_bf16 v[14:17], v[146:149], v[244:247], v[14:17]
	v_mfma_f32_16x16x32_bf16 v[10:13], v[162:165], v[244:247], v[10:13]
	s_setprio 0
	s_setprio 1
	v_mfma_f32_16x16x32_bf16 v[54:57], v[166:169], v[182:185], v[54:57]
	v_mfma_f32_16x16x32_bf16 v[50:53], v[174:177], v[182:185], v[50:53]
	v_mfma_f32_16x16x32_bf16 v[38:41], v[166:169], v[206:209], v[38:41]
	v_mfma_f32_16x16x32_bf16 v[34:37], v[174:177], v[206:209], v[34:37]
	v_mfma_f32_16x16x32_bf16 v[22:25], v[166:169], v[232:235], v[22:25]
	v_mfma_f32_16x16x32_bf16 v[18:21], v[174:177], v[232:235], v[18:21]
	v_mfma_f32_16x16x32_bf16 v[6:9], v[166:169], v[240:243], v[6:9]
	v_mfma_f32_16x16x32_bf16 v[2:5], v[174:177], v[240:243], v[2:5]
	s_setprio 0
	s_setprio 1
	v_mfma_f32_16x16x32_bf16 v[54:57], v[170:173], v[202:205], v[54:57]
	v_mfma_f32_16x16x32_bf16 v[50:53], v[178:181], v[202:205], v[50:53]
	v_mfma_f32_16x16x32_bf16 v[38:41], v[170:173], v[210:213], v[38:41]
	v_mfma_f32_16x16x32_bf16 v[34:37], v[178:181], v[210:213], v[34:37]
	v_mfma_f32_16x16x32_bf16 v[22:25], v[170:173], v[236:239], v[22:25]
	v_mfma_f32_16x16x32_bf16 v[18:21], v[178:181], v[236:239], v[18:21]
	v_mfma_f32_16x16x32_bf16 v[6:9], v[170:173], v[244:247], v[6:9]
	v_mfma_f32_16x16x32_bf16 v[2:5], v[178:181], v[244:247], v[2:5]
	s_setprio 0
	s_barrier
	s_add_i32 s53, 0, 0x18000
	v_add_u32_e32 v157, s53, v153
	s_add_i32 s54, 0, 0x1c000
	ds_read_b128 v[142:145], v157
	ds_read_b128 v[146:149], v157 offset:1024
	ds_read_b128 v[158:161], v157 offset:2048
	ds_read_b128 v[162:165], v157 offset:3072
	v_add_u32_e32 v157, s54, v153
	ds_read_b128 v[166:169], v157
	ds_read_b128 v[170:173], v157 offset:1024
	ds_read_b128 v[174:177], v157 offset:2048
	ds_read_b128 v[178:181], v157 offset:3072
	s_add_u32 s30, s30, 0x40000
	s_addc_u32 s31, s31, 0
	s_mov_b32 m0, s42
	ds_read_b128 v[182:185], v156 offset:32768
	ds_read_b128 v[202:205], v156 offset:33792
	ds_read_b128 v[206:209], v156 offset:34816
	ds_read_b128 v[210:213], v156 offset:35840
	ds_read_b128 v[232:235], v156 offset:36864
	ds_read_b128 v[236:239], v156 offset:37888
	ds_read_b128 v[240:243], v156 offset:38912
	ds_read_b128 v[244:247], v156 offset:39936
	global_load_lds_dwordx4 v130, s[30:31]
	s_mov_b32 m0, s43
	s_nop 0
	global_load_lds_dwordx4 v134, s[30:31]
	s_waitcnt vmcnt(8)
	s_waitcnt lgkmcnt(0)
	s_barrier
	s_setprio 1
	s_waitcnt lgkmcnt(0)
	v_mfma_f32_16x16x32_bf16 v[126:129], v[142:145], v[182:185], v[126:129]
	v_mfma_f32_16x16x32_bf16 v[122:125], v[158:161], v[182:185], v[122:125]
	v_mfma_f32_16x16x32_bf16 v[110:113], v[142:145], v[206:209], v[110:113]
	v_mfma_f32_16x16x32_bf16 v[106:109], v[158:161], v[206:209], v[106:109]
	v_mfma_f32_16x16x32_bf16 v[94:97], v[142:145], v[232:235], v[94:97]
	v_mfma_f32_16x16x32_bf16 v[90:93], v[158:161], v[232:235], v[90:93]
	v_mfma_f32_16x16x32_bf16 v[78:81], v[142:145], v[240:243], v[78:81]
	v_mfma_f32_16x16x32_bf16 v[74:77], v[158:161], v[240:243], v[74:77]
	s_setprio 0
	s_setprio 1
	v_mfma_f32_16x16x32_bf16 v[126:129], v[146:149], v[202:205], v[126:129]
	v_mfma_f32_16x16x32_bf16 v[122:125], v[162:165], v[202:205], v[122:125]
	v_mfma_f32_16x16x32_bf16 v[110:113], v[146:149], v[210:213], v[110:113]
	v_mfma_f32_16x16x32_bf16 v[106:109], v[162:165], v[210:213], v[106:109]
	v_mfma_f32_16x16x32_bf16 v[94:97], v[146:149], v[236:239], v[94:97]
	v_mfma_f32_16x16x32_bf16 v[90:93], v[162:165], v[236:239], v[90:93]
	v_mfma_f32_16x16x32_bf16 v[78:81], v[146:149], v[244:247], v[78:81]
	v_mfma_f32_16x16x32_bf16 v[74:77], v[162:165], v[244:247], v[74:77]
	s_setprio 0
	s_setprio 1
	v_mfma_f32_16x16x32_bf16 v[118:121], v[166:169], v[182:185], v[118:121]
	v_mfma_f32_16x16x32_bf16 v[114:117], v[174:177], v[182:185], v[114:117]
	v_mfma_f32_16x16x32_bf16 v[102:105], v[166:169], v[206:209], v[102:105]
	v_mfma_f32_16x16x32_bf16 v[98:101], v[174:177], v[206:209], v[98:101]
	v_mfma_f32_16x16x32_bf16 v[86:89], v[166:169], v[232:235], v[86:89]
	v_mfma_f32_16x16x32_bf16 v[82:85], v[174:177], v[232:235], v[82:85]
	v_mfma_f32_16x16x32_bf16 v[70:73], v[166:169], v[240:243], v[70:73]
	v_mfma_f32_16x16x32_bf16 v[66:69], v[174:177], v[240:243], v[66:69]
	s_setprio 0
	s_setprio 1
	v_mfma_f32_16x16x32_bf16 v[118:121], v[170:173], v[202:205], v[118:121]
	v_mfma_f32_16x16x32_bf16 v[114:117], v[178:181], v[202:205], v[114:117]
	v_mfma_f32_16x16x32_bf16 v[102:105], v[170:173], v[210:213], v[102:105]
	v_mfma_f32_16x16x32_bf16 v[98:101], v[178:181], v[210:213], v[98:101]
	v_mfma_f32_16x16x32_bf16 v[86:89], v[170:173], v[236:239], v[86:89]
	v_mfma_f32_16x16x32_bf16 v[82:85], v[178:181], v[236:239], v[82:85]
	v_mfma_f32_16x16x32_bf16 v[70:73], v[170:173], v[244:247], v[70:73]
	v_mfma_f32_16x16x32_bf16 v[66:69], v[178:181], v[244:247], v[66:69]
	s_setprio 0
	s_barrier
; #define PG8_STAGE(bufoff, gbase, voff) do { _Pragma("unroll") for (int _i = 0; _i < 2; ++_i) \
;         __builtin_amdgcn_global_load_lds((const unsigned*)((const char*)(gbase) + (voff)[_i]), (PG8_LAS unsigned*)(lds + (bufoff) + ldsw + _i * 8192), 16, 0, 0); } while (0)
; #define PG8_LDA(dst, b, h) do { _Pragma("unroll") for (int m = 0; m < 4; ++m) _Pragma("unroll") for (int k = 0; k < 2; ++k) dst[m][k] = *(const PG8_LAS bf16x8*)(lds + PG8_SA(b, h) + aoff + m * 2048 + k * 1024); } while (0)
; #define PG8_MMA(ai, bj, At, Bt) do { __builtin_amdgcn_s_setprio(1); _Pragma("unroll") for (int m = 0; m < 4; ++m) _Pragma("unroll") for (int n = 0; n < 2; ++n) _Pragma("unroll") for (int k = 0; k < 2; ++k) \
;         acc[ai][bj][m][n] = __builtin_amdgcn_mfma_f32_16x16x32_bf16(Bt[n][k], At[m][k], acc[ai][bj][m][n], 0, 0, 0); __builtin_amdgcn_s_setprio(0); } while (0)
; #define PG8_WAIT_V(n) asm volatile("s_waitcnt vmcnt(" #n ")" ::: "memory")
; #define PG8_WAIT_L(n) asm volatile("s_waitcnt lgkmcnt(" #n ")" ::: "memory")
; #define PG8_BAR __builtin_amdgcn_s_barrier()
; #define PG8_SCHED __builtin_amdgcn_sched_barrier(0)
; template <class Epi, class Sched, bool ALIGN_EPI = false, bool SP2 = false>
; __device__ __forceinline__ void gemm_phase(PG8_LAS unsigned char* lds, const Gemm g, const Sched& S, const Epi& E) {
;     ...
;             PG8_LDA(At, 1, 1); PG8_STAGE(PG8_SB(1, 0), b3, voffB); PG8_STAGE(PG8_SB(1, 1), b3 + hstepB, voffB); PG8_STAGE(PG8_SA(1, 0), a3, voffA);
;             PG8_WAIT_V(8); PG8_WAIT_L(0); PG8_BAR; PG8_MMA(1, 0, At, B0); PG8_MMA(1, 1, At, B1); PG8_BAR; PG8_SCHED;
	s_add_i32 s30, s53, s39
	s_mov_b32 m0, s30
	ds_read_b128 v[182:185], v156 offset:49152
	ds_read_b128 v[202:205], v156 offset:50176
	ds_read_b128 v[206:209], v156 offset:51200
	ds_read_b128 v[210:213], v156 offset:52224
	ds_read_b128 v[232:235], v156 offset:53248
	ds_read_b128 v[236:239], v156 offset:54272
	ds_read_b128 v[240:243], v156 offset:55296
	ds_read_b128 v[244:247], v156 offset:56320
	global_load_lds_dwordx4 v132, s[60:61]
	s_add_i32 m0, s30, 0x2000
	s_add_u32 s28, s28, 0x40080
	s_addc_u32 s29, s29, 0
	s_add_i32 s30, s54, s39
	global_load_lds_dwordx4 v136, s[60:61]
	s_mov_b32 m0, s30
	s_nop 0
	global_load_lds_dwordx4 v132, s[28:29]
	s_add_i32 m0, s30, 0x2000
	s_nop 0
	global_load_lds_dwordx4 v136, s[28:29]
	s_mov_b32 m0, s45
	s_nop 0
	global_load_lds_dwordx4 v130, s[62:63]
	s_mov_b32 m0, s46
	s_nop 0
	global_load_lds_dwordx4 v134, s[62:63]
	s_waitcnt vmcnt(8)
	s_waitcnt lgkmcnt(0)
	s_barrier
	s_setprio 1
	s_waitcnt lgkmcnt(0)
	v_mfma_f32_16x16x32_bf16 v[62:65], v[142:145], v[182:185], v[62:65]
	v_mfma_f32_16x16x32_bf16 v[58:61], v[158:161], v[182:185], v[58:61]
	v_mfma_f32_16x16x32_bf16 v[46:49], v[142:145], v[206:209], v[46:49]
	v_mfma_f32_16x16x32_bf16 v[42:45], v[158:161], v[206:209], v[42:45]
	v_mfma_f32_16x16x32_bf16 v[30:33], v[142:145], v[232:235], v[30:33]
	v_mfma_f32_16x16x32_bf16 v[26:29], v[158:161], v[232:235], v[26:29]
	v_mfma_f32_16x16x32_bf16 v[14:17], v[142:145], v[240:243], v[14:17]
	v_mfma_f32_16x16x32_bf16 v[10:13], v[158:161], v[240:243], v[10:13]
	s_setprio 0
	s_setprio 1
	v_mfma_f32_16x16x32_bf16 v[62:65], v[146:149], v[202:205], v[62:65]
	v_mfma_f32_16x16x32_bf16 v[58:61], v[162:165], v[202:205], v[58:61]
	v_mfma_f32_16x16x32_bf16 v[46:49], v[146:149], v[210:213], v[46:49]
	v_mfma_f32_16x16x32_bf16 v[42:45], v[162:165], v[210:213], v[42:45]
	v_mfma_f32_16x16x32_bf16 v[30:33], v[146:149], v[236:239], v[30:33]
	v_mfma_f32_16x16x32_bf16 v[26:29], v[162:165], v[236:239], v[26:29]
	v_mfma_f32_16x16x32_bf16 v[14:17], v[146:149], v[244:247], v[14:17]
	v_mfma_f32_16x16x32_bf16 v[10:13], v[162:165], v[244:247], v[10:13]
	s_setprio 0
	s_setprio 1
	v_mfma_f32_16x16x32_bf16 v[54:57], v[166:169], v[182:185], v[54:57]
	v_mfma_f32_16x16x32_bf16 v[50:53], v[174:177], v[182:185], v[50:53]
	v_mfma_f32_16x16x32_bf16 v[38:41], v[166:169], v[206:209], v[38:41]
	v_mfma_f32_16x16x32_bf16 v[34:37], v[174:177], v[206:209], v[34:37]
	v_mfma_f32_16x16x32_bf16 v[22:25], v[166:169], v[232:235], v[22:25]
	v_mfma_f32_16x16x32_bf16 v[18:21], v[174:177], v[232:235], v[18:21]
	v_mfma_f32_16x16x32_bf16 v[6:9], v[166:169], v[240:243], v[6:9]
	v_mfma_f32_16x16x32_bf16 v[2:5], v[174:177], v[240:243], v[2:5]
	s_setprio 0
	s_setprio 1
	v_mfma_f32_16x16x32_bf16 v[54:57], v[170:173], v[202:205], v[54:57]
	v_mfma_f32_16x16x32_bf16 v[50:53], v[178:181], v[202:205], v[50:53]
	v_mfma_f32_16x16x32_bf16 v[38:41], v[170:173], v[210:213], v[38:41]
	v_mfma_f32_16x16x32_bf16 v[34:37], v[178:181], v[210:213], v[34:37]
	v_mfma_f32_16x16x32_bf16 v[22:25], v[170:173], v[236:239], v[22:25]
	v_mfma_f32_16x16x32_bf16 v[18:21], v[178:181], v[236:239], v[18:21]
	v_mfma_f32_16x16x32_bf16 v[6:9], v[170:173], v[244:247], v[6:9]
	v_mfma_f32_16x16x32_bf16 v[2:5], v[178:181], v[244:247], v[2:5]
	s_setprio 0
	s_barrier
	s_add_i32 s52, s52, 2
	s_add_u32 s26, s26, 0x100
	s_addc_u32 s27, s27, 0
	s_add_u32 s50, s50, 0x100
	s_addc_u32 s51, s51, 0
	s_cmp_gt_u32 s52, 13
	s_cbranch_scc0 .LBB0_254
	s_and_b64 vcc, exec, s[16:17]
	s_cbranch_vccz .LBB0_257
	s_barrier

; #define PG8_STAGE(bufoff, gbase, voff) do { _Pragma("unroll") for (int _i = 0; _i < 2; ++_i) \
;         __builtin_amdgcn_global_load_lds((const unsigned*)((const char*)(gbase) + (voff)[_i]), (PG8_LAS unsigned*)(lds + (bufoff) + ldsw + _i * 8192), 16, 0, 0); } while (0)
; #define PG8_LDA(dst, b, h) do { _Pragma("unroll") for (int m = 0; m < 4; ++m) _Pragma("unroll") for (int k = 0; k < 2; ++k) dst[m][k] = *(const PG8_LAS bf16x8*)(lds + PG8_SA(b, h) + aoff + m * 2048 + k * 1024); } while (0)
; #define PG8_LDB(dst, b, h) do { _Pragma("unroll") for (int n = 0; n < 2; ++n) _Pragma("unroll") for (int k = 0; k < 2; ++k) dst[n][k] = *(const PG8_LAS bf16x8*)(lds + PG8_SB(b, h) + boff + n * 2048 + k * 1024); } while (0)
; template <class Epi, class Sched, bool ALIGN_EPI = false, bool SP2 = false>
; __device__ __forceinline__ void gemm_phase(PG8_LAS unsigned char* lds, const Gemm g, const Sched& S, const Epi& E) {
;     ...
;         for (int t = 0; t < nt; t += 2) {
;             const bool last = (t == nt - 2);
;             const char* a1 = cA + (size_t)(t + 1) * kstep;
;             const char* a2 = last ? nA : cA + (size_t)(t + 2) * kstep; const char* b2 = last ? nB : cB + (size_t)(t + 2) * kstep;
;             const char* a3 = a2 + kstep; const char* b3 = b2 + kstep;
;             if (last && has_next) S.a_ready(nxt);
;             if constexpr (SP2) {
;             PG8_LDB(B0, 0, 0); PG8_LDB(B1, 0, 1); PG8_SCHED; PG8_LDA(At, 0, 0); PG8_STAGE(PG8_SA(1, 1), a1 + hstepA, voffA);
;             PG8_WAIT_V(8); PG8_WAIT_L(0); PG8_BAR; PG8_MMA(0, 0, At, B0); PG8_MMA(0, 1, At, B1); PG8_BAR; PG8_SCHED;
;             PG8_LDA(At, 0, 1); PG8_STAGE(PG8_SB(0, 0), b2, voffB); PG8_STAGE(PG8_SB(0, 1), b2 + hstepB, voffB); PG8_STAGE(PG8_SA(0, 0), a2, voffA);
;             PG8_WAIT_V(8); PG8_WAIT_L(0); PG8_BAR; PG8_MMA(1, 0, At, B0); PG8_MMA(1, 1, At, B1); PG8_BAR; PG8_SCHED;
;             PG8_LDB(B0, 1, 0); PG8_LDB(B1, 1, 1); PG8_SCHED; PG8_LDA(At, 1, 0); PG8_STAGE(PG8_SA(0, 1), a2 + hstepA, voffA);
;             PG8_WAIT_V(8); PG8_WAIT_L(0); PG8_BAR; PG8_MMA(0, 0, At, B0); PG8_MMA(0, 1, At, B1); PG8_BAR; PG8_SCHED;
;             PG8_LDA(At, 1, 1); PG8_STAGE(PG8_SB(1, 0), b3, voffB); PG8_STAGE(PG8_SB(1, 1), b3 + hstepB, voffB); PG8_STAGE(PG8_SA(1, 0), a3, voffA);
;             PG8_WAIT_V(8); PG8_WAIT_L(0); PG8_BAR; PG8_MMA(1, 0, At, B0); PG8_MMA(1, 1, At, B1); PG8_BAR; PG8_SCHED;
.LBB0_448:
	s_add_u32 s16, s38, s14
	s_addc_u32 s17, s39, s15
	s_add_u32 s16, s16, 0x4e00100
	s_addc_u32 s17, s17, 0
	s_add_u32 s43, s40, s14
	s_addc_u32 s44, s41, s15
	s_add_i32 s45, 0, 0x10000
	v_add_u32_e32 v96, s45, v82
	ds_read_b128 v[84:87], v96
	ds_read_b128 v[88:91], v96 offset:1024
	ds_read_b128 v[92:95], v96 offset:2048
	ds_read_b128 v[96:99], v96 offset:3072
	s_cmpk_eq_i32 s14, 0x700
	s_cselect_b32 s19, s13, s17
	s_cselect_b32 s18, s12, s16
	s_cselect_b32 s17, s5, s44
	s_cselect_b32 s16, s4, s43
	v_lshl_add_u64 v[132:133], v[76:77], 0, s[14:15]
	s_add_i32 m0, s25, 0xc000
	ds_read_b128 v[100:103], v83
	ds_read_b128 v[104:107], v83 offset:1024
	ds_read_b128 v[108:111], v83 offset:2048
	ds_read_b128 v[112:115], v83 offset:3072
	ds_read_b128 v[116:119], v83 offset:4096
	ds_read_b128 v[120:123], v83 offset:5120
	ds_read_b128 v[124:127], v83 offset:6144
	ds_read_b128 v[128:131], v83 offset:7168
	global_load_lds_dwordx4 v[132:133], off
	v_lshl_add_u64 v[132:133], v[78:79], 0, s[14:15]
	s_add_i32 m0, s25, 0xe000
	s_nop 0
	global_load_lds_dwordx4 v[132:133], off
	s_waitcnt vmcnt(8)
	s_waitcnt lgkmcnt(0)
	s_barrier
	s_setprio 1
	s_waitcnt lgkmcnt(0)
	v_mfma_f32_16x16x32_bf16 v[62:65], v[84:87], v[100:103], v[62:65]
	v_mfma_f32_16x16x32_bf16 v[58:61], v[92:95], v[100:103], v[58:61]
	v_mfma_f32_16x16x32_bf16 v[54:57], v[84:87], v[108:111], v[54:57]
	v_mfma_f32_16x16x32_bf16 v[50:53], v[92:95], v[108:111], v[50:53]
	v_mfma_f32_16x16x32_bf16 v[46:49], v[84:87], v[116:119], v[46:49]
	v_mfma_f32_16x16x32_bf16 v[42:45], v[92:95], v[116:119], v[42:45]
	v_mfma_f32_16x16x32_bf16 v[38:41], v[84:87], v[124:127], v[38:41]
	v_mfma_f32_16x16x32_bf16 v[34:37], v[92:95], v[124:127], v[34:37]
	s_setprio 0
	s_setprio 1
	v_mfma_f32_16x16x32_bf16 v[62:65], v[88:91], v[104:107], v[62:65]
	v_mfma_f32_16x16x32_bf16 v[58:61], v[96:99], v[104:107], v[58:61]
	v_mfma_f32_16x16x32_bf16 v[54:57], v[88:91], v[112:115], v[54:57]
	v_mfma_f32_16x16x32_bf16 v[50:53], v[96:99], v[112:115], v[50:53]
	v_mfma_f32_16x16x32_bf16 v[46:49], v[88:91], v[120:123], v[46:49]
	v_mfma_f32_16x16x32_bf16 v[42:45], v[96:99], v[120:123], v[42:45]
	v_mfma_f32_16x16x32_bf16 v[38:41], v[88:91], v[128:131], v[38:41]
	v_mfma_f32_16x16x32_bf16 v[34:37], v[96:99], v[128:131], v[34:37]
	s_setprio 0
	s_setprio 1
	s_setprio 0
	s_barrier
	s_add_i32 s43, s45, s24
	v_lshl_add_u64 v[132:133], s[16:17], 0, v[72:73]
	s_mov_b32 m0, s43
	ds_read_b128 v[100:103], v83 offset:16384
	ds_read_b128 v[104:107], v83 offset:17408
	ds_read_b128 v[108:111], v83 offset:18432
	ds_read_b128 v[112:115], v83 offset:19456
	ds_read_b128 v[116:119], v83 offset:20480
	ds_read_b128 v[120:123], v83 offset:21504
	ds_read_b128 v[124:127], v83 offset:22528
	ds_read_b128 v[128:131], v83 offset:23552
	global_load_lds_dwordx4 v[132:133], off
	s_add_i32 m0, s43, 0x2000
	s_add_u32 s44, s16, 0x40000
	v_lshl_add_u64 v[134:135], s[16:17], 0, v[68:69]
	s_addc_u32 s45, s17, 0
	global_load_lds_dwordx4 v[134:135], off
	v_lshl_add_u64 v[136:137], s[44:45], 0, v[72:73]
	s_mov_b32 m0, s26
	v_lshl_add_u64 v[138:139], s[18:19], 0, v[70:71]
	global_load_lds_dwordx4 v[136:137], off
	v_lshl_add_u64 v[136:137], s[44:45], 0, v[68:69]
	s_mov_b32 m0, s27
	s_nop 0
	global_load_lds_dwordx4 v[136:137], off
	v_lshl_add_u64 v[136:137], s[18:19], 0, v[74:75]
	s_mov_b32 m0, s25
	s_nop 0
	global_load_lds_dwordx4 v[136:137], off
	s_mov_b32 m0, s28
	s_nop 0
	global_load_lds_dwordx4 v[138:139], off
	s_waitcnt vmcnt(8)
	s_waitcnt lgkmcnt(0)
	s_barrier
	s_setprio 1
	s_waitcnt lgkmcnt(0)
	v_mfma_f32_16x16x32_bf16 v[30:33], v[84:87], v[100:103], v[30:33]
	v_mfma_f32_16x16x32_bf16 v[26:29], v[92:95], v[100:103], v[26:29]
	v_mfma_f32_16x16x32_bf16 v[22:25], v[84:87], v[108:111], v[22:25]
	v_mfma_f32_16x16x32_bf16 v[18:21], v[92:95], v[108:111], v[18:21]
	v_mfma_f32_16x16x32_bf16 v[14:17], v[84:87], v[116:119], v[14:17]
	v_mfma_f32_16x16x32_bf16 v[10:13], v[92:95], v[116:119], v[10:13]
	v_mfma_f32_16x16x32_bf16 v[6:9], v[84:87], v[124:127], v[6:9]
	v_mfma_f32_16x16x32_bf16 v[2:5], v[92:95], v[124:127], v[2:5]
	s_setprio 0
	s_setprio 1
	v_mfma_f32_16x16x32_bf16 v[30:33], v[88:91], v[104:107], v[30:33]
	v_mfma_f32_16x16x32_bf16 v[26:29], v[96:99], v[104:107], v[26:29]
	v_mfma_f32_16x16x32_bf16 v[22:25], v[88:91], v[112:115], v[22:25]
	v_mfma_f32_16x16x32_bf16 v[18:21], v[96:99], v[112:115], v[18:21]
	v_mfma_f32_16x16x32_bf16 v[14:17], v[88:91], v[120:123], v[14:17]
	v_mfma_f32_16x16x32_bf16 v[10:13], v[96:99], v[120:123], v[10:13]
	v_mfma_f32_16x16x32_bf16 v[6:9], v[88:91], v[128:131], v[6:9]
	v_mfma_f32_16x16x32_bf16 v[2:5], v[96:99], v[128:131], v[2:5]
	s_setprio 0
	s_setprio 1
	s_setprio 0
	s_barrier
; #define PG8_STAGE(bufoff, gbase, voff) do { _Pragma("unroll") for (int _i = 0; _i < 2; ++_i) \
;         __builtin_amdgcn_global_load_lds((const unsigned*)((const char*)(gbase) + (voff)[_i]), (PG8_LAS unsigned*)(lds + (bufoff) + ldsw + _i * 8192), 16, 0, 0); } while (0)
; #define PG8_LDA(dst, b, h) do { _Pragma("unroll") for (int m = 0; m < 4; ++m) _Pragma("unroll") for (int k = 0; k < 2; ++k) dst[m][k] = *(const PG8_LAS bf16x8*)(lds + PG8_SA(b, h) + aoff + m * 2048 + k * 1024); } while (0)
; #define PG8_LDB(dst, b, h) do { _Pragma("unroll") for (int n = 0; n < 2; ++n) _Pragma("unroll") for (int k = 0; k < 2; ++k) dst[n][k] = *(const PG8_LAS bf16x8*)(lds + PG8_SB(b, h) + boff + n * 2048 + k * 1024); } while (0)
; #define PG8_MMA(ai, bj, At, Bt) do { __builtin_amdgcn_s_setprio(1); _Pragma("unroll") for (int m = 0; m < 4; ++m) _Pragma("unroll") for (int n = 0; n < 2; ++n) _Pragma("unroll") for (int k = 0; k < 2; ++k) \
;         acc[ai][bj][m][n] = __builtin_amdgcn_mfma_f32_16x16x32_bf16(Bt[n][k], At[m][k], acc[ai][bj][m][n], 0, 0, 0); __builtin_amdgcn_s_setprio(0); } while (0)
; #define PG8_WAIT_V(n) asm volatile("s_waitcnt vmcnt(" #n ")" ::: "memory")
; template <class Epi, class Sched, bool ALIGN_EPI = false, bool SP2 = false>
; __device__ __forceinline__ void gemm_phase(PG8_LAS unsigned char* lds, const Gemm g, const Sched& S, const Epi& E) {
;     ...
;             PG8_LDB(B0, 0, 0); PG8_LDB(B1, 0, 1); PG8_SCHED; PG8_LDA(At, 0, 0); PG8_STAGE(PG8_SA(1, 1), a1 + hstepA, voffA);
;             PG8_WAIT_V(8); PG8_WAIT_L(0); PG8_BAR; PG8_MMA(0, 0, At, B0); PG8_MMA(0, 1, At, B1); PG8_BAR; PG8_SCHED;
;             PG8_LDA(At, 0, 1); PG8_STAGE(PG8_SB(0, 0), b2, voffB); PG8_STAGE(PG8_SB(0, 1), b2 + hstepB, voffB); PG8_STAGE(PG8_SA(0, 0), a2, voffA);
;             PG8_WAIT_V(8); PG8_WAIT_L(0); PG8_BAR; PG8_MMA(1, 0, At, B0); PG8_MMA(1, 1, At, B1); PG8_BAR; PG8_SCHED;
;             PG8_LDB(B0, 1, 0); PG8_LDB(B1, 1, 1); PG8_SCHED; PG8_LDA(At, 1, 0); PG8_STAGE(PG8_SA(0, 1), a2 + hstepA, voffA);
;             PG8_WAIT_V(8); PG8_WAIT_L(0); PG8_BAR; PG8_MMA(0, 0, At, B0); PG8_MMA(0, 1, At, B1); PG8_BAR; PG8_SCHED;
;             PG8_LDA(At, 1, 1); PG8_STAGE(PG8_SB(1, 0), b3, voffB); PG8_STAGE(PG8_SB(1, 1), b3 + hstepB, voffB); PG8_STAGE(PG8_SA(1, 0), a3, voffA);
;             PG8_WAIT_V(8); PG8_WAIT_L(0); PG8_BAR; PG8_MMA(1, 0, At, B0); PG8_MMA(1, 1, At, B1); PG8_BAR; PG8_SCHED;
	s_add_i32 s43, 0, 0x18000
	v_add_u32_e32 v96, s43, v82
	ds_read_b128 v[84:87], v96
	ds_read_b128 v[88:91], v96 offset:1024
	ds_read_b128 v[92:95], v96 offset:2048
	ds_read_b128 v[96:99], v96 offset:3072
	s_add_u32 s18, s18, 0x40000
	s_addc_u32 s19, s19, 0
	s_mov_b32 m0, s29
	v_lshl_add_u64 v[140:141], s[18:19], 0, v[74:75]
	ds_read_b128 v[100:103], v83 offset:32768
	ds_read_b128 v[104:107], v83 offset:33792
	ds_read_b128 v[108:111], v83 offset:34816
	ds_read_b128 v[112:115], v83 offset:35840
	ds_read_b128 v[116:119], v83 offset:36864
	ds_read_b128 v[120:123], v83 offset:37888
	ds_read_b128 v[124:127], v83 offset:38912
	ds_read_b128 v[128:131], v83 offset:39936
	global_load_lds_dwordx4 v[140:141], off
	v_lshl_add_u64 v[140:141], s[18:19], 0, v[70:71]
	s_mov_b32 m0, s30
	s_nop 0
	global_load_lds_dwordx4 v[140:141], off
	s_waitcnt vmcnt(8)
	s_waitcnt lgkmcnt(0)
	s_barrier
	s_setprio 1
	s_waitcnt lgkmcnt(0)
	v_mfma_f32_16x16x32_bf16 v[62:65], v[84:87], v[100:103], v[62:65]
	v_mfma_f32_16x16x32_bf16 v[58:61], v[92:95], v[100:103], v[58:61]
	v_mfma_f32_16x16x32_bf16 v[54:57], v[84:87], v[108:111], v[54:57]
	v_mfma_f32_16x16x32_bf16 v[50:53], v[92:95], v[108:111], v[50:53]
	v_mfma_f32_16x16x32_bf16 v[46:49], v[84:87], v[116:119], v[46:49]
	v_mfma_f32_16x16x32_bf16 v[42:45], v[92:95], v[116:119], v[42:45]
	v_mfma_f32_16x16x32_bf16 v[38:41], v[84:87], v[124:127], v[38:41]
	v_mfma_f32_16x16x32_bf16 v[34:37], v[92:95], v[124:127], v[34:37]
	s_setprio 0
	s_setprio 1
	v_mfma_f32_16x16x32_bf16 v[62:65], v[88:91], v[104:107], v[62:65]
	v_mfma_f32_16x16x32_bf16 v[58:61], v[96:99], v[104:107], v[58:61]
	v_mfma_f32_16x16x32_bf16 v[54:57], v[88:91], v[112:115], v[54:57]
	v_mfma_f32_16x16x32_bf16 v[50:53], v[96:99], v[112:115], v[50:53]
	v_mfma_f32_16x16x32_bf16 v[46:49], v[88:91], v[120:123], v[46:49]
	v_mfma_f32_16x16x32_bf16 v[42:45], v[96:99], v[120:123], v[42:45]
	v_mfma_f32_16x16x32_bf16 v[38:41], v[88:91], v[128:131], v[38:41]
	v_mfma_f32_16x16x32_bf16 v[34:37], v[96:99], v[128:131], v[34:37]
	s_setprio 0
	s_setprio 1
	s_setprio 0
	s_barrier
	s_add_i32 s18, s43, s24
	v_lshl_add_u64 v[132:133], v[132:133], 0, s[96:97]
	s_mov_b32 m0, s18
	ds_read_b128 v[100:103], v83 offset:49152
	ds_read_b128 v[104:107], v83 offset:50176
	ds_read_b128 v[108:111], v83 offset:51200
	ds_read_b128 v[112:115], v83 offset:52224
	ds_read_b128 v[116:119], v83 offset:53248
	ds_read_b128 v[120:123], v83 offset:54272
	ds_read_b128 v[124:127], v83 offset:55296
	ds_read_b128 v[128:131], v83 offset:56320
	global_load_lds_dwordx4 v[132:133], off
	s_add_i32 m0, s18, 0x2000
	s_add_u32 s16, s16, 0x40080
	v_lshl_add_u64 v[132:133], v[134:135], 0, s[96:97]
	s_addc_u32 s17, s17, 0
	global_load_lds_dwordx4 v[132:133], off
	v_lshl_add_u64 v[132:133], s[16:17], 0, v[72:73]
	s_mov_b32 m0, s36
	s_nop 0
	global_load_lds_dwordx4 v[132:133], off
	v_lshl_add_u64 v[132:133], s[16:17], 0, v[68:69]
	s_mov_b32 m0, s37
	s_nop 0
	global_load_lds_dwordx4 v[132:133], off
	v_lshl_add_u64 v[132:133], v[136:137], 0, s[96:97]
	s_mov_b32 m0, s34
	s_nop 0
	global_load_lds_dwordx4 v[132:133], off
	v_lshl_add_u64 v[132:133], v[138:139], 0, s[96:97]
	s_mov_b32 m0, s35
	s_nop 0
	global_load_lds_dwordx4 v[132:133], off
	s_waitcnt vmcnt(8)
	s_waitcnt lgkmcnt(0)
	s_barrier
	s_setprio 1
	s_waitcnt lgkmcnt(0)
	v_mfma_f32_16x16x32_bf16 v[30:33], v[84:87], v[100:103], v[30:33]
	v_mfma_f32_16x16x32_bf16 v[26:29], v[92:95], v[100:103], v[26:29]
	v_mfma_f32_16x16x32_bf16 v[22:25], v[84:87], v[108:111], v[22:25]
	v_mfma_f32_16x16x32_bf16 v[18:21], v[92:95], v[108:111], v[18:21]
	v_mfma_f32_16x16x32_bf16 v[14:17], v[84:87], v[116:119], v[14:17]
	v_mfma_f32_16x16x32_bf16 v[10:13], v[92:95], v[116:119], v[10:13]
	v_mfma_f32_16x16x32_bf16 v[6:9], v[84:87], v[124:127], v[6:9]
	v_mfma_f32_16x16x32_bf16 v[2:5], v[92:95], v[124:127], v[2:5]
	s_setprio 0
	s_setprio 1
	v_mfma_f32_16x16x32_bf16 v[30:33], v[88:91], v[104:107], v[30:33]
	v_mfma_f32_16x16x32_bf16 v[26:29], v[96:99], v[104:107], v[26:29]
	v_mfma_f32_16x16x32_bf16 v[22:25], v[88:91], v[112:115], v[22:25]
	v_mfma_f32_16x16x32_bf16 v[18:21], v[96:99], v[112:115], v[18:21]
	v_mfma_f32_16x16x32_bf16 v[14:17], v[88:91], v[120:123], v[14:17]
	v_mfma_f32_16x16x32_bf16 v[10:13], v[96:99], v[120:123], v[10:13]
	v_mfma_f32_16x16x32_bf16 v[6:9], v[88:91], v[128:131], v[6:9]
	v_mfma_f32_16x16x32_bf16 v[2:5], v[96:99], v[128:131], v[2:5]
	s_setprio 0
	s_setprio 1
	s_setprio 0
	s_barrier
	s_add_i32 s42, s42, 2
	s_add_u32 s14, s14, 0x100
	s_addc_u32 s15, s15, 0
	s_cmp_gt_u32 s42, 13
	s_cbranch_scc0 .LBB0_448
	s_cmpk_lt_u32 s23, 0x100
	s_cbranch_scc0 .LBB0_451
	s_barrier

; #define PG8_STAGE(bufoff, gbase, voff) do { _Pragma("unroll") for (int _i = 0; _i < 2; ++_i) \
;         __builtin_amdgcn_global_load_lds((const unsigned*)((const char*)(gbase) + (voff)[_i]), (PG8_LAS unsigned*)(lds + (bufoff) + ldsw + _i * 8192), 16, 0, 0); } while (0)
; #define PG8_LDA(dst, b, h) do { _Pragma("unroll") for (int m = 0; m < 4; ++m) _Pragma("unroll") for (int k = 0; k < 2; ++k) dst[m][k] = *(const PG8_LAS bf16x8*)(lds + PG8_SA(b, h) + aoff + m * 2048 + k * 1024); } while (0)
; #define PG8_LDB(dst, b, h) do { _Pragma("unroll") for (int n = 0; n < 2; ++n) _Pragma("unroll") for (int k = 0; k < 2; ++k) dst[n][k] = *(const PG8_LAS bf16x8*)(lds + PG8_SB(b, h) + boff + n * 2048 + k * 1024); } while (0)
; #define PG8_MMA(ai, bj, At, Bt) do { __builtin_amdgcn_s_setprio(1); _Pragma("unroll") for (int m = 0; m < 4; ++m) _Pragma("unroll") for (int n = 0; n < 2; ++n) _Pragma("unroll") for (int k = 0; k < 2; ++k) \
;         acc[ai][bj][m][n] = __builtin_amdgcn_mfma_f32_16x16x32_bf16(Bt[n][k], At[m][k], acc[ai][bj][m][n], 0, 0, 0); __builtin_amdgcn_s_setprio(0); } while (0)
; #define PG8_WAIT_V(n) asm volatile("s_waitcnt vmcnt(" #n ")" ::: "memory")
; #define PG8_BAR __builtin_amdgcn_s_barrier()
; template <class Epi, class Sched, bool ALIGN_EPI = false, bool SP2 = false>
; __device__ __forceinline__ void gemm_phase(PG8_LAS unsigned char* lds, const Gemm g, const Sched& S, const Epi& E) {
;     ...
;         for (int t = 0; t < nt; t += 2) {
;             const bool last = (t == nt - 2);
;             const char* a1 = cA + (size_t)(t + 1) * kstep;
;             const char* a2 = last ? nA : cA + (size_t)(t + 2) * kstep; const char* b2 = last ? nB : cB + (size_t)(t + 2) * kstep;
;             const char* a3 = a2 + kstep; const char* b3 = b2 + kstep;
;             if (last && has_next) S.a_ready(nxt);
;             if constexpr (SP2) {
;             PG8_LDB(B0, 0, 0); PG8_LDB(B1, 0, 1); PG8_SCHED; PG8_LDA(At, 0, 0); PG8_STAGE(PG8_SA(1, 1), a1 + hstepA, voffA);
;             PG8_WAIT_V(8); PG8_WAIT_L(0); PG8_BAR; PG8_MMA(0, 0, At, B0); PG8_MMA(0, 1, At, B1); PG8_BAR; PG8_SCHED;
;             PG8_LDA(At, 0, 1); PG8_STAGE(PG8_SB(0, 0), b2, voffB); PG8_STAGE(PG8_SB(0, 1), b2 + hstepB, voffB); PG8_STAGE(PG8_SA(0, 0), a2, voffA);
;             PG8_WAIT_V(8); PG8_WAIT_L(0); PG8_BAR; PG8_MMA(1, 0, At, B0); PG8_MMA(1, 1, At, B1); PG8_BAR; PG8_SCHED;
.LBB0_530:
	s_add_u32 s12, s1, s8
	s_addc_u32 s13, s28, s9
	s_add_u32 s12, s12, 0xfe00100
	s_addc_u32 s13, s13, 0
	s_add_u32 s34, s29, s8
	s_addc_u32 s35, s30, s9
	s_add_i32 s36, 0, 0x10000
	s_cmpk_eq_i32 s8, 0x700
	s_cselect_b32 s15, s7, s13
	s_cselect_b32 s14, s6, s12
	v_add_u32_e32 v145, s36, v143
	s_cselect_b32 s13, s5, s35
	s_cselect_b32 s12, s4, s34
	s_add_i32 s37, 0, 0x14000
	ds_read_b128 v[146:149], v145
	ds_read_b128 v[150:153], v145 offset:1024
	ds_read_b128 v[154:157], v145 offset:2048
	ds_read_b128 v[158:161], v145 offset:3072
	v_add_u32_e32 v145, s37, v143
	ds_read_b128 v[162:165], v145
	ds_read_b128 v[166:169], v145 offset:1024
	ds_read_b128 v[170:173], v145 offset:2048
	ds_read_b128 v[174:177], v145 offset:3072
	v_lshl_add_u64 v[186:187], v[138:139], 0, s[8:9]
	s_add_i32 m0, s21, 0xc000
	ds_read_b128 v[178:181], v144
	ds_read_b128 v[182:185], v144 offset:1024
	ds_read_b128 v[202:205], v144 offset:2048
	ds_read_b128 v[206:209], v144 offset:3072
	ds_read_b128 v[210:213], v144 offset:4096
	ds_read_b128 v[232:235], v144 offset:5120
	ds_read_b128 v[236:239], v144 offset:6144
	ds_read_b128 v[240:243], v144 offset:7168
	global_load_lds_dwordx4 v[186:187], off
	v_lshl_add_u64 v[186:187], v[140:141], 0, s[8:9]
	s_add_i32 m0, s21, 0xe000
	s_nop 0
	global_load_lds_dwordx4 v[186:187], off
	s_waitcnt vmcnt(8)
	s_waitcnt lgkmcnt(0)
	s_barrier
	s_setprio 1
	s_waitcnt lgkmcnt(0)
	v_mfma_f32_16x16x32_bf16 v[126:129], v[146:149], v[178:181], v[126:129]
	v_mfma_f32_16x16x32_bf16 v[122:125], v[154:157], v[178:181], v[122:125]
	v_mfma_f32_16x16x32_bf16 v[118:121], v[146:149], v[202:205], v[118:121]
	v_mfma_f32_16x16x32_bf16 v[114:117], v[154:157], v[202:205], v[114:117]
	v_mfma_f32_16x16x32_bf16 v[110:113], v[146:149], v[210:213], v[110:113]
	v_mfma_f32_16x16x32_bf16 v[106:109], v[154:157], v[210:213], v[106:109]
	v_mfma_f32_16x16x32_bf16 v[102:105], v[146:149], v[236:239], v[102:105]
	v_mfma_f32_16x16x32_bf16 v[98:101], v[154:157], v[236:239], v[98:101]
	s_setprio 0
	s_setprio 1
	v_mfma_f32_16x16x32_bf16 v[126:129], v[150:153], v[182:185], v[126:129]
	v_mfma_f32_16x16x32_bf16 v[122:125], v[158:161], v[182:185], v[122:125]
	v_mfma_f32_16x16x32_bf16 v[118:121], v[150:153], v[206:209], v[118:121]
	v_mfma_f32_16x16x32_bf16 v[114:117], v[158:161], v[206:209], v[114:117]
	v_mfma_f32_16x16x32_bf16 v[110:113], v[150:153], v[232:235], v[110:113]
	v_mfma_f32_16x16x32_bf16 v[106:109], v[158:161], v[232:235], v[106:109]
	v_mfma_f32_16x16x32_bf16 v[102:105], v[150:153], v[240:243], v[102:105]
	v_mfma_f32_16x16x32_bf16 v[98:101], v[158:161], v[240:243], v[98:101]
	s_setprio 0
	s_setprio 1
	v_mfma_f32_16x16x32_bf16 v[94:97], v[162:165], v[178:181], v[94:97]
	v_mfma_f32_16x16x32_bf16 v[86:89], v[170:173], v[178:181], v[86:89]
	v_mfma_f32_16x16x32_bf16 v[78:81], v[162:165], v[202:205], v[78:81]
	v_mfma_f32_16x16x32_bf16 v[74:77], v[170:173], v[202:205], v[74:77]
	v_mfma_f32_16x16x32_bf16 v[70:73], v[162:165], v[210:213], v[70:73]
	v_mfma_f32_16x16x32_bf16 v[62:65], v[170:173], v[210:213], v[62:65]
	v_mfma_f32_16x16x32_bf16 v[54:57], v[162:165], v[236:239], v[54:57]
	v_mfma_f32_16x16x32_bf16 v[50:53], v[170:173], v[236:239], v[50:53]
	s_setprio 0
	s_setprio 1
	v_mfma_f32_16x16x32_bf16 v[94:97], v[166:169], v[182:185], v[94:97]
	v_mfma_f32_16x16x32_bf16 v[86:89], v[174:177], v[182:185], v[86:89]
	v_mfma_f32_16x16x32_bf16 v[78:81], v[166:169], v[206:209], v[78:81]
	v_mfma_f32_16x16x32_bf16 v[74:77], v[174:177], v[206:209], v[74:77]
	v_mfma_f32_16x16x32_bf16 v[70:73], v[166:169], v[232:235], v[70:73]
	v_mfma_f32_16x16x32_bf16 v[62:65], v[174:177], v[232:235], v[62:65]
	v_mfma_f32_16x16x32_bf16 v[54:57], v[166:169], v[240:243], v[54:57]
	v_mfma_f32_16x16x32_bf16 v[50:53], v[174:177], v[240:243], v[50:53]
	s_setprio 0
	s_barrier
	s_add_i32 s34, s36, s20
	s_mov_b32 m0, s34
	ds_read_b128 v[178:181], v144 offset:16384
	ds_read_b128 v[182:185], v144 offset:17408
	ds_read_b128 v[202:205], v144 offset:18432
	ds_read_b128 v[206:209], v144 offset:19456
	ds_read_b128 v[210:213], v144 offset:20480
	ds_read_b128 v[232:235], v144 offset:21504
	ds_read_b128 v[236:239], v144 offset:22528
	ds_read_b128 v[240:243], v144 offset:23552
	s_add_u32 s60, s12, 0x80
	s_addc_u32 s61, s13, 0
	s_add_u32 s62, s14, 0x80
	s_addc_u32 s63, s15, 0
	global_load_lds_dwordx4 v134, s[12:13]
	s_add_i32 m0, s34, 0x2000
	s_add_u32 s34, s12, 0x80000
	s_addc_u32 s35, s13, 0
	s_add_i32 s36, s37, s20
	global_load_lds_dwordx4 v130, s[12:13]
	s_mov_b32 m0, s36
	s_nop 0
	global_load_lds_dwordx4 v134, s[34:35]
	s_add_i32 m0, s36, 0x2000
	s_nop 0
	global_load_lds_dwordx4 v130, s[34:35]
	s_mov_b32 m0, s21
	s_nop 0
	global_load_lds_dwordx4 v136, s[14:15]
	s_mov_b32 m0, s22
	s_nop 0
	global_load_lds_dwordx4 v132, s[14:15]
	s_waitcnt vmcnt(8)
	s_waitcnt lgkmcnt(0)
	s_barrier
; #define PG8_STAGE(bufoff, gbase, voff) do { _Pragma("unroll") for (int _i = 0; _i < 2; ++_i) \
;         __builtin_amdgcn_global_load_lds((const unsigned*)((const char*)(gbase) + (voff)[_i]), (PG8_LAS unsigned*)(lds + (bufoff) + ldsw + _i * 8192), 16, 0, 0); } while (0)
; #define PG8_LDA(dst, b, h) do { _Pragma("unroll") for (int m = 0; m < 4; ++m) _Pragma("unroll") for (int k = 0; k < 2; ++k) dst[m][k] = *(const PG8_LAS bf16x8*)(lds + PG8_SA(b, h) + aoff + m * 2048 + k * 1024); } while (0)
; #define PG8_LDB(dst, b, h) do { _Pragma("unroll") for (int n = 0; n < 2; ++n) _Pragma("unroll") for (int k = 0; k < 2; ++k) dst[n][k] = *(const PG8_LAS bf16x8*)(lds + PG8_SB(b, h) + boff + n * 2048 + k * 1024); } while (0)
; #define PG8_MMA(ai, bj, At, Bt) do { __builtin_amdgcn_s_setprio(1); _Pragma("unroll") for (int m = 0; m < 4; ++m) _Pragma("unroll") for (int n = 0; n < 2; ++n) _Pragma("unroll") for (int k = 0; k < 2; ++k) \
;         acc[ai][bj][m][n] = __builtin_amdgcn_mfma_f32_16x16x32_bf16(Bt[n][k], At[m][k], acc[ai][bj][m][n], 0, 0, 0); __builtin_amdgcn_s_setprio(0); } while (0)
; #define PG8_WAIT_V(n) asm volatile("s_waitcnt vmcnt(" #n ")" ::: "memory")
; #define PG8_WAIT_L(n) asm volatile("s_waitcnt lgkmcnt(" #n ")" ::: "memory")
; #define PG8_BAR __builtin_amdgcn_s_barrier()
; #define PG8_SCHED __builtin_amdgcn_sched_barrier(0)
; template <class Epi, class Sched, bool ALIGN_EPI = false, bool SP2 = false>
; __device__ __forceinline__ void gemm_phase(PG8_LAS unsigned char* lds, const Gemm g, const Sched& S, const Epi& E) {
;     ...
;             PG8_WAIT_V(8); PG8_WAIT_L(0); PG8_BAR; PG8_MMA(1, 0, At, B0); PG8_MMA(1, 1, At, B1); PG8_BAR; PG8_SCHED;
;             PG8_LDB(B0, 1, 0); PG8_LDB(B1, 1, 1); PG8_SCHED; PG8_LDA(At, 1, 0); PG8_STAGE(PG8_SA(0, 1), a2 + hstepA, voffA);
;             PG8_WAIT_V(8); PG8_WAIT_L(0); PG8_BAR; PG8_MMA(0, 0, At, B0); PG8_MMA(0, 1, At, B1); PG8_BAR; PG8_SCHED;
	s_setprio 1
	s_waitcnt lgkmcnt(0)
	v_mfma_f32_16x16x32_bf16 v[90:93], v[146:149], v[178:181], v[90:93]
	v_mfma_f32_16x16x32_bf16 v[82:85], v[154:157], v[178:181], v[82:85]
	v_mfma_f32_16x16x32_bf16 v[66:69], v[146:149], v[202:205], v[66:69]
	v_mfma_f32_16x16x32_bf16 v[58:61], v[154:157], v[202:205], v[58:61]
	v_mfma_f32_16x16x32_bf16 v[46:49], v[146:149], v[210:213], v[46:49]
	v_mfma_f32_16x16x32_bf16 v[42:45], v[154:157], v[210:213], v[42:45]
	v_mfma_f32_16x16x32_bf16 v[38:41], v[146:149], v[236:239], v[38:41]
	v_mfma_f32_16x16x32_bf16 v[34:37], v[154:157], v[236:239], v[34:37]
	s_setprio 0
	s_setprio 1
	v_mfma_f32_16x16x32_bf16 v[90:93], v[150:153], v[182:185], v[90:93]
	v_mfma_f32_16x16x32_bf16 v[82:85], v[158:161], v[182:185], v[82:85]
	v_mfma_f32_16x16x32_bf16 v[66:69], v[150:153], v[206:209], v[66:69]
	v_mfma_f32_16x16x32_bf16 v[58:61], v[158:161], v[206:209], v[58:61]
	v_mfma_f32_16x16x32_bf16 v[46:49], v[150:153], v[232:235], v[46:49]
	v_mfma_f32_16x16x32_bf16 v[42:45], v[158:161], v[232:235], v[42:45]
	v_mfma_f32_16x16x32_bf16 v[38:41], v[150:153], v[240:243], v[38:41]
	v_mfma_f32_16x16x32_bf16 v[34:37], v[158:161], v[240:243], v[34:37]
	s_setprio 0
	s_setprio 1
	v_mfma_f32_16x16x32_bf16 v[30:33], v[162:165], v[178:181], v[30:33]
	v_mfma_f32_16x16x32_bf16 v[26:29], v[170:173], v[178:181], v[26:29]
	v_mfma_f32_16x16x32_bf16 v[22:25], v[162:165], v[202:205], v[22:25]
	v_mfma_f32_16x16x32_bf16 v[18:21], v[170:173], v[202:205], v[18:21]
	v_mfma_f32_16x16x32_bf16 v[14:17], v[162:165], v[210:213], v[14:17]
	v_mfma_f32_16x16x32_bf16 v[10:13], v[170:173], v[210:213], v[10:13]
	v_mfma_f32_16x16x32_bf16 v[6:9], v[162:165], v[236:239], v[6:9]
	v_mfma_f32_16x16x32_bf16 v[2:5], v[170:173], v[236:239], v[2:5]
	s_setprio 0
	s_setprio 1
	v_mfma_f32_16x16x32_bf16 v[30:33], v[166:169], v[182:185], v[30:33]
	v_mfma_f32_16x16x32_bf16 v[26:29], v[174:177], v[182:185], v[26:29]
	v_mfma_f32_16x16x32_bf16 v[22:25], v[166:169], v[206:209], v[22:25]
	v_mfma_f32_16x16x32_bf16 v[18:21], v[174:177], v[206:209], v[18:21]
	v_mfma_f32_16x16x32_bf16 v[14:17], v[166:169], v[232:235], v[14:17]
	v_mfma_f32_16x16x32_bf16 v[10:13], v[174:177], v[232:235], v[10:13]
	v_mfma_f32_16x16x32_bf16 v[6:9], v[166:169], v[240:243], v[6:9]
	v_mfma_f32_16x16x32_bf16 v[2:5], v[174:177], v[240:243], v[2:5]
	s_setprio 0
	s_barrier
	s_add_i32 s34, 0, 0x18000
	v_add_u32_e32 v145, s34, v143
	s_add_i32 s35, 0, 0x1c000
	ds_read_b128 v[146:149], v145
	ds_read_b128 v[150:153], v145 offset:1024
	ds_read_b128 v[154:157], v145 offset:2048
	ds_read_b128 v[158:161], v145 offset:3072
	v_add_u32_e32 v145, s35, v143
	ds_read_b128 v[162:165], v145
	ds_read_b128 v[166:169], v145 offset:1024
	ds_read_b128 v[170:173], v145 offset:2048
	ds_read_b128 v[174:177], v145 offset:3072
	s_add_u32 s14, s14, 0x40000
	s_addc_u32 s15, s15, 0
	s_mov_b32 m0, s23
	ds_read_b128 v[178:181], v144 offset:32768
	ds_read_b128 v[182:185], v144 offset:33792
	ds_read_b128 v[202:205], v144 offset:34816
	ds_read_b128 v[206:209], v144 offset:35840
	ds_read_b128 v[210:213], v144 offset:36864
	ds_read_b128 v[232:235], v144 offset:37888
	ds_read_b128 v[236:239], v144 offset:38912
	ds_read_b128 v[240:243], v144 offset:39936
	global_load_lds_dwordx4 v136, s[14:15]
	s_mov_b32 m0, s24
	s_nop 0
	global_load_lds_dwordx4 v132, s[14:15]
	s_waitcnt vmcnt(8)
	s_waitcnt lgkmcnt(0)
	s_barrier
	s_setprio 1
	s_waitcnt lgkmcnt(0)
	v_mfma_f32_16x16x32_bf16 v[126:129], v[146:149], v[178:181], v[126:129]
	v_mfma_f32_16x16x32_bf16 v[122:125], v[154:157], v[178:181], v[122:125]
	v_mfma_f32_16x16x32_bf16 v[118:121], v[146:149], v[202:205], v[118:121]
	v_mfma_f32_16x16x32_bf16 v[114:117], v[154:157], v[202:205], v[114:117]
	v_mfma_f32_16x16x32_bf16 v[110:113], v[146:149], v[210:213], v[110:113]
	v_mfma_f32_16x16x32_bf16 v[106:109], v[154:157], v[210:213], v[106:109]
	v_mfma_f32_16x16x32_bf16 v[102:105], v[146:149], v[236:239], v[102:105]
	v_mfma_f32_16x16x32_bf16 v[98:101], v[154:157], v[236:239], v[98:101]
	s_setprio 0
	s_setprio 1
	v_mfma_f32_16x16x32_bf16 v[126:129], v[150:153], v[182:185], v[126:129]
	v_mfma_f32_16x16x32_bf16 v[122:125], v[158:161], v[182:185], v[122:125]
	v_mfma_f32_16x16x32_bf16 v[118:121], v[150:153], v[206:209], v[118:121]
	v_mfma_f32_16x16x32_bf16 v[114:117], v[158:161], v[206:209], v[114:117]
	v_mfma_f32_16x16x32_bf16 v[110:113], v[150:153], v[232:235], v[110:113]
	v_mfma_f32_16x16x32_bf16 v[106:109], v[158:161], v[232:235], v[106:109]
	v_mfma_f32_16x16x32_bf16 v[102:105], v[150:153], v[240:243], v[102:105]
	v_mfma_f32_16x16x32_bf16 v[98:101], v[158:161], v[240:243], v[98:101]
	s_setprio 0
	s_setprio 1
	v_mfma_f32_16x16x32_bf16 v[94:97], v[162:165], v[178:181], v[94:97]
	v_mfma_f32_16x16x32_bf16 v[86:89], v[170:173], v[178:181], v[86:89]
	v_mfma_f32_16x16x32_bf16 v[78:81], v[162:165], v[202:205], v[78:81]
	v_mfma_f32_16x16x32_bf16 v[74:77], v[170:173], v[202:205], v[74:77]
	v_mfma_f32_16x16x32_bf16 v[70:73], v[162:165], v[210:213], v[70:73]
	v_mfma_f32_16x16x32_bf16 v[62:65], v[170:173], v[210:213], v[62:65]
	v_mfma_f32_16x16x32_bf16 v[54:57], v[162:165], v[236:239], v[54:57]
	v_mfma_f32_16x16x32_bf16 v[50:53], v[170:173], v[236:239], v[50:53]
	s_setprio 0
	s_setprio 1
	v_mfma_f32_16x16x32_bf16 v[94:97], v[166:169], v[182:185], v[94:97]
	v_mfma_f32_16x16x32_bf16 v[86:89], v[174:177], v[182:185], v[86:89]
	v_mfma_f32_16x16x32_bf16 v[78:81], v[166:169], v[206:209], v[78:81]
	v_mfma_f32_16x16x32_bf16 v[74:77], v[174:177], v[206:209], v[74:77]
	v_mfma_f32_16x16x32_bf16 v[70:73], v[166:169], v[232:235], v[70:73]
	v_mfma_f32_16x16x32_bf16 v[62:65], v[174:177], v[232:235], v[62:65]
	v_mfma_f32_16x16x32_bf16 v[54:57], v[166:169], v[240:243], v[54:57]
	v_mfma_f32_16x16x32_bf16 v[50:53], v[174:177], v[240:243], v[50:53]
	s_setprio 0
	s_barrier
; #define PG8_STAGE(bufoff, gbase, voff) do { _Pragma("unroll") for (int _i = 0; _i < 2; ++_i) \
;         __builtin_amdgcn_global_load_lds((const unsigned*)((const char*)(gbase) + (voff)[_i]), (PG8_LAS unsigned*)(lds + (bufoff) + ldsw + _i * 8192), 16, 0, 0); } while (0)
; #define PG8_LDA(dst, b, h) do { _Pragma("unroll") for (int m = 0; m < 4; ++m) _Pragma("unroll") for (int k = 0; k < 2; ++k) dst[m][k] = *(const PG8_LAS bf16x8*)(lds + PG8_SA(b, h) + aoff + m * 2048 + k * 1024); } while (0)
; #define PG8_MMA(ai, bj, At, Bt) do { __builtin_amdgcn_s_setprio(1); _Pragma("unroll") for (int m = 0; m < 4; ++m) _Pragma("unroll") for (int n = 0; n < 2; ++n) _Pragma("unroll") for (int k = 0; k < 2; ++k) \
;         acc[ai][bj][m][n] = __builtin_amdgcn_mfma_f32_16x16x32_bf16(Bt[n][k], At[m][k], acc[ai][bj][m][n], 0, 0, 0); __builtin_amdgcn_s_setprio(0); } while (0)
; #define PG8_WAIT_V(n) asm volatile("s_waitcnt vmcnt(" #n ")" ::: "memory")
; #define PG8_WAIT_L(n) asm volatile("s_waitcnt lgkmcnt(" #n ")" ::: "memory")
; #define PG8_BAR __builtin_amdgcn_s_barrier()
; #define PG8_SCHED __builtin_amdgcn_sched_barrier(0)
; template <class Epi, class Sched, bool ALIGN_EPI = false, bool SP2 = false>
; __device__ __forceinline__ void gemm_phase(PG8_LAS unsigned char* lds, const Gemm g, const Sched& S, const Epi& E) {
;     ...
;             PG8_LDA(At, 1, 1); PG8_STAGE(PG8_SB(1, 0), b3, voffB); PG8_STAGE(PG8_SB(1, 1), b3 + hstepB, voffB); PG8_STAGE(PG8_SA(1, 0), a3, voffA);
;             PG8_WAIT_V(8); PG8_WAIT_L(0); PG8_BAR; PG8_MMA(1, 0, At, B0); PG8_MMA(1, 1, At, B1); PG8_BAR; PG8_SCHED;
	s_add_i32 s14, s34, s20
	s_mov_b32 m0, s14
	ds_read_b128 v[178:181], v144 offset:49152
	ds_read_b128 v[182:185], v144 offset:50176
	ds_read_b128 v[202:205], v144 offset:51200
	ds_read_b128 v[206:209], v144 offset:52224
	ds_read_b128 v[210:213], v144 offset:53248
	ds_read_b128 v[232:235], v144 offset:54272
	ds_read_b128 v[236:239], v144 offset:55296
	ds_read_b128 v[240:243], v144 offset:56320
	global_load_lds_dwordx4 v134, s[60:61]
	s_add_i32 m0, s14, 0x2000
	s_add_u32 s12, s12, 0x80080
	s_addc_u32 s13, s13, 0
	s_add_i32 s14, s35, s20
	global_load_lds_dwordx4 v130, s[60:61]
	s_mov_b32 m0, s14
	s_nop 0
	global_load_lds_dwordx4 v134, s[12:13]
	s_add_i32 m0, s14, 0x2000
	s_nop 0
	global_load_lds_dwordx4 v130, s[12:13]
	s_mov_b32 m0, s26
	s_nop 0
	global_load_lds_dwordx4 v136, s[62:63]
	s_mov_b32 m0, s27
	s_nop 0
	global_load_lds_dwordx4 v132, s[62:63]
	s_waitcnt vmcnt(8)
	s_waitcnt lgkmcnt(0)
	s_barrier
	s_setprio 1
	s_waitcnt lgkmcnt(0)
	v_mfma_f32_16x16x32_bf16 v[90:93], v[146:149], v[178:181], v[90:93]
	v_mfma_f32_16x16x32_bf16 v[82:85], v[154:157], v[178:181], v[82:85]
	v_mfma_f32_16x16x32_bf16 v[66:69], v[146:149], v[202:205], v[66:69]
	v_mfma_f32_16x16x32_bf16 v[58:61], v[154:157], v[202:205], v[58:61]
	v_mfma_f32_16x16x32_bf16 v[46:49], v[146:149], v[210:213], v[46:49]
	v_mfma_f32_16x16x32_bf16 v[42:45], v[154:157], v[210:213], v[42:45]
	v_mfma_f32_16x16x32_bf16 v[38:41], v[146:149], v[236:239], v[38:41]
	v_mfma_f32_16x16x32_bf16 v[34:37], v[154:157], v[236:239], v[34:37]
	s_setprio 0
	s_setprio 1
	v_mfma_f32_16x16x32_bf16 v[90:93], v[150:153], v[182:185], v[90:93]
	v_mfma_f32_16x16x32_bf16 v[82:85], v[158:161], v[182:185], v[82:85]
	v_mfma_f32_16x16x32_bf16 v[66:69], v[150:153], v[206:209], v[66:69]
	v_mfma_f32_16x16x32_bf16 v[58:61], v[158:161], v[206:209], v[58:61]
	v_mfma_f32_16x16x32_bf16 v[46:49], v[150:153], v[232:235], v[46:49]
	v_mfma_f32_16x16x32_bf16 v[42:45], v[158:161], v[232:235], v[42:45]
	v_mfma_f32_16x16x32_bf16 v[38:41], v[150:153], v[240:243], v[38:41]
	v_mfma_f32_16x16x32_bf16 v[34:37], v[158:161], v[240:243], v[34:37]
	s_setprio 0
	s_setprio 1
	v_mfma_f32_16x16x32_bf16 v[30:33], v[162:165], v[178:181], v[30:33]
	v_mfma_f32_16x16x32_bf16 v[26:29], v[170:173], v[178:181], v[26:29]
	v_mfma_f32_16x16x32_bf16 v[22:25], v[162:165], v[202:205], v[22:25]
	v_mfma_f32_16x16x32_bf16 v[18:21], v[170:173], v[202:205], v[18:21]
	v_mfma_f32_16x16x32_bf16 v[14:17], v[162:165], v[210:213], v[14:17]
	v_mfma_f32_16x16x32_bf16 v[10:13], v[170:173], v[210:213], v[10:13]
	v_mfma_f32_16x16x32_bf16 v[6:9], v[162:165], v[236:239], v[6:9]
	v_mfma_f32_16x16x32_bf16 v[2:5], v[170:173], v[236:239], v[2:5]
	s_setprio 0
	s_setprio 1
	v_mfma_f32_16x16x32_bf16 v[30:33], v[166:169], v[182:185], v[30:33]
	v_mfma_f32_16x16x32_bf16 v[26:29], v[174:177], v[182:185], v[26:29]
	v_mfma_f32_16x16x32_bf16 v[22:25], v[166:169], v[206:209], v[22:25]
	v_mfma_f32_16x16x32_bf16 v[18:21], v[174:177], v[206:209], v[18:21]
	v_mfma_f32_16x16x32_bf16 v[14:17], v[166:169], v[232:235], v[14:17]
	v_mfma_f32_16x16x32_bf16 v[10:13], v[174:177], v[232:235], v[10:13]
	v_mfma_f32_16x16x32_bf16 v[6:9], v[166:169], v[240:243], v[6:9]
	v_mfma_f32_16x16x32_bf16 v[2:5], v[174:177], v[240:243], v[2:5]
	s_setprio 0
	s_barrier
	s_add_i32 s31, s31, 2
	s_add_u32 s8, s8, 0x100
	s_addc_u32 s9, s9, 0
	s_cmp_gt_u32 s31, 13
	s_cbranch_scc0 .LBB0_530
	s_cmpk_lt_u32 s19, 0x100
	s_cbranch_scc0 .LBB0_533
	s_barrier

; #define PG8_STAGE(bufoff, gbase, voff) do { _Pragma("unroll") for (int _i = 0; _i < 2; ++_i) \
;         __builtin_amdgcn_global_load_lds((const unsigned*)((const char*)(gbase) + (voff)[_i]), (PG8_LAS unsigned*)(lds + (bufoff) + ldsw + _i * 8192), 16, 0, 0); } while (0)
; #define PG8_BAR __builtin_amdgcn_s_barrier()
; template <class Epi, class Sched, bool ALIGN_EPI = false, bool SP2 = false>
; __device__ __forceinline__ void gemm_phase(PG8_LAS unsigned char* lds, const Gemm g, const Sched& S, const Epi& E) {
;     ...
;         PG8_WAIT_V(2); PG8_BAR;
;         PG8_STAGE(PG8_SB(1, 0), cB + kstep, voffB); PG8_STAGE(PG8_SA(1, 0), cA + kstep, voffA); PG8_STAGE(PG8_SB(1, 1), cB + hstepB + kstep, voffB);
;         PG8_WAIT_V(6); PG8_BAR;
;     } else {
;         PG8_STAGE(PG8_SB(0, 0), cB, voffB); PG8_STAGE(PG8_SA(0, 0), cA, voffA); PG8_STAGE(PG8_SB(0, 1), cB + hstepB, voffB); PG8_STAGE(PG8_SA(0, 1), cA + hstepA, voffA);
;         if (wr == 1) PG8_BAR;
;         PG8_WAIT_V(4); PG8_BAR;
;         PG8_STAGE(PG8_SB(1, 0), cB + kstep, voffB); PG8_STAGE(PG8_SA(1, 0), cA + kstep, voffA); PG8_STAGE(PG8_SB(1, 1), cB + hstepB + kstep, voffB);
;         PG8_WAIT_V(6); PG8_BAR;
;     }
;     for (;;) {
;         const bool has_next = S.next(ui + 1, nxt);
;         const char* nA = has_next ? (const char*)g.A + (size_t)nxt.pm * tstepA : cA; const char* nB = has_next ? (const char*)g.Bt + (size_t)nxt.pn * tstepB : cB;
;         for (int t = 0; t < nt; t += 2) {
;             const bool last = (t == nt - 2);
;             const char* a1 = cA + (size_t)(t + 1) * kstep;
;             const char* a2 = last ? nA : cA + (size_t)(t + 2) * kstep; const char* b2 = last ? nB : cB + (size_t)(t + 2) * kstep;
;             const char* a3 = a2 + kstep; const char* b3 = b2 + kstep;
;             if (last && has_next) S.a_ready(nxt);
;             if constexpr (SP2) {
;             PG8_LDB(B0, 0, 0); PG8_LDB(B1, 0, 1); PG8_SCHED; PG8_LDA(At, 0, 0); PG8_STAGE(PG8_SA(1, 1), a1 + hstepA, voffA);
;             PG8_WAIT_V(8); PG8_WAIT_L(0); PG8_BAR; PG8_MMA(0, 0, At, B0); PG8_MMA(0, 1, At, B1); PG8_BAR; PG8_SCHED;
;             PG8_LDA(At, 0, 1); PG8_STAGE(PG8_SB(0, 0), b2, voffB); PG8_STAGE(PG8_SB(0, 1), b2 + hstepB, voffB); PG8_STAGE(PG8_SA(0, 0), a2, voffA);
;             PG8_WAIT_V(8); PG8_WAIT_L(0); PG8_BAR; PG8_MMA(1, 0, At, B0); PG8_MMA(1, 1, At, B1); PG8_BAR; PG8_SCHED;
.LBB0_592:
	s_add_i32 s44, 0, 0x18000
	s_add_i32 s36, s44, s14
	s_and_b32 s28, s15, 3
	v_lshl_add_u64 v[26:27], v[4:5], 0, s[96:97]
	s_mov_b32 m0, s36
	s_add_i32 s38, s36, 0x2000
	s_lshl_b32 s15, s26, 13
	s_lshl_b32 s43, s28, 12
	s_waitcnt vmcnt(2)
	s_barrier
	global_load_lds_dwordx4 v[26:27], off
	v_lshl_add_u64 v[28:29], v[6:7], 0, s[96:97]
	s_mov_b32 m0, s38
	s_add_i32 s37, s27, 0x8000
	s_add_i32 s39, s27, 0xa000
	global_load_lds_dwordx4 v[28:29], off
	v_lshl_add_u64 v[24:25], v[18:19], 0, s[96:97]
	s_mov_b32 m0, s37
	s_add_u32 s16, s8, 0x10080
	global_load_lds_dwordx4 v[24:25], off
	v_lshl_add_u64 v[30:31], v[22:23], 0, s[96:97]
	s_mov_b32 m0, s39
	s_addc_u32 s17, s9, 0
	s_add_i32 s40, s27, 0x1c000
	global_load_lds_dwordx4 v[30:31], off
	v_lshl_add_u64 v[68:69], s[16:17], 0, v[32:33]
	s_mov_b32 m0, s40
	s_add_i32 s41, s27, 0x1e000
	global_load_lds_dwordx4 v[68:69], off
	v_lshl_add_u64 v[70:71], s[16:17], 0, v[20:21]
	s_mov_b32 m0, s41
	v_lshrrev_b32_e32 v35, 1, v34
	global_load_lds_dwordx4 v[70:71], off
	v_and_b32_e32 v72, 24, v35
	v_and_b32_e32 v67, 15, v34
	v_lshlrev_b32_e32 v35, 1, v72
	v_lshlrev_b32_e32 v34, 2, v34
	v_lshl_or_b32 v35, v67, 6, v35
	v_and_b32_e32 v34, 32, v34
	v_bitop3_b32 v36, v35, s15, v34 bitop3:0xde
	s_add_i32 s15, 0, 0x10000
	v_bitop3_b32 v34, v35, s43, v34 bitop3:0xde
	s_add_u32 s48, s12, 0x10080
	v_add_u32_e32 v157, s44, v34
	s_addc_u32 s49, s13, 0
	s_add_i32 s44, s15, s14
	s_add_i32 s46, s27, 0xc000
	s_add_i32 s45, s27, 0xe000
	s_add_i32 s43, s44, 0x2000
	v_add_u32_e32 v73, s15, v34
	s_add_u32 s50, s8, 0x10100
	s_waitcnt vmcnt(6)
	s_barrier
	v_add_u32_e32 v156, 0, v36
	s_addc_u32 s51, s9, 0
	ds_read_b128 v[34:37], v73
	ds_read_b128 v[38:41], v73 offset:1024
	ds_read_b128 v[42:45], v73 offset:2048
	ds_read_b128 v[46:49], v73 offset:3072
	s_add_u32 s16, s12, 0x10100
	s_addc_u32 s17, s13, 0
	s_add_u32 s14, s8, 0x10180
	s_addc_u32 s15, s9, 0
	s_add_u32 s8, s12, 0x10180
	s_addc_u32 s9, s13, 0
	s_cmpk_gt_u32 s42, 0xff
	s_mov_b32 m0, s46
	v_lshl_add_u64 v[90:91], s[48:49], 0, v[14:15]
	ds_read_b128 v[50:53], v156
	ds_read_b128 v[54:57], v156 offset:1024
	ds_read_b128 v[58:61], v156 offset:2048
	ds_read_b128 v[62:65], v156 offset:3072
	ds_read_b128 v[74:77], v156 offset:4096
	ds_read_b128 v[78:81], v156 offset:5120
	ds_read_b128 v[82:85], v156 offset:6144
	ds_read_b128 v[86:89], v156 offset:7168
	global_load_lds_dwordx4 v[90:91], off
	v_lshl_add_u64 v[90:91], s[48:49], 0, v[2:3]
	s_mov_b32 m0, s45
	s_nop 0
	global_load_lds_dwordx4 v[90:91], off
	s_waitcnt vmcnt(8)
	s_waitcnt lgkmcnt(0)
	s_barrier
	s_setprio 1
	s_waitcnt lgkmcnt(0)
	v_mfma_f32_16x16x32_bf16 v[90:93], v[34:37], v[50:53], 0
	v_mfma_f32_16x16x32_bf16 v[50:53], v[42:45], v[50:53], 0
	v_mfma_f32_16x16x32_bf16 v[90:93], v[38:41], v[54:57], v[90:93]
	v_mfma_f32_16x16x32_bf16 v[50:53], v[46:49], v[54:57], v[50:53]
	v_mfma_f32_16x16x32_bf16 v[54:57], v[34:37], v[58:61], 0
	v_mfma_f32_16x16x32_bf16 v[58:61], v[42:45], v[58:61], 0
	v_mfma_f32_16x16x32_bf16 v[54:57], v[38:41], v[62:65], v[54:57]
	v_mfma_f32_16x16x32_bf16 v[58:61], v[46:49], v[62:65], v[58:61]
	s_setprio 0
	s_setprio 1
	v_mfma_f32_16x16x32_bf16 v[62:65], v[34:37], v[74:77], 0
	v_mfma_f32_16x16x32_bf16 v[74:77], v[42:45], v[74:77], 0
	v_mfma_f32_16x16x32_bf16 v[62:65], v[38:41], v[78:81], v[62:65]
	v_mfma_f32_16x16x32_bf16 v[74:77], v[46:49], v[78:81], v[74:77]
	v_mfma_f32_16x16x32_bf16 v[78:81], v[34:37], v[82:85], 0
	v_mfma_f32_16x16x32_bf16 v[82:85], v[42:45], v[82:85], 0
	v_mfma_f32_16x16x32_bf16 v[78:81], v[38:41], v[86:89], v[78:81]
	v_mfma_f32_16x16x32_bf16 v[82:85], v[46:49], v[86:89], v[82:85]
	s_setprio 0
	s_setprio 1
	s_setprio 0
	s_barrier
	s_mov_b64 s[12:13], 0x100
	s_mov_b32 m0, s44
	v_lshl_add_u64 v[122:123], v[4:5], 0, s[12:13]
	ds_read_b128 v[86:89], v156 offset:16384
	ds_read_b128 v[94:97], v156 offset:17408
	ds_read_b128 v[98:101], v156 offset:18432
	ds_read_b128 v[102:105], v156 offset:19456
	ds_read_b128 v[106:109], v156 offset:20480
	ds_read_b128 v[110:113], v156 offset:21504
	ds_read_b128 v[114:117], v156 offset:22528
	ds_read_b128 v[118:121], v156 offset:23552
	global_load_lds_dwordx4 v[122:123], off
	v_lshl_add_u64 v[122:123], v[6:7], 0, s[12:13]
	s_mov_b32 m0, s43
	s_nop 0
	global_load_lds_dwordx4 v[122:123], off
	v_lshl_add_u64 v[122:123], s[50:51], 0, v[32:33]
	s_mov_b32 m0, s29
	s_nop 0
	global_load_lds_dwordx4 v[122:123], off
	v_lshl_add_u64 v[122:123], s[50:51], 0, v[20:21]
	s_mov_b32 m0, s31
	s_nop 0
	global_load_lds_dwordx4 v[122:123], off
	v_lshl_add_u64 v[122:123], v[18:19], 0, s[12:13]
	s_mov_b32 m0, s27
	s_nop 0
	global_load_lds_dwordx4 v[122:123], off
	v_lshl_add_u64 v[122:123], v[22:23], 0, s[12:13]
	s_mov_b32 m0, s35
	s_nop 0
	global_load_lds_dwordx4 v[122:123], off
	s_waitcnt vmcnt(8)
	s_waitcnt lgkmcnt(0)
	s_barrier
	s_setprio 1
	s_waitcnt lgkmcnt(0)
	v_mfma_f32_16x16x32_bf16 v[122:125], v[34:37], v[86:89], 0
	v_mfma_f32_16x16x32_bf16 v[86:89], v[42:45], v[86:89], 0
	v_mfma_f32_16x16x32_bf16 v[122:125], v[38:41], v[94:97], v[122:125]
	v_mfma_f32_16x16x32_bf16 v[86:89], v[46:49], v[94:97], v[86:89]
	v_mfma_f32_16x16x32_bf16 v[94:97], v[34:37], v[98:101], 0
	v_mfma_f32_16x16x32_bf16 v[98:101], v[42:45], v[98:101], 0
	v_mfma_f32_16x16x32_bf16 v[94:97], v[38:41], v[102:105], v[94:97]
	v_mfma_f32_16x16x32_bf16 v[98:101], v[46:49], v[102:105], v[98:101]
	s_setprio 0
	s_setprio 1
	v_mfma_f32_16x16x32_bf16 v[102:105], v[34:37], v[106:109], 0
	v_mfma_f32_16x16x32_bf16 v[34:37], v[34:37], v[114:117], 0
	v_mfma_f32_16x16x32_bf16 v[102:105], v[38:41], v[110:113], v[102:105]
	v_mfma_f32_16x16x32_bf16 v[34:37], v[38:41], v[118:121], v[34:37]
	v_mfma_f32_16x16x32_bf16 v[38:41], v[42:45], v[114:117], 0
	v_mfma_f32_16x16x32_bf16 v[106:109], v[42:45], v[106:109], 0
	v_mfma_f32_16x16x32_bf16 v[38:41], v[46:49], v[118:121], v[38:41]
	v_mfma_f32_16x16x32_bf16 v[106:109], v[46:49], v[110:113], v[106:109]
	s_setprio 0
	s_setprio 1
	s_setprio 0
	s_barrier
; #define PG8_STAGE(bufoff, gbase, voff) do { _Pragma("unroll") for (int _i = 0; _i < 2; ++_i) \
;         __builtin_amdgcn_global_load_lds((const unsigned*)((const char*)(gbase) + (voff)[_i]), (PG8_LAS unsigned*)(lds + (bufoff) + ldsw + _i * 8192), 16, 0, 0); } while (0)
; #define PG8_LDA(dst, b, h) do { _Pragma("unroll") for (int m = 0; m < 4; ++m) _Pragma("unroll") for (int k = 0; k < 2; ++k) dst[m][k] = *(const PG8_LAS bf16x8*)(lds + PG8_SA(b, h) + aoff + m * 2048 + k * 1024); } while (0)
; #define PG8_LDB(dst, b, h) do { _Pragma("unroll") for (int n = 0; n < 2; ++n) _Pragma("unroll") for (int k = 0; k < 2; ++k) dst[n][k] = *(const PG8_LAS bf16x8*)(lds + PG8_SB(b, h) + boff + n * 2048 + k * 1024); } while (0)
; #define PG8_MMA(ai, bj, At, Bt) do { __builtin_amdgcn_s_setprio(1); _Pragma("unroll") for (int m = 0; m < 4; ++m) _Pragma("unroll") for (int n = 0; n < 2; ++n) _Pragma("unroll") for (int k = 0; k < 2; ++k) \
;         acc[ai][bj][m][n] = __builtin_amdgcn_mfma_f32_16x16x32_bf16(Bt[n][k], At[m][k], acc[ai][bj][m][n], 0, 0, 0); __builtin_amdgcn_s_setprio(0); } while (0)
; #define PG8_WAIT_V(n) asm volatile("s_waitcnt vmcnt(" #n ")" ::: "memory")
; template <class Epi, class Sched, bool ALIGN_EPI = false, bool SP2 = false>
; __device__ __forceinline__ void gemm_phase(PG8_LAS unsigned char* lds, const Gemm g, const Sched& S, const Epi& E) {
;     ...
;             PG8_LDB(B0, 0, 0); PG8_LDB(B1, 0, 1); PG8_SCHED; PG8_LDA(At, 0, 0); PG8_STAGE(PG8_SA(1, 1), a1 + hstepA, voffA);
;             PG8_WAIT_V(8); PG8_WAIT_L(0); PG8_BAR; PG8_MMA(0, 0, At, B0); PG8_MMA(0, 1, At, B1); PG8_BAR; PG8_SCHED;
;             PG8_LDA(At, 0, 1); PG8_STAGE(PG8_SB(0, 0), b2, voffB); PG8_STAGE(PG8_SB(0, 1), b2 + hstepB, voffB); PG8_STAGE(PG8_SA(0, 0), a2, voffA);
;             PG8_WAIT_V(8); PG8_WAIT_L(0); PG8_BAR; PG8_MMA(1, 0, At, B0); PG8_MMA(1, 1, At, B1); PG8_BAR; PG8_SCHED;
;             PG8_LDB(B0, 1, 0); PG8_LDB(B1, 1, 1); PG8_SCHED; PG8_LDA(At, 1, 0); PG8_STAGE(PG8_SA(0, 1), a2 + hstepA, voffA);
;             PG8_WAIT_V(8); PG8_WAIT_L(0); PG8_BAR; PG8_MMA(0, 0, At, B0); PG8_MMA(0, 1, At, B1); PG8_BAR; PG8_SCHED;
;             PG8_LDA(At, 1, 1); PG8_STAGE(PG8_SB(1, 0), b3, voffB); PG8_STAGE(PG8_SB(1, 1), b3 + hstepB, voffB); PG8_STAGE(PG8_SA(1, 0), a3, voffA);
;             PG8_WAIT_V(8); PG8_WAIT_L(0); PG8_BAR; PG8_MMA(1, 0, At, B0); PG8_MMA(1, 1, At, B1); PG8_BAR; PG8_SCHED;
	ds_read_b128 v[42:45], v157
	ds_read_b128 v[46:49], v157 offset:1024
	ds_read_b128 v[110:113], v157 offset:2048
	ds_read_b128 v[114:117], v157 offset:3072
	s_mov_b32 m0, s30
	v_lshl_add_u64 v[154:155], s[16:17], 0, v[14:15]
	ds_read_b128 v[118:121], v156 offset:32768
	ds_read_b128 v[126:129], v156 offset:33792
	ds_read_b128 v[130:133], v156 offset:34816
	ds_read_b128 v[134:137], v156 offset:35840
	ds_read_b128 v[138:141], v156 offset:36864
	ds_read_b128 v[142:145], v156 offset:37888
	ds_read_b128 v[146:149], v156 offset:38912
	ds_read_b128 v[150:153], v156 offset:39936
	global_load_lds_dwordx4 v[154:155], off
	v_lshl_add_u64 v[154:155], s[16:17], 0, v[2:3]
	s_mov_b32 m0, s34
	s_nop 0
	global_load_lds_dwordx4 v[154:155], off
	s_waitcnt vmcnt(8)
	s_waitcnt lgkmcnt(0)
	s_barrier
	s_setprio 1
	s_waitcnt lgkmcnt(0)
	v_mfma_f32_16x16x32_bf16 v[50:53], v[110:113], v[118:121], v[50:53]
	v_mfma_f32_16x16x32_bf16 v[54:57], v[42:45], v[130:133], v[54:57]
	v_mfma_f32_16x16x32_bf16 v[58:61], v[110:113], v[130:133], v[58:61]
	v_mfma_f32_16x16x32_bf16 v[62:65], v[42:45], v[138:141], v[62:65]
	v_mfma_f32_16x16x32_bf16 v[90:93], v[42:45], v[118:121], v[90:93]
	v_mfma_f32_16x16x32_bf16 v[50:53], v[114:117], v[126:129], v[50:53]
	v_mfma_f32_16x16x32_bf16 v[54:57], v[46:49], v[134:137], v[54:57]
	v_mfma_f32_16x16x32_bf16 v[58:61], v[114:117], v[134:137], v[58:61]
	s_setprio 0
	s_setprio 1
	v_mfma_f32_16x16x32_bf16 v[62:65], v[46:49], v[142:145], v[62:65]
	v_mfma_f32_16x16x32_bf16 v[74:77], v[110:113], v[138:141], v[74:77]
	v_mfma_f32_16x16x32_bf16 v[78:81], v[42:45], v[146:149], v[78:81]
	v_mfma_f32_16x16x32_bf16 v[82:85], v[110:113], v[146:149], v[82:85]
	v_mfma_f32_16x16x32_bf16 v[90:93], v[46:49], v[126:129], v[90:93]
	v_mfma_f32_16x16x32_bf16 v[74:77], v[114:117], v[142:145], v[74:77]
	v_mfma_f32_16x16x32_bf16 v[78:81], v[46:49], v[150:153], v[78:81]
	v_mfma_f32_16x16x32_bf16 v[82:85], v[114:117], v[150:153], v[82:85]
	s_setprio 0
	s_setprio 1
	s_setprio 0
	s_barrier
	s_mov_b64 s[12:13], 0x180
	s_mov_b32 m0, s36
	v_lshl_add_u64 v[154:155], v[4:5], 0, s[12:13]
	ds_read_b128 v[118:121], v156 offset:49152
	ds_read_b128 v[126:129], v156 offset:50176
	ds_read_b128 v[130:133], v156 offset:51200
	ds_read_b128 v[134:137], v156 offset:52224
	ds_read_b128 v[138:141], v156 offset:53248
	ds_read_b128 v[142:145], v156 offset:54272
	ds_read_b128 v[146:149], v156 offset:55296
	ds_read_b128 v[150:153], v156 offset:56320
	global_load_lds_dwordx4 v[154:155], off
	v_lshl_add_u64 v[154:155], v[6:7], 0, s[12:13]
	s_mov_b32 m0, s38
	v_lshl_add_u64 v[32:33], s[14:15], 0, v[32:33]
	global_load_lds_dwordx4 v[154:155], off
	s_mov_b32 m0, s40
	v_lshl_add_u64 v[20:21], s[14:15], 0, v[20:21]
	global_load_lds_dwordx4 v[32:33], off
	s_mov_b32 m0, s41
	s_nop 0
	global_load_lds_dwordx4 v[20:21], off
	v_lshl_add_u64 v[20:21], v[18:19], 0, s[12:13]
	s_mov_b32 m0, s37
	s_nop 0
	global_load_lds_dwordx4 v[20:21], off
	v_lshl_add_u64 v[20:21], v[22:23], 0, s[12:13]
	s_mov_b32 m0, s39
	s_nop 0
	global_load_lds_dwordx4 v[20:21], off
	s_waitcnt vmcnt(8)
	s_waitcnt lgkmcnt(0)
	s_barrier
	s_setprio 1
	s_waitcnt lgkmcnt(0)
	v_mfma_f32_16x16x32_bf16 v[32:35], v[42:45], v[146:149], v[34:37]
	v_mfma_f32_16x16x32_bf16 v[36:39], v[110:113], v[146:149], v[38:41]
	v_mfma_f32_16x16x32_bf16 v[122:125], v[42:45], v[118:121], v[122:125]
	v_mfma_f32_16x16x32_bf16 v[86:89], v[110:113], v[118:121], v[86:89]
	v_mfma_f32_16x16x32_bf16 v[94:97], v[42:45], v[130:133], v[94:97]
	v_mfma_f32_16x16x32_bf16 v[98:101], v[110:113], v[130:133], v[98:101]
	v_mfma_f32_16x16x32_bf16 v[102:105], v[42:45], v[138:141], v[102:105]
	v_mfma_f32_16x16x32_bf16 v[106:109], v[110:113], v[138:141], v[106:109]
	s_setprio 0
	s_setprio 1
	v_mfma_f32_16x16x32_bf16 v[32:35], v[46:49], v[150:153], v[32:35]
	v_mfma_f32_16x16x32_bf16 v[36:39], v[114:117], v[150:153], v[36:39]
	v_mfma_f32_16x16x32_bf16 v[122:125], v[46:49], v[126:129], v[122:125]
	v_mfma_f32_16x16x32_bf16 v[86:89], v[114:117], v[126:129], v[86:89]
	v_mfma_f32_16x16x32_bf16 v[94:97], v[46:49], v[134:137], v[94:97]
	v_mfma_f32_16x16x32_bf16 v[98:101], v[114:117], v[134:137], v[98:101]
	v_mfma_f32_16x16x32_bf16 v[102:105], v[46:49], v[142:145], v[102:105]
	v_mfma_f32_16x16x32_bf16 v[106:109], v[114:117], v[142:145], v[106:109]
	s_setprio 0
	s_setprio 1
	s_setprio 0
	s_barrier
	ds_read_b128 v[40:43], v73
	ds_read_b128 v[44:47], v73 offset:1024
	ds_read_b128 v[110:113], v73 offset:2048
	ds_read_b128 v[114:117], v73 offset:3072
	s_mov_b32 m0, s46
	v_lshl_add_u64 v[14:15], s[8:9], 0, v[14:15]
	ds_read_b128 v[118:121], v156
	ds_read_b128 v[126:129], v156 offset:1024
	ds_read_b128 v[130:133], v156 offset:2048
	ds_read_b128 v[134:137], v156 offset:3072
	ds_read_b128 v[138:141], v156 offset:4096
	ds_read_b128 v[142:145], v156 offset:5120
	ds_read_b128 v[146:149], v156 offset:6144
	ds_read_b128 v[150:153], v156 offset:7168
	global_load_lds_dwordx4 v[14:15], off
	v_lshl_add_u64 v[2:3], s[8:9], 0, v[2:3]
	s_mov_b32 m0, s45
	s_nop 0
	global_load_lds_dwordx4 v[2:3], off
	s_waitcnt vmcnt(8)
	s_waitcnt lgkmcnt(0)
	s_barrier
; #define PG8_STAGE(bufoff, gbase, voff) do { _Pragma("unroll") for (int _i = 0; _i < 2; ++_i) \
;         __builtin_amdgcn_global_load_lds((const unsigned*)((const char*)(gbase) + (voff)[_i]), (PG8_LAS unsigned*)(lds + (bufoff) + ldsw + _i * 8192), 16, 0, 0); } while (0)
; #define PG8_LDA(dst, b, h) do { _Pragma("unroll") for (int m = 0; m < 4; ++m) _Pragma("unroll") for (int k = 0; k < 2; ++k) dst[m][k] = *(const PG8_LAS bf16x8*)(lds + PG8_SA(b, h) + aoff + m * 2048 + k * 1024); } while (0)
; #define PG8_MMA(ai, bj, At, Bt) do { __builtin_amdgcn_s_setprio(1); _Pragma("unroll") for (int m = 0; m < 4; ++m) _Pragma("unroll") for (int n = 0; n < 2; ++n) _Pragma("unroll") for (int k = 0; k < 2; ++k) \
;         acc[ai][bj][m][n] = __builtin_amdgcn_mfma_f32_16x16x32_bf16(Bt[n][k], At[m][k], acc[ai][bj][m][n], 0, 0, 0); __builtin_amdgcn_s_setprio(0); } while (0)
; #define PG8_WAIT_V(n) asm volatile("s_waitcnt vmcnt(" #n ")" ::: "memory")
; #define PG8_WAIT_L(n) asm volatile("s_waitcnt lgkmcnt(" #n ")" ::: "memory")
; #define PG8_BAR __builtin_amdgcn_s_barrier()
; #define PG8_SCHED __builtin_amdgcn_sched_barrier(0)
; template <class Epi, class Sched, bool ALIGN_EPI = false, bool SP2 = false>
; __device__ __forceinline__ void gemm_phase(PG8_LAS unsigned char* lds, const Gemm g, const Sched& S, const Epi& E) {
;     ...
;             PG8_WAIT_V(8); PG8_WAIT_L(0); PG8_BAR; PG8_MMA(0, 0, At, B0); PG8_MMA(0, 1, At, B1); PG8_BAR; PG8_SCHED;
;             PG8_LDA(At, 0, 1); PG8_STAGE(PG8_SB(0, 0), b2, voffB); PG8_STAGE(PG8_SB(0, 1), b2 + hstepB, voffB); PG8_STAGE(PG8_SA(0, 0), a2, voffA);
;             PG8_WAIT_V(8); PG8_WAIT_L(0); PG8_BAR; PG8_MMA(1, 0, At, B0); PG8_MMA(1, 1, At, B1); PG8_BAR; PG8_SCHED;
	s_setprio 1
	s_waitcnt lgkmcnt(0)
	v_mfma_f32_16x16x32_bf16 v[48:51], v[110:113], v[118:121], v[50:53]
	v_mfma_f32_16x16x32_bf16 v[52:55], v[40:43], v[130:133], v[54:57]
	v_mfma_f32_16x16x32_bf16 v[56:59], v[110:113], v[130:133], v[58:61]
	v_mfma_f32_16x16x32_bf16 v[90:93], v[40:43], v[118:121], v[90:93]
	v_mfma_f32_16x16x32_bf16 v[118:121], v[114:117], v[134:137], v[56:59]
	v_mfma_f32_16x16x32_bf16 v[56:59], v[40:43], v[138:141], v[62:65]
	v_mfma_f32_16x16x32_bf16 v[90:93], v[44:47], v[126:129], v[90:93]
	v_mfma_f32_16x16x32_bf16 v[48:51], v[114:117], v[126:129], v[48:51]
	s_setprio 0
	s_setprio 1
	v_mfma_f32_16x16x32_bf16 v[126:129], v[44:47], v[142:145], v[56:59]
	v_mfma_f32_16x16x32_bf16 v[56:59], v[110:113], v[138:141], v[74:77]
	v_mfma_f32_16x16x32_bf16 v[74:77], v[114:117], v[142:145], v[56:59]
	v_mfma_f32_16x16x32_bf16 v[56:59], v[40:43], v[146:149], v[78:81]
	v_mfma_f32_16x16x32_bf16 v[52:55], v[44:47], v[134:137], v[52:55]
	v_mfma_f32_16x16x32_bf16 v[78:81], v[44:47], v[150:153], v[56:59]
	v_mfma_f32_16x16x32_bf16 v[56:59], v[110:113], v[146:149], v[82:85]
	v_mfma_f32_16x16x32_bf16 v[82:85], v[114:117], v[150:153], v[56:59]
	s_setprio 0
	s_setprio 1
	s_setprio 0
	s_barrier
	s_mov_b32 m0, s44
	s_nop 1
	ds_read_b128 v[56:59], v156 offset:16384
	ds_read_b128 v[60:63], v156 offset:17408
	ds_read_b128 v[130:133], v156 offset:18432
	ds_read_b128 v[134:137], v156 offset:19456
	ds_read_b128 v[138:141], v156 offset:20480
	ds_read_b128 v[142:145], v156 offset:21504
	ds_read_b128 v[146:149], v156 offset:22528
	ds_read_b128 v[150:153], v156 offset:23552
	global_load_lds_dwordx4 v[4:5], off
	s_mov_b32 m0, s43
	s_nop 0
	global_load_lds_dwordx4 v[6:7], off
	s_mov_b32 m0, s29
	s_nop 0
	global_load_lds_dwordx4 v[8:9], off
	s_mov_b32 m0, s31
	s_nop 0
	global_load_lds_dwordx4 v[10:11], off
	s_mov_b32 m0, s27
	s_nop 0
	global_load_lds_dwordx4 v[18:19], off
	s_mov_b32 m0, s35
	s_nop 0
	global_load_lds_dwordx4 v[22:23], off
	s_waitcnt vmcnt(8)
	s_waitcnt lgkmcnt(0)
	s_barrier
	s_setprio 1
	s_waitcnt lgkmcnt(0)
	v_mfma_f32_16x16x32_bf16 v[2:5], v[40:43], v[56:59], v[122:125]
	v_mfma_f32_16x16x32_bf16 v[6:9], v[110:113], v[56:59], v[86:89]
	v_mfma_f32_16x16x32_bf16 v[56:59], v[110:113], v[130:133], v[98:101]
	v_mfma_f32_16x16x32_bf16 v[18:21], v[40:43], v[130:133], v[94:97]
	v_mfma_f32_16x16x32_bf16 v[86:89], v[114:117], v[134:137], v[56:59]
	v_mfma_f32_16x16x32_bf16 v[56:59], v[40:43], v[138:141], v[102:105]
	v_mfma_f32_16x16x32_bf16 v[32:35], v[40:43], v[146:149], v[32:35]
	v_mfma_f32_16x16x32_bf16 v[2:5], v[44:47], v[60:63], v[2:5]
	s_setprio 0
	s_setprio 1
	v_mfma_f32_16x16x32_bf16 v[6:9], v[114:117], v[60:63], v[6:9]
	v_mfma_f32_16x16x32_bf16 v[18:21], v[44:47], v[134:137], v[18:21]
	v_mfma_f32_16x16x32_bf16 v[94:97], v[44:47], v[142:145], v[56:59]
	v_mfma_f32_16x16x32_bf16 v[56:59], v[110:113], v[138:141], v[106:109]
	v_mfma_f32_16x16x32_bf16 v[102:105], v[44:47], v[150:153], v[32:35]
	v_mfma_f32_16x16x32_bf16 v[32:35], v[110:113], v[146:149], v[36:39]
	v_mfma_f32_16x16x32_bf16 v[98:101], v[114:117], v[142:145], v[56:59]
	v_mfma_f32_16x16x32_bf16 v[106:109], v[114:117], v[150:153], v[32:35]
	s_setprio 0
	s_setprio 1
	s_setprio 0
	s_barrier
; #define PG8_STAGE(bufoff, gbase, voff) do { _Pragma("unroll") for (int _i = 0; _i < 2; ++_i) \
;         __builtin_amdgcn_global_load_lds((const unsigned*)((const char*)(gbase) + (voff)[_i]), (PG8_LAS unsigned*)(lds + (bufoff) + ldsw + _i * 8192), 16, 0, 0); } while (0)
; #define PG8_LDA(dst, b, h) do { _Pragma("unroll") for (int m = 0; m < 4; ++m) _Pragma("unroll") for (int k = 0; k < 2; ++k) dst[m][k] = *(const PG8_LAS bf16x8*)(lds + PG8_SA(b, h) + aoff + m * 2048 + k * 1024); } while (0)
; #define PG8_LDB(dst, b, h) do { _Pragma("unroll") for (int n = 0; n < 2; ++n) _Pragma("unroll") for (int k = 0; k < 2; ++k) dst[n][k] = *(const PG8_LAS bf16x8*)(lds + PG8_SB(b, h) + boff + n * 2048 + k * 1024); } while (0)
; #define PG8_MMA(ai, bj, At, Bt) do { __builtin_amdgcn_s_setprio(1); _Pragma("unroll") for (int m = 0; m < 4; ++m) _Pragma("unroll") for (int n = 0; n < 2; ++n) _Pragma("unroll") for (int k = 0; k < 2; ++k) \
;         acc[ai][bj][m][n] = __builtin_amdgcn_mfma_f32_16x16x32_bf16(Bt[n][k], At[m][k], acc[ai][bj][m][n], 0, 0, 0); __builtin_amdgcn_s_setprio(0); } while (0)
; #define PG8_WAIT_V(n) asm volatile("s_waitcnt vmcnt(" #n ")" ::: "memory")
; #define PG8_WAIT_L(n) asm volatile("s_waitcnt lgkmcnt(" #n ")" ::: "memory")
; #define PG8_BAR __builtin_amdgcn_s_barrier()
; #define PG8_SCHED __builtin_amdgcn_sched_barrier(0)
; template <class Epi, class Sched, bool ALIGN_EPI = false, bool SP2 = false>
; __device__ __forceinline__ void gemm_phase(PG8_LAS unsigned char* lds, const Gemm g, const Sched& S, const Epi& E) {
;     ...
;             PG8_LDB(B0, 1, 0); PG8_LDB(B1, 1, 1); PG8_SCHED; PG8_LDA(At, 1, 0); PG8_STAGE(PG8_SA(0, 1), a2 + hstepA, voffA);
;             PG8_WAIT_V(8); PG8_WAIT_L(0); PG8_BAR; PG8_MMA(0, 0, At, B0); PG8_MMA(0, 1, At, B1); PG8_BAR; PG8_SCHED;
;             PG8_LDA(At, 1, 1); PG8_STAGE(PG8_SB(1, 0), b3, voffB); PG8_STAGE(PG8_SB(1, 1), b3 + hstepB, voffB); PG8_STAGE(PG8_SA(1, 0), a3, voffA);
;             PG8_WAIT_V(8); PG8_WAIT_L(0); PG8_BAR; PG8_MMA(1, 0, At, B0); PG8_MMA(1, 1, At, B1); PG8_BAR; PG8_SCHED;
	ds_read_b128 v[110:113], v157
	ds_read_b128 v[114:117], v157 offset:1024
	ds_read_b128 v[122:125], v157 offset:2048
	ds_read_b128 v[130:133], v157 offset:3072
	s_mov_b32 m0, s30
	ds_read_b128 v[32:35], v156 offset:32768
	ds_read_b128 v[36:39], v156 offset:33792
	ds_read_b128 v[40:43], v156 offset:34816
	ds_read_b128 v[44:47], v156 offset:35840
	ds_read_b128 v[134:137], v156 offset:36864
	ds_read_b128 v[138:141], v156 offset:37888
	ds_read_b128 v[142:145], v156 offset:38912
	ds_read_b128 v[146:149], v156 offset:39936
	global_load_lds_dwordx4 v[12:13], off
	s_mov_b32 m0, s34
	s_nop 0
	global_load_lds_dwordx4 v[16:17], off
	s_waitcnt vmcnt(8)
	s_waitcnt lgkmcnt(0)
	s_barrier
	s_setprio 1
	s_waitcnt lgkmcnt(0)
	v_mfma_f32_16x16x32_bf16 v[10:13], v[110:113], v[32:35], v[90:93]
	v_mfma_f32_16x16x32_bf16 v[58:61], v[114:117], v[36:39], v[10:13]
	v_mfma_f32_16x16x32_bf16 v[10:13], v[122:125], v[32:35], v[48:51]
	v_mfma_f32_16x16x32_bf16 v[62:65], v[130:133], v[36:39], v[10:13]
	v_mfma_f32_16x16x32_bf16 v[10:13], v[110:113], v[40:43], v[52:55]
	v_mfma_f32_16x16x32_bf16 v[50:53], v[114:117], v[44:47], v[10:13]
	v_mfma_f32_16x16x32_bf16 v[10:13], v[122:125], v[40:43], v[118:121]
	v_mfma_f32_16x16x32_bf16 v[54:57], v[130:133], v[44:47], v[10:13]
	s_setprio 0
	s_setprio 1
	v_mfma_f32_16x16x32_bf16 v[10:13], v[110:113], v[134:137], v[126:129]
	v_mfma_f32_16x16x32_bf16 v[42:45], v[114:117], v[138:141], v[10:13]
	v_mfma_f32_16x16x32_bf16 v[10:13], v[122:125], v[134:137], v[74:77]
	v_mfma_f32_16x16x32_bf16 v[46:49], v[130:133], v[138:141], v[10:13]
	v_mfma_f32_16x16x32_bf16 v[10:13], v[110:113], v[142:145], v[78:81]
	v_mfma_f32_16x16x32_bf16 v[34:37], v[114:117], v[146:149], v[10:13]
	v_mfma_f32_16x16x32_bf16 v[10:13], v[122:125], v[142:145], v[82:85]
	v_mfma_f32_16x16x32_bf16 v[38:41], v[130:133], v[146:149], v[10:13]
	s_setprio 0
	s_setprio 1
	s_setprio 0
	s_barrier
	s_mov_b32 m0, s36
	s_nop 1
	ds_read_b128 v[10:13], v156 offset:49152
	ds_read_b128 v[14:17], v156 offset:50176
	ds_read_b128 v[74:77], v156 offset:51200
	ds_read_b128 v[78:81], v156 offset:52224
	ds_read_b128 v[82:85], v156 offset:53248
	ds_read_b128 v[90:93], v156 offset:54272
	ds_read_b128 v[118:121], v156 offset:55296
	ds_read_b128 v[126:129], v156 offset:56320
	global_load_lds_dwordx4 v[26:27], off
	s_mov_b32 m0, s38
	s_nop 0
	global_load_lds_dwordx4 v[28:29], off
	s_mov_b32 m0, s40
	s_nop 0
	global_load_lds_dwordx4 v[68:69], off
	s_mov_b32 m0, s41
	s_nop 0
	global_load_lds_dwordx4 v[70:71], off
	s_mov_b32 m0, s37
	s_nop 0
	global_load_lds_dwordx4 v[24:25], off
	s_mov_b32 m0, s39
	s_nop 0
	global_load_lds_dwordx4 v[30:31], off
	s_waitcnt vmcnt(8)
	s_waitcnt lgkmcnt(0)
	s_barrier
	s_setprio 1
	s_waitcnt lgkmcnt(0)
	v_mfma_f32_16x16x32_bf16 v[2:5], v[110:113], v[10:13], v[2:5]
	v_mfma_f32_16x16x32_bf16 v[26:29], v[114:117], v[14:17], v[2:5]
	v_mfma_f32_16x16x32_bf16 v[2:5], v[122:125], v[10:13], v[6:9]
	v_mfma_f32_16x16x32_bf16 v[30:33], v[130:133], v[14:17], v[2:5]
	v_mfma_f32_16x16x32_bf16 v[2:5], v[110:113], v[74:77], v[18:21]
	v_mfma_f32_16x16x32_bf16 v[18:21], v[114:117], v[78:81], v[2:5]
	v_mfma_f32_16x16x32_bf16 v[2:5], v[122:125], v[74:77], v[86:89]
	v_mfma_f32_16x16x32_bf16 v[22:25], v[130:133], v[78:81], v[2:5]
	s_setprio 0
	s_setprio 1
	v_mfma_f32_16x16x32_bf16 v[2:5], v[110:113], v[82:85], v[94:97]
	v_mfma_f32_16x16x32_bf16 v[10:13], v[114:117], v[90:93], v[2:5]
	v_mfma_f32_16x16x32_bf16 v[2:5], v[122:125], v[82:85], v[98:101]
	v_mfma_f32_16x16x32_bf16 v[14:17], v[130:133], v[90:93], v[2:5]
	v_mfma_f32_16x16x32_bf16 v[2:5], v[110:113], v[118:121], v[102:105]
	v_mfma_f32_16x16x32_bf16 v[6:9], v[122:125], v[118:121], v[106:109]
	v_mfma_f32_16x16x32_bf16 v[2:5], v[114:117], v[126:129], v[2:5]
	v_mfma_f32_16x16x32_bf16 v[6:9], v[130:133], v[126:129], v[6:9]
	s_setprio 0
	s_setprio 1
	s_setprio 0
	s_barrier
	s_cbranch_scc1 .LBB0_594
	s_barrier

; #define PG8_STAGE(bufoff, gbase, voff) do { _Pragma("unroll") for (int _i = 0; _i < 2; ++_i) \
;         __builtin_amdgcn_global_load_lds((const unsigned*)((const char*)(gbase) + (voff)[_i]), (PG8_LAS unsigned*)(lds + (bufoff) + ldsw + _i * 8192), 16, 0, 0); } while (0)
; #define PG8_LDA(dst, b, h) do { _Pragma("unroll") for (int m = 0; m < 4; ++m) _Pragma("unroll") for (int k = 0; k < 2; ++k) dst[m][k] = *(const PG8_LAS bf16x8*)(lds + PG8_SA(b, h) + aoff + m * 2048 + k * 1024); } while (0)
; #define PG8_LDB(dst, b, h) do { _Pragma("unroll") for (int n = 0; n < 2; ++n) _Pragma("unroll") for (int k = 0; k < 2; ++k) dst[n][k] = *(const PG8_LAS bf16x8*)(lds + PG8_SB(b, h) + boff + n * 2048 + k * 1024); } while (0)
; #define PG8_MMA(ai, bj, At, Bt) do { __builtin_amdgcn_s_setprio(1); _Pragma("unroll") for (int m = 0; m < 4; ++m) _Pragma("unroll") for (int n = 0; n < 2; ++n) _Pragma("unroll") for (int k = 0; k < 2; ++k) \
;         acc[ai][bj][m][n] = __builtin_amdgcn_mfma_f32_16x16x32_bf16(Bt[n][k], At[m][k], acc[ai][bj][m][n], 0, 0, 0); __builtin_amdgcn_s_setprio(0); } while (0)
; #define PG8_WAIT_V(n) asm volatile("s_waitcnt vmcnt(" #n ")" ::: "memory")
; #define PG8_BAR __builtin_amdgcn_s_barrier()
; template <class Epi, class Sched, bool ALIGN_EPI = false, bool SP2 = false>
; __device__ __forceinline__ void gemm_phase(PG8_LAS unsigned char* lds, const Gemm g, const Sched& S, const Epi& E) {
;     ...
;         for (int t = 0; t < nt; t += 2) {
;             const bool last = (t == nt - 2);
;             const char* a1 = cA + (size_t)(t + 1) * kstep;
;             const char* a2 = last ? nA : cA + (size_t)(t + 2) * kstep; const char* b2 = last ? nB : cB + (size_t)(t + 2) * kstep;
;             const char* a3 = a2 + kstep; const char* b3 = b2 + kstep;
;             if (last && has_next) S.a_ready(nxt);
;             if constexpr (SP2) {
;             PG8_LDB(B0, 0, 0); PG8_LDB(B1, 0, 1); PG8_SCHED; PG8_LDA(At, 0, 0); PG8_STAGE(PG8_SA(1, 1), a1 + hstepA, voffA);
;             PG8_WAIT_V(8); PG8_WAIT_L(0); PG8_BAR; PG8_MMA(0, 0, At, B0); PG8_MMA(0, 1, At, B1); PG8_BAR; PG8_SCHED;
;             PG8_LDA(At, 0, 1); PG8_STAGE(PG8_SB(0, 0), b2, voffB); PG8_STAGE(PG8_SB(0, 1), b2 + hstepB, voffB); PG8_STAGE(PG8_SA(0, 0), a2, voffA);
;             PG8_WAIT_V(8); PG8_WAIT_L(0); PG8_BAR; PG8_MMA(1, 0, At, B0); PG8_MMA(1, 1, At, B1); PG8_BAR; PG8_SCHED;
.LBB0_1160:
	s_add_u32 s24, s22, 0x100
	s_addc_u32 s25, s23, 0
	s_add_i32 s57, 0, 0x10000
	s_cmp_eq_u32 s56, 4
	s_cselect_b32 s29, s17, s25
	s_cselect_b32 s28, s16, s24
	v_add_u32_e32 v145, s57, v142
	s_cselect_b32 s27, s52, s55
	s_cselect_b32 s26, s53, s54
	s_add_i32 s58, 0, 0x14000
	ds_read_b128 v[146:149], v145
	ds_read_b128 v[150:153], v145 offset:1024
	ds_read_b128 v[154:157], v145 offset:2048
	ds_read_b128 v[158:161], v145 offset:3072
	v_add_u32_e32 v145, s58, v142
	ds_read_b128 v[162:165], v145
	ds_read_b128 v[166:169], v145 offset:1024
	ds_read_b128 v[170:173], v145 offset:2048
	ds_read_b128 v[174:177], v145 offset:3072
	s_add_i32 m0, s39, 0xc000
	ds_read_b128 v[178:181], v143
	ds_read_b128 v[182:185], v143 offset:1024
	ds_read_b128 v[202:205], v143 offset:2048
	ds_read_b128 v[206:209], v143 offset:3072
	ds_read_b128 v[210:213], v143 offset:4096
	ds_read_b128 v[232:235], v143 offset:5120
	ds_read_b128 v[236:239], v143 offset:6144
	ds_read_b128 v[240:243], v143 offset:7168
	global_load_lds_dwordx4 v138, s[22:23]
	s_add_i32 m0, s39, 0xe000
	s_nop 0
	global_load_lds_dwordx4 v140, s[22:23]
	s_waitcnt vmcnt(8)
	s_waitcnt lgkmcnt(0)
	s_barrier
	s_setprio 1
	s_waitcnt lgkmcnt(0)
	v_mfma_f32_16x16x32_bf16 v[126:129], v[146:149], v[178:181], v[126:129]
	v_mfma_f32_16x16x32_bf16 v[122:125], v[154:157], v[178:181], v[122:125]
	v_mfma_f32_16x16x32_bf16 v[118:121], v[146:149], v[202:205], v[118:121]
	v_mfma_f32_16x16x32_bf16 v[114:117], v[154:157], v[202:205], v[114:117]
	v_mfma_f32_16x16x32_bf16 v[110:113], v[146:149], v[210:213], v[110:113]
	v_mfma_f32_16x16x32_bf16 v[106:109], v[154:157], v[210:213], v[106:109]
	v_mfma_f32_16x16x32_bf16 v[102:105], v[146:149], v[236:239], v[102:105]
	v_mfma_f32_16x16x32_bf16 v[98:101], v[154:157], v[236:239], v[98:101]
	s_setprio 0
	s_setprio 1
	v_mfma_f32_16x16x32_bf16 v[126:129], v[150:153], v[182:185], v[126:129]
	v_mfma_f32_16x16x32_bf16 v[122:125], v[158:161], v[182:185], v[122:125]
	v_mfma_f32_16x16x32_bf16 v[118:121], v[150:153], v[206:209], v[118:121]
	v_mfma_f32_16x16x32_bf16 v[114:117], v[158:161], v[206:209], v[114:117]
	v_mfma_f32_16x16x32_bf16 v[110:113], v[150:153], v[232:235], v[110:113]
	v_mfma_f32_16x16x32_bf16 v[106:109], v[158:161], v[232:235], v[106:109]
	v_mfma_f32_16x16x32_bf16 v[102:105], v[150:153], v[240:243], v[102:105]
	v_mfma_f32_16x16x32_bf16 v[98:101], v[158:161], v[240:243], v[98:101]
	s_setprio 0
	s_setprio 1
	v_mfma_f32_16x16x32_bf16 v[78:81], v[162:165], v[178:181], v[78:81]
	v_mfma_f32_16x16x32_bf16 v[70:73], v[170:173], v[178:181], v[70:73]
	v_mfma_f32_16x16x32_bf16 v[62:65], v[162:165], v[202:205], v[62:65]
	v_mfma_f32_16x16x32_bf16 v[54:57], v[170:173], v[202:205], v[54:57]
	v_mfma_f32_16x16x32_bf16 v[46:49], v[162:165], v[210:213], v[46:49]
	v_mfma_f32_16x16x32_bf16 v[42:45], v[170:173], v[210:213], v[42:45]
	v_mfma_f32_16x16x32_bf16 v[38:41], v[162:165], v[236:239], v[38:41]
	v_mfma_f32_16x16x32_bf16 v[34:37], v[170:173], v[236:239], v[34:37]
	s_setprio 0
	s_setprio 1
	v_mfma_f32_16x16x32_bf16 v[78:81], v[166:169], v[182:185], v[78:81]
	v_mfma_f32_16x16x32_bf16 v[70:73], v[174:177], v[182:185], v[70:73]
	v_mfma_f32_16x16x32_bf16 v[62:65], v[166:169], v[206:209], v[62:65]
	v_mfma_f32_16x16x32_bf16 v[54:57], v[174:177], v[206:209], v[54:57]
	v_mfma_f32_16x16x32_bf16 v[46:49], v[166:169], v[232:235], v[46:49]
	v_mfma_f32_16x16x32_bf16 v[42:45], v[174:177], v[232:235], v[42:45]
	v_mfma_f32_16x16x32_bf16 v[38:41], v[166:169], v[240:243], v[38:41]
	v_mfma_f32_16x16x32_bf16 v[34:37], v[174:177], v[240:243], v[34:37]
	s_setprio 0
	s_barrier
	s_add_i32 s22, s57, s38
	s_mov_b32 m0, s22
	ds_read_b128 v[178:181], v143 offset:16384
	ds_read_b128 v[182:185], v143 offset:17408
	ds_read_b128 v[202:205], v143 offset:18432
	ds_read_b128 v[206:209], v143 offset:19456
	ds_read_b128 v[210:213], v143 offset:20480
	ds_read_b128 v[232:235], v143 offset:21504
	ds_read_b128 v[236:239], v143 offset:22528
	ds_read_b128 v[240:243], v143 offset:23552
	s_add_u32 s60, s26, 0x80
	s_addc_u32 s61, s27, 0
	s_add_u32 s62, s28, 0x80
	s_addc_u32 s63, s29, 0
	global_load_lds_dwordx4 v134, s[26:27]
	s_add_i32 m0, s22, 0x2000
	s_add_u32 s22, s26, 0x20000
	s_addc_u32 s23, s27, 0
	s_add_i32 s57, s58, s38
	global_load_lds_dwordx4 v130, s[26:27]
	s_mov_b32 m0, s57
	s_nop 0
	global_load_lds_dwordx4 v134, s[22:23]
	s_add_i32 m0, s57, 0x2000
	s_nop 0
	global_load_lds_dwordx4 v130, s[22:23]
	s_mov_b32 m0, s39
	s_nop 0
	global_load_lds_dwordx4 v136, s[28:29]
	s_mov_b32 m0, s40
	s_nop 0
	global_load_lds_dwordx4 v132, s[28:29]
	s_waitcnt vmcnt(8)
	s_waitcnt lgkmcnt(0)
	s_barrier
; #define PG8_STAGE(bufoff, gbase, voff) do { _Pragma("unroll") for (int _i = 0; _i < 2; ++_i) \
;         __builtin_amdgcn_global_load_lds((const unsigned*)((const char*)(gbase) + (voff)[_i]), (PG8_LAS unsigned*)(lds + (bufoff) + ldsw + _i * 8192), 16, 0, 0); } while (0)
; #define PG8_LDA(dst, b, h) do { _Pragma("unroll") for (int m = 0; m < 4; ++m) _Pragma("unroll") for (int k = 0; k < 2; ++k) dst[m][k] = *(const PG8_LAS bf16x8*)(lds + PG8_SA(b, h) + aoff + m * 2048 + k * 1024); } while (0)
; #define PG8_LDB(dst, b, h) do { _Pragma("unroll") for (int n = 0; n < 2; ++n) _Pragma("unroll") for (int k = 0; k < 2; ++k) dst[n][k] = *(const PG8_LAS bf16x8*)(lds + PG8_SB(b, h) + boff + n * 2048 + k * 1024); } while (0)
; #define PG8_MMA(ai, bj, At, Bt) do { __builtin_amdgcn_s_setprio(1); _Pragma("unroll") for (int m = 0; m < 4; ++m) _Pragma("unroll") for (int n = 0; n < 2; ++n) _Pragma("unroll") for (int k = 0; k < 2; ++k) \
;         acc[ai][bj][m][n] = __builtin_amdgcn_mfma_f32_16x16x32_bf16(Bt[n][k], At[m][k], acc[ai][bj][m][n], 0, 0, 0); __builtin_amdgcn_s_setprio(0); } while (0)
; #define PG8_WAIT_V(n) asm volatile("s_waitcnt vmcnt(" #n ")" ::: "memory")
; #define PG8_WAIT_L(n) asm volatile("s_waitcnt lgkmcnt(" #n ")" ::: "memory")
; #define PG8_BAR __builtin_amdgcn_s_barrier()
; #define PG8_SCHED __builtin_amdgcn_sched_barrier(0)
; template <class Epi, class Sched, bool ALIGN_EPI = false, bool SP2 = false>
; __device__ __forceinline__ void gemm_phase(PG8_LAS unsigned char* lds, const Gemm g, const Sched& S, const Epi& E) {
;     ...
;             PG8_WAIT_V(8); PG8_WAIT_L(0); PG8_BAR; PG8_MMA(1, 0, At, B0); PG8_MMA(1, 1, At, B1); PG8_BAR; PG8_SCHED;
;             PG8_LDB(B0, 1, 0); PG8_LDB(B1, 1, 1); PG8_SCHED; PG8_LDA(At, 1, 0); PG8_STAGE(PG8_SA(0, 1), a2 + hstepA, voffA);
;             PG8_WAIT_V(8); PG8_WAIT_L(0); PG8_BAR; PG8_MMA(0, 0, At, B0); PG8_MMA(0, 1, At, B1); PG8_BAR; PG8_SCHED;
	s_setprio 1
	s_waitcnt lgkmcnt(0)
	v_mfma_f32_16x16x32_bf16 v[94:97], v[146:149], v[178:181], v[94:97]
	v_mfma_f32_16x16x32_bf16 v[90:93], v[154:157], v[178:181], v[90:93]
	v_mfma_f32_16x16x32_bf16 v[86:89], v[146:149], v[202:205], v[86:89]
	v_mfma_f32_16x16x32_bf16 v[82:85], v[154:157], v[202:205], v[82:85]
	v_mfma_f32_16x16x32_bf16 v[74:77], v[146:149], v[210:213], v[74:77]
	v_mfma_f32_16x16x32_bf16 v[66:69], v[154:157], v[210:213], v[66:69]
	v_mfma_f32_16x16x32_bf16 v[58:61], v[146:149], v[236:239], v[58:61]
	v_mfma_f32_16x16x32_bf16 v[50:53], v[154:157], v[236:239], v[50:53]
	s_setprio 0
	s_setprio 1
	v_mfma_f32_16x16x32_bf16 v[94:97], v[150:153], v[182:185], v[94:97]
	v_mfma_f32_16x16x32_bf16 v[90:93], v[158:161], v[182:185], v[90:93]
	v_mfma_f32_16x16x32_bf16 v[86:89], v[150:153], v[206:209], v[86:89]
	v_mfma_f32_16x16x32_bf16 v[82:85], v[158:161], v[206:209], v[82:85]
	v_mfma_f32_16x16x32_bf16 v[74:77], v[150:153], v[232:235], v[74:77]
	v_mfma_f32_16x16x32_bf16 v[66:69], v[158:161], v[232:235], v[66:69]
	v_mfma_f32_16x16x32_bf16 v[58:61], v[150:153], v[240:243], v[58:61]
	v_mfma_f32_16x16x32_bf16 v[50:53], v[158:161], v[240:243], v[50:53]
	s_setprio 0
	s_setprio 1
	v_mfma_f32_16x16x32_bf16 v[30:33], v[162:165], v[178:181], v[30:33]
	v_mfma_f32_16x16x32_bf16 v[26:29], v[170:173], v[178:181], v[26:29]
	v_mfma_f32_16x16x32_bf16 v[22:25], v[162:165], v[202:205], v[22:25]
	v_mfma_f32_16x16x32_bf16 v[18:21], v[170:173], v[202:205], v[18:21]
	v_mfma_f32_16x16x32_bf16 v[14:17], v[162:165], v[210:213], v[14:17]
	v_mfma_f32_16x16x32_bf16 v[10:13], v[170:173], v[210:213], v[10:13]
	v_mfma_f32_16x16x32_bf16 v[6:9], v[162:165], v[236:239], v[6:9]
	v_mfma_f32_16x16x32_bf16 v[2:5], v[170:173], v[236:239], v[2:5]
	s_setprio 0
	s_setprio 1
	v_mfma_f32_16x16x32_bf16 v[30:33], v[166:169], v[182:185], v[30:33]
	v_mfma_f32_16x16x32_bf16 v[26:29], v[174:177], v[182:185], v[26:29]
	v_mfma_f32_16x16x32_bf16 v[22:25], v[166:169], v[206:209], v[22:25]
	v_mfma_f32_16x16x32_bf16 v[18:21], v[174:177], v[206:209], v[18:21]
	v_mfma_f32_16x16x32_bf16 v[14:17], v[166:169], v[232:235], v[14:17]
	v_mfma_f32_16x16x32_bf16 v[10:13], v[174:177], v[232:235], v[10:13]
	v_mfma_f32_16x16x32_bf16 v[6:9], v[166:169], v[240:243], v[6:9]
	v_mfma_f32_16x16x32_bf16 v[2:5], v[174:177], v[240:243], v[2:5]
	s_setprio 0
	s_barrier
	s_add_i32 s57, 0, 0x18000
	v_add_u32_e32 v145, s57, v142
	s_add_i32 s58, 0, 0x1c000
	ds_read_b128 v[146:149], v145
	ds_read_b128 v[150:153], v145 offset:1024
	ds_read_b128 v[154:157], v145 offset:2048
	ds_read_b128 v[158:161], v145 offset:3072
	v_add_u32_e32 v145, s58, v142
	ds_read_b128 v[162:165], v145
	ds_read_b128 v[166:169], v145 offset:1024
	ds_read_b128 v[170:173], v145 offset:2048
	ds_read_b128 v[174:177], v145 offset:3072
	s_add_u32 s22, s28, 0x30000
	s_addc_u32 s23, s29, 0
	s_mov_b32 m0, s41
	ds_read_b128 v[178:181], v143 offset:32768
	ds_read_b128 v[182:185], v143 offset:33792
	ds_read_b128 v[202:205], v143 offset:34816
	ds_read_b128 v[206:209], v143 offset:35840
	ds_read_b128 v[210:213], v143 offset:36864
	ds_read_b128 v[232:235], v143 offset:37888
	ds_read_b128 v[236:239], v143 offset:38912
	ds_read_b128 v[240:243], v143 offset:39936
	global_load_lds_dwordx4 v136, s[22:23]
	s_mov_b32 m0, s42
	s_nop 0
	global_load_lds_dwordx4 v132, s[22:23]
	s_waitcnt vmcnt(8)
	s_waitcnt lgkmcnt(0)
	s_barrier
	s_setprio 1
	s_waitcnt lgkmcnt(0)
	v_mfma_f32_16x16x32_bf16 v[126:129], v[146:149], v[178:181], v[126:129]
	v_mfma_f32_16x16x32_bf16 v[122:125], v[154:157], v[178:181], v[122:125]
	v_mfma_f32_16x16x32_bf16 v[118:121], v[146:149], v[202:205], v[118:121]
	v_mfma_f32_16x16x32_bf16 v[114:117], v[154:157], v[202:205], v[114:117]
	v_mfma_f32_16x16x32_bf16 v[110:113], v[146:149], v[210:213], v[110:113]
	v_mfma_f32_16x16x32_bf16 v[106:109], v[154:157], v[210:213], v[106:109]
	v_mfma_f32_16x16x32_bf16 v[102:105], v[146:149], v[236:239], v[102:105]
	v_mfma_f32_16x16x32_bf16 v[98:101], v[154:157], v[236:239], v[98:101]
	s_setprio 0
	s_setprio 1
	v_mfma_f32_16x16x32_bf16 v[126:129], v[150:153], v[182:185], v[126:129]
	v_mfma_f32_16x16x32_bf16 v[122:125], v[158:161], v[182:185], v[122:125]
	v_mfma_f32_16x16x32_bf16 v[118:121], v[150:153], v[206:209], v[118:121]
	v_mfma_f32_16x16x32_bf16 v[114:117], v[158:161], v[206:209], v[114:117]
	v_mfma_f32_16x16x32_bf16 v[110:113], v[150:153], v[232:235], v[110:113]
	v_mfma_f32_16x16x32_bf16 v[106:109], v[158:161], v[232:235], v[106:109]
	v_mfma_f32_16x16x32_bf16 v[102:105], v[150:153], v[240:243], v[102:105]
	v_mfma_f32_16x16x32_bf16 v[98:101], v[158:161], v[240:243], v[98:101]
	s_setprio 0
	s_setprio 1
	v_mfma_f32_16x16x32_bf16 v[78:81], v[162:165], v[178:181], v[78:81]
	v_mfma_f32_16x16x32_bf16 v[70:73], v[170:173], v[178:181], v[70:73]
	v_mfma_f32_16x16x32_bf16 v[62:65], v[162:165], v[202:205], v[62:65]
	v_mfma_f32_16x16x32_bf16 v[54:57], v[170:173], v[202:205], v[54:57]
	v_mfma_f32_16x16x32_bf16 v[46:49], v[162:165], v[210:213], v[46:49]
	v_mfma_f32_16x16x32_bf16 v[42:45], v[170:173], v[210:213], v[42:45]
	v_mfma_f32_16x16x32_bf16 v[38:41], v[162:165], v[236:239], v[38:41]
	v_mfma_f32_16x16x32_bf16 v[34:37], v[170:173], v[236:239], v[34:37]
	s_setprio 0
	s_setprio 1
	v_mfma_f32_16x16x32_bf16 v[78:81], v[166:169], v[182:185], v[78:81]
	v_mfma_f32_16x16x32_bf16 v[70:73], v[174:177], v[182:185], v[70:73]
	v_mfma_f32_16x16x32_bf16 v[62:65], v[166:169], v[206:209], v[62:65]
	v_mfma_f32_16x16x32_bf16 v[54:57], v[174:177], v[206:209], v[54:57]
	v_mfma_f32_16x16x32_bf16 v[46:49], v[166:169], v[232:235], v[46:49]
	v_mfma_f32_16x16x32_bf16 v[42:45], v[174:177], v[232:235], v[42:45]
	v_mfma_f32_16x16x32_bf16 v[38:41], v[166:169], v[240:243], v[38:41]
	v_mfma_f32_16x16x32_bf16 v[34:37], v[174:177], v[240:243], v[34:37]
	s_setprio 0
	s_barrier
; #define PG8_STAGE(bufoff, gbase, voff) do { _Pragma("unroll") for (int _i = 0; _i < 2; ++_i) \
;         __builtin_amdgcn_global_load_lds((const unsigned*)((const char*)(gbase) + (voff)[_i]), (PG8_LAS unsigned*)(lds + (bufoff) + ldsw + _i * 8192), 16, 0, 0); } while (0)
; #define PG8_LDA(dst, b, h) do { _Pragma("unroll") for (int m = 0; m < 4; ++m) _Pragma("unroll") for (int k = 0; k < 2; ++k) dst[m][k] = *(const PG8_LAS bf16x8*)(lds + PG8_SA(b, h) + aoff + m * 2048 + k * 1024); } while (0)
; #define PG8_MMA(ai, bj, At, Bt) do { __builtin_amdgcn_s_setprio(1); _Pragma("unroll") for (int m = 0; m < 4; ++m) _Pragma("unroll") for (int n = 0; n < 2; ++n) _Pragma("unroll") for (int k = 0; k < 2; ++k) \
;         acc[ai][bj][m][n] = __builtin_amdgcn_mfma_f32_16x16x32_bf16(Bt[n][k], At[m][k], acc[ai][bj][m][n], 0, 0, 0); __builtin_amdgcn_s_setprio(0); } while (0)
; #define PG8_WAIT_V(n) asm volatile("s_waitcnt vmcnt(" #n ")" ::: "memory")
; #define PG8_WAIT_L(n) asm volatile("s_waitcnt lgkmcnt(" #n ")" ::: "memory")
; #define PG8_BAR __builtin_amdgcn_s_barrier()
; #define PG8_SCHED __builtin_amdgcn_sched_barrier(0)
; template <class Epi, class Sched, bool ALIGN_EPI = false, bool SP2 = false>
; __device__ __forceinline__ void gemm_phase(PG8_LAS unsigned char* lds, const Gemm g, const Sched& S, const Epi& E) {
;     ...
;             PG8_LDA(At, 1, 1); PG8_STAGE(PG8_SB(1, 0), b3, voffB); PG8_STAGE(PG8_SB(1, 1), b3 + hstepB, voffB); PG8_STAGE(PG8_SA(1, 0), a3, voffA);
;             PG8_WAIT_V(8); PG8_WAIT_L(0); PG8_BAR; PG8_MMA(1, 0, At, B0); PG8_MMA(1, 1, At, B1); PG8_BAR; PG8_SCHED;
	s_add_i32 s22, s57, s38
	s_mov_b32 m0, s22
	ds_read_b128 v[178:181], v143 offset:49152
	ds_read_b128 v[182:185], v143 offset:50176
	ds_read_b128 v[202:205], v143 offset:51200
	ds_read_b128 v[206:209], v143 offset:52224
	ds_read_b128 v[210:213], v143 offset:53248
	ds_read_b128 v[232:235], v143 offset:54272
	ds_read_b128 v[236:239], v143 offset:55296
	ds_read_b128 v[240:243], v143 offset:56320
	global_load_lds_dwordx4 v134, s[60:61]
	s_add_i32 m0, s22, 0x2000
	s_add_u32 s22, s26, 0x20080
	s_addc_u32 s23, s27, 0
	s_add_i32 s26, s58, s38
	global_load_lds_dwordx4 v130, s[60:61]
	s_mov_b32 m0, s26
	s_nop 0
	global_load_lds_dwordx4 v134, s[22:23]
	s_add_i32 m0, s26, 0x2000
	s_nop 0
	global_load_lds_dwordx4 v130, s[22:23]
	s_mov_b32 m0, s43
	s_nop 0
	global_load_lds_dwordx4 v136, s[62:63]
	s_mov_b32 m0, s46
	s_nop 0
	global_load_lds_dwordx4 v132, s[62:63]
	s_waitcnt vmcnt(8)
	s_waitcnt lgkmcnt(0)
	s_barrier
	s_setprio 1
	s_waitcnt lgkmcnt(0)
	v_mfma_f32_16x16x32_bf16 v[94:97], v[146:149], v[178:181], v[94:97]
	v_mfma_f32_16x16x32_bf16 v[90:93], v[154:157], v[178:181], v[90:93]
	v_mfma_f32_16x16x32_bf16 v[86:89], v[146:149], v[202:205], v[86:89]
	v_mfma_f32_16x16x32_bf16 v[82:85], v[154:157], v[202:205], v[82:85]
	v_mfma_f32_16x16x32_bf16 v[74:77], v[146:149], v[210:213], v[74:77]
	v_mfma_f32_16x16x32_bf16 v[66:69], v[154:157], v[210:213], v[66:69]
	v_mfma_f32_16x16x32_bf16 v[58:61], v[146:149], v[236:239], v[58:61]
	v_mfma_f32_16x16x32_bf16 v[50:53], v[154:157], v[236:239], v[50:53]
	s_setprio 0
	s_setprio 1
	v_mfma_f32_16x16x32_bf16 v[94:97], v[150:153], v[182:185], v[94:97]
	v_mfma_f32_16x16x32_bf16 v[90:93], v[158:161], v[182:185], v[90:93]
	v_mfma_f32_16x16x32_bf16 v[86:89], v[150:153], v[206:209], v[86:89]
	v_mfma_f32_16x16x32_bf16 v[82:85], v[158:161], v[206:209], v[82:85]
	v_mfma_f32_16x16x32_bf16 v[74:77], v[150:153], v[232:235], v[74:77]
	v_mfma_f32_16x16x32_bf16 v[66:69], v[158:161], v[232:235], v[66:69]
	v_mfma_f32_16x16x32_bf16 v[58:61], v[150:153], v[240:243], v[58:61]
	v_mfma_f32_16x16x32_bf16 v[50:53], v[158:161], v[240:243], v[50:53]
	s_setprio 0
	s_setprio 1
	v_mfma_f32_16x16x32_bf16 v[30:33], v[162:165], v[178:181], v[30:33]
	v_mfma_f32_16x16x32_bf16 v[26:29], v[170:173], v[178:181], v[26:29]
	v_mfma_f32_16x16x32_bf16 v[22:25], v[162:165], v[202:205], v[22:25]
	v_mfma_f32_16x16x32_bf16 v[18:21], v[170:173], v[202:205], v[18:21]
	v_mfma_f32_16x16x32_bf16 v[14:17], v[162:165], v[210:213], v[14:17]
	v_mfma_f32_16x16x32_bf16 v[10:13], v[170:173], v[210:213], v[10:13]
	v_mfma_f32_16x16x32_bf16 v[6:9], v[162:165], v[236:239], v[6:9]
	v_mfma_f32_16x16x32_bf16 v[2:5], v[170:173], v[236:239], v[2:5]
	s_setprio 0
	s_setprio 1
	v_mfma_f32_16x16x32_bf16 v[30:33], v[166:169], v[182:185], v[30:33]
	v_mfma_f32_16x16x32_bf16 v[26:29], v[174:177], v[182:185], v[26:29]
	v_mfma_f32_16x16x32_bf16 v[22:25], v[166:169], v[206:209], v[22:25]
	v_mfma_f32_16x16x32_bf16 v[18:21], v[174:177], v[206:209], v[18:21]
	v_mfma_f32_16x16x32_bf16 v[14:17], v[166:169], v[232:235], v[14:17]
	v_mfma_f32_16x16x32_bf16 v[10:13], v[174:177], v[232:235], v[10:13]
	v_mfma_f32_16x16x32_bf16 v[6:9], v[166:169], v[240:243], v[6:9]
	v_mfma_f32_16x16x32_bf16 v[2:5], v[174:177], v[240:243], v[2:5]
	s_setprio 0
	s_barrier
	s_add_i32 s56, s56, 2
	s_add_u32 s54, s54, 0x100
	s_addc_u32 s55, s55, 0
	s_cmp_gt_u32 s56, 5
	s_mov_b64 s[22:23], s[24:25]
	s_cbranch_scc0 .LBB0_1160
	s_and_b64 vcc, exec, s[8:9]
	s_cbranch_vccz .LBB0_1163
	s_barrier

; #define PG8_STAGE(bufoff, gbase, voff) do { _Pragma("unroll") for (int _i = 0; _i < 2; ++_i) \
;         __builtin_amdgcn_global_load_lds((const unsigned*)((const char*)(gbase) + (voff)[_i]), (PG8_LAS unsigned*)(lds + (bufoff) + ldsw + _i * 8192), 16, 0, 0); } while (0)
; #define PG8_LDA(dst, b, h) do { _Pragma("unroll") for (int m = 0; m < 4; ++m) _Pragma("unroll") for (int k = 0; k < 2; ++k) dst[m][k] = *(const PG8_LAS bf16x8*)(lds + PG8_SA(b, h) + aoff + m * 2048 + k * 1024); } while (0)
; #define PG8_LDB(dst, b, h) do { _Pragma("unroll") for (int n = 0; n < 2; ++n) _Pragma("unroll") for (int k = 0; k < 2; ++k) dst[n][k] = *(const PG8_LAS bf16x8*)(lds + PG8_SB(b, h) + boff + n * 2048 + k * 1024); } while (0)
; #define PG8_WAIT_V(n) asm volatile("s_waitcnt vmcnt(" #n ")" ::: "memory")
; #define PG8_WAIT_L(n) asm volatile("s_waitcnt lgkmcnt(" #n ")" ::: "memory")
; #define PG8_BAR __builtin_amdgcn_s_barrier()
; #define PG8_SCHED __builtin_amdgcn_sched_barrier(0)
; template <class Epi, class Sched, bool ALIGN_EPI = false, bool SP2 = false>
; __device__ __forceinline__ void gemm_phase(PG8_LAS unsigned char* lds, const Gemm g, const Sched& S, const Epi& E) {
;     ...
;         const char* nA = has_next ? (const char*)g.A + (size_t)nxt.pm * tstepA : cA; const char* nB = has_next ? (const char*)g.Bt + (size_t)nxt.pn * tstepB : cB;
;         for (int t = 0; t < nt; t += 2) {
;             const bool last = (t == nt - 2);
;             const char* a1 = cA + (size_t)(t + 1) * kstep;
;             const char* a2 = last ? nA : cA + (size_t)(t + 2) * kstep; const char* b2 = last ? nB : cB + (size_t)(t + 2) * kstep;
;             const char* a3 = a2 + kstep; const char* b3 = b2 + kstep;
;             if (last && has_next) S.a_ready(nxt);
;             if constexpr (SP2) {
;             PG8_LDB(B0, 0, 0); PG8_LDB(B1, 0, 1); PG8_SCHED; PG8_LDA(At, 0, 0); PG8_STAGE(PG8_SA(1, 1), a1 + hstepA, voffA);
;             PG8_WAIT_V(8); PG8_WAIT_L(0); PG8_BAR; PG8_MMA(0, 0, At, B0); PG8_MMA(0, 1, At, B1); PG8_BAR; PG8_SCHED;
;             PG8_LDA(At, 0, 1); PG8_STAGE(PG8_SB(0, 0), b2, voffB); PG8_STAGE(PG8_SB(0, 1), b2 + hstepB, voffB); PG8_STAGE(PG8_SA(0, 0), a2, voffA);
;             PG8_WAIT_V(8); PG8_WAIT_L(0); PG8_BAR; PG8_MMA(1, 0, At, B0); PG8_MMA(1, 1, At, B1); PG8_BAR; PG8_SCHED;
.LBB0_1176:
	s_add_u32 s35, s26, s34
	s_addc_u32 s40, s27, 0
	s_add_u32 s38, s35, 0x100
	s_addc_u32 s39, s40, 0
	s_and_b64 s[36:37], s[30:31], exec
	s_cselect_b32 s37, s19, s39
	s_cselect_b32 s36, s18, s38
	s_add_u32 s34, s24, s34
	s_addc_u32 s38, s25, 0
	s_add_u32 s34, s34, 0x100
	s_addc_u32 s38, s38, 0
	s_add_i32 s72, 0, 0x10000
	s_and_b64 s[30:31], s[30:31], exec
	s_cselect_b32 s39, s61, s38
	s_cselect_b32 s38, s62, s34
	s_add_i32 s31, 0, 0x14000
	s_add_u32 s42, s35, 0x30080
	s_addc_u32 s43, s40, 0
	s_add_i32 s71, s72, s50
	s_add_i32 m0, s51, 0xc000
	s_add_i32 s74, s51, 0xe000
	s_add_i32 s67, s71, 0x2000
	v_add_u32_e32 v141, s72, v138
	s_add_u32 s40, s38, 0x10000
	ds_read_b128 v[142:145], v141
	ds_read_b128 v[146:149], v141 offset:1024
	ds_read_b128 v[150:153], v141 offset:2048
	ds_read_b128 v[154:157], v141 offset:3072
	v_add_u32_e32 v141, s31, v138
	s_addc_u32 s41, s39, 0
	s_add_i32 s69, s31, s50
	ds_read_b128 v[158:161], v141
	ds_read_b128 v[162:165], v141 offset:1024
	ds_read_b128 v[166:169], v141 offset:2048
	ds_read_b128 v[170:173], v141 offset:3072
	s_add_i32 s68, s69, 0x2000
	s_add_i32 s66, 0, 0x18000
	s_add_i32 s65, 0, 0x1c000
	s_add_u32 s34, s36, 0x30000
	s_addc_u32 s35, s37, 0
	s_add_i32 s64, s66, s50
	s_add_i32 s63, s64, 0x2000
	s_add_u32 s30, s38, 0x10080
	s_addc_u32 s31, s39, 0
	s_add_i32 s73, s65, s50
	s_add_i32 s72, s73, 0x2000
	v_lshl_add_u64 v[186:187], s[42:43], 0, v[136:137]
	ds_read_b128 v[174:177], v140
	ds_read_b128 v[178:181], v140 offset:1024
	ds_read_b128 v[182:185], v140 offset:2048
	ds_read_b128 v[202:205], v140 offset:3072
	ds_read_b128 v[206:209], v140 offset:4096
	ds_read_b128 v[210:213], v140 offset:5120
	ds_read_b128 v[232:235], v140 offset:6144
	ds_read_b128 v[236:239], v140 offset:7168
	global_load_lds_dwordx4 v[186:187], off
	v_lshl_add_u64 v[186:187], s[42:43], 0, v[132:133]
	s_mov_b32 m0, s74
	s_nop 0
	global_load_lds_dwordx4 v[186:187], off
	s_waitcnt vmcnt(8)
	s_waitcnt lgkmcnt(0)
	s_barrier
	s_setprio 1
	s_waitcnt lgkmcnt(0)
	v_mfma_f32_16x16x32_bf16 v[126:129], v[142:145], v[174:177], v[126:129]
	v_mfma_f32_16x16x32_bf16 v[122:125], v[150:153], v[174:177], v[122:125]
	v_mfma_f32_16x16x32_bf16 v[118:121], v[142:145], v[182:185], v[118:121]
	v_mfma_f32_16x16x32_bf16 v[114:117], v[150:153], v[182:185], v[114:117]
	v_mfma_f32_16x16x32_bf16 v[110:113], v[142:145], v[206:209], v[110:113]
	v_mfma_f32_16x16x32_bf16 v[106:109], v[150:153], v[206:209], v[106:109]
	v_mfma_f32_16x16x32_bf16 v[102:105], v[142:145], v[232:235], v[102:105]
	v_mfma_f32_16x16x32_bf16 v[98:101], v[150:153], v[232:235], v[98:101]
	s_setprio 0
	s_setprio 1
	v_mfma_f32_16x16x32_bf16 v[126:129], v[146:149], v[178:181], v[126:129]
	v_mfma_f32_16x16x32_bf16 v[122:125], v[154:157], v[178:181], v[122:125]
	v_mfma_f32_16x16x32_bf16 v[118:121], v[146:149], v[202:205], v[118:121]
	v_mfma_f32_16x16x32_bf16 v[114:117], v[154:157], v[202:205], v[114:117]
	v_mfma_f32_16x16x32_bf16 v[110:113], v[146:149], v[210:213], v[110:113]
	v_mfma_f32_16x16x32_bf16 v[106:109], v[154:157], v[210:213], v[106:109]
	v_mfma_f32_16x16x32_bf16 v[102:105], v[146:149], v[236:239], v[102:105]
	v_mfma_f32_16x16x32_bf16 v[98:101], v[154:157], v[236:239], v[98:101]
	s_setprio 0
	s_setprio 1
	v_mfma_f32_16x16x32_bf16 v[78:81], v[158:161], v[174:177], v[78:81]
	v_mfma_f32_16x16x32_bf16 v[70:73], v[166:169], v[174:177], v[70:73]
	v_mfma_f32_16x16x32_bf16 v[62:65], v[158:161], v[182:185], v[62:65]
	v_mfma_f32_16x16x32_bf16 v[54:57], v[166:169], v[182:185], v[54:57]
	v_mfma_f32_16x16x32_bf16 v[46:49], v[158:161], v[206:209], v[46:49]
	v_mfma_f32_16x16x32_bf16 v[42:45], v[166:169], v[206:209], v[42:45]
	v_mfma_f32_16x16x32_bf16 v[38:41], v[158:161], v[232:235], v[38:41]
	v_mfma_f32_16x16x32_bf16 v[34:37], v[166:169], v[232:235], v[34:37]
	s_setprio 0
	s_setprio 1
	v_mfma_f32_16x16x32_bf16 v[78:81], v[162:165], v[178:181], v[78:81]
	v_mfma_f32_16x16x32_bf16 v[70:73], v[170:173], v[178:181], v[70:73]
	v_mfma_f32_16x16x32_bf16 v[62:65], v[162:165], v[202:205], v[62:65]
	v_mfma_f32_16x16x32_bf16 v[54:57], v[170:173], v[202:205], v[54:57]
	v_mfma_f32_16x16x32_bf16 v[46:49], v[162:165], v[210:213], v[46:49]
	v_mfma_f32_16x16x32_bf16 v[42:45], v[170:173], v[210:213], v[42:45]
	v_mfma_f32_16x16x32_bf16 v[38:41], v[162:165], v[236:239], v[38:41]
	v_mfma_f32_16x16x32_bf16 v[34:37], v[170:173], v[236:239], v[34:37]
	s_setprio 0
	s_barrier
	s_mov_b32 m0, s71
	v_lshl_add_u64 v[186:187], s[38:39], 0, v[134:135]
	ds_read_b128 v[174:177], v140 offset:16384
	ds_read_b128 v[178:181], v140 offset:17408
	ds_read_b128 v[182:185], v140 offset:18432
	ds_read_b128 v[202:205], v140 offset:19456
	ds_read_b128 v[206:209], v140 offset:20480
	ds_read_b128 v[210:213], v140 offset:21504
	ds_read_b128 v[232:235], v140 offset:22528
	ds_read_b128 v[236:239], v140 offset:23552
	global_load_lds_dwordx4 v[186:187], off
	v_lshl_add_u64 v[214:215], s[38:39], 0, v[130:131]
	s_mov_b32 m0, s67
	v_lshl_add_u64 v[240:241], s[40:41], 0, v[134:135]
	global_load_lds_dwordx4 v[214:215], off
	s_mov_b32 m0, s69
	v_lshl_add_u64 v[242:243], s[36:37], 0, v[132:133]
	global_load_lds_dwordx4 v[240:241], off
	v_lshl_add_u64 v[240:241], s[40:41], 0, v[130:131]
	s_mov_b32 m0, s68
	s_nop 0
	global_load_lds_dwordx4 v[240:241], off
	v_lshl_add_u64 v[240:241], s[36:37], 0, v[136:137]
	s_mov_b32 m0, s51
	s_nop 0
	global_load_lds_dwordx4 v[240:241], off
	s_mov_b32 m0, s52
	s_nop 0
	global_load_lds_dwordx4 v[242:243], off
	s_waitcnt vmcnt(8)
	s_waitcnt lgkmcnt(0)
	s_barrier
; #define PG8_STAGE(bufoff, gbase, voff) do { _Pragma("unroll") for (int _i = 0; _i < 2; ++_i) \
;         __builtin_amdgcn_global_load_lds((const unsigned*)((const char*)(gbase) + (voff)[_i]), (PG8_LAS unsigned*)(lds + (bufoff) + ldsw + _i * 8192), 16, 0, 0); } while (0)
; #define PG8_LDA(dst, b, h) do { _Pragma("unroll") for (int m = 0; m < 4; ++m) _Pragma("unroll") for (int k = 0; k < 2; ++k) dst[m][k] = *(const PG8_LAS bf16x8*)(lds + PG8_SA(b, h) + aoff + m * 2048 + k * 1024); } while (0)
; #define PG8_LDB(dst, b, h) do { _Pragma("unroll") for (int n = 0; n < 2; ++n) _Pragma("unroll") for (int k = 0; k < 2; ++k) dst[n][k] = *(const PG8_LAS bf16x8*)(lds + PG8_SB(b, h) + boff + n * 2048 + k * 1024); } while (0)
; #define PG8_MMA(ai, bj, At, Bt) do { __builtin_amdgcn_s_setprio(1); _Pragma("unroll") for (int m = 0; m < 4; ++m) _Pragma("unroll") for (int n = 0; n < 2; ++n) _Pragma("unroll") for (int k = 0; k < 2; ++k) \
;         acc[ai][bj][m][n] = __builtin_amdgcn_mfma_f32_16x16x32_bf16(Bt[n][k], At[m][k], acc[ai][bj][m][n], 0, 0, 0); __builtin_amdgcn_s_setprio(0); } while (0)
; #define PG8_WAIT_V(n) asm volatile("s_waitcnt vmcnt(" #n ")" ::: "memory")
; #define PG8_WAIT_L(n) asm volatile("s_waitcnt lgkmcnt(" #n ")" ::: "memory")
; #define PG8_BAR __builtin_amdgcn_s_barrier()
; #define PG8_SCHED __builtin_amdgcn_sched_barrier(0)
; template <class Epi, class Sched, bool ALIGN_EPI = false, bool SP2 = false>
; __device__ __forceinline__ void gemm_phase(PG8_LAS unsigned char* lds, const Gemm g, const Sched& S, const Epi& E) {
;     ...
;             PG8_WAIT_V(8); PG8_WAIT_L(0); PG8_BAR; PG8_MMA(1, 0, At, B0); PG8_MMA(1, 1, At, B1); PG8_BAR; PG8_SCHED;
;             PG8_LDB(B0, 1, 0); PG8_LDB(B1, 1, 1); PG8_SCHED; PG8_LDA(At, 1, 0); PG8_STAGE(PG8_SA(0, 1), a2 + hstepA, voffA);
;             PG8_WAIT_V(8); PG8_WAIT_L(0); PG8_BAR; PG8_MMA(0, 0, At, B0); PG8_MMA(0, 1, At, B1); PG8_BAR; PG8_SCHED;
	s_setprio 1
	s_waitcnt lgkmcnt(0)
	v_mfma_f32_16x16x32_bf16 v[94:97], v[142:145], v[174:177], v[94:97]
	v_mfma_f32_16x16x32_bf16 v[90:93], v[150:153], v[174:177], v[90:93]
	v_mfma_f32_16x16x32_bf16 v[86:89], v[142:145], v[182:185], v[86:89]
	v_mfma_f32_16x16x32_bf16 v[82:85], v[150:153], v[182:185], v[82:85]
	v_mfma_f32_16x16x32_bf16 v[74:77], v[142:145], v[206:209], v[74:77]
	v_mfma_f32_16x16x32_bf16 v[66:69], v[150:153], v[206:209], v[66:69]
	v_mfma_f32_16x16x32_bf16 v[58:61], v[142:145], v[232:235], v[58:61]
	v_mfma_f32_16x16x32_bf16 v[50:53], v[150:153], v[232:235], v[50:53]
	s_setprio 0
	s_setprio 1
	v_mfma_f32_16x16x32_bf16 v[94:97], v[146:149], v[178:181], v[94:97]
	v_mfma_f32_16x16x32_bf16 v[90:93], v[154:157], v[178:181], v[90:93]
	v_mfma_f32_16x16x32_bf16 v[86:89], v[146:149], v[202:205], v[86:89]
	v_mfma_f32_16x16x32_bf16 v[82:85], v[154:157], v[202:205], v[82:85]
	v_mfma_f32_16x16x32_bf16 v[74:77], v[146:149], v[210:213], v[74:77]
	v_mfma_f32_16x16x32_bf16 v[66:69], v[154:157], v[210:213], v[66:69]
	v_mfma_f32_16x16x32_bf16 v[58:61], v[146:149], v[236:239], v[58:61]
	v_mfma_f32_16x16x32_bf16 v[50:53], v[154:157], v[236:239], v[50:53]
	s_setprio 0
	s_setprio 1
	v_mfma_f32_16x16x32_bf16 v[30:33], v[158:161], v[174:177], v[30:33]
	v_mfma_f32_16x16x32_bf16 v[26:29], v[166:169], v[174:177], v[26:29]
	v_mfma_f32_16x16x32_bf16 v[22:25], v[158:161], v[182:185], v[22:25]
	v_mfma_f32_16x16x32_bf16 v[18:21], v[166:169], v[182:185], v[18:21]
	v_mfma_f32_16x16x32_bf16 v[14:17], v[158:161], v[206:209], v[14:17]
	v_mfma_f32_16x16x32_bf16 v[10:13], v[166:169], v[206:209], v[10:13]
	v_mfma_f32_16x16x32_bf16 v[6:9], v[158:161], v[232:235], v[6:9]
	v_mfma_f32_16x16x32_bf16 v[2:5], v[166:169], v[232:235], v[2:5]
	s_setprio 0
	s_setprio 1
	v_mfma_f32_16x16x32_bf16 v[30:33], v[162:165], v[178:181], v[30:33]
	v_mfma_f32_16x16x32_bf16 v[26:29], v[170:173], v[178:181], v[26:29]
	v_mfma_f32_16x16x32_bf16 v[22:25], v[162:165], v[202:205], v[22:25]
	v_mfma_f32_16x16x32_bf16 v[18:21], v[170:173], v[202:205], v[18:21]
	v_mfma_f32_16x16x32_bf16 v[14:17], v[162:165], v[210:213], v[14:17]
	v_mfma_f32_16x16x32_bf16 v[10:13], v[170:173], v[210:213], v[10:13]
	v_mfma_f32_16x16x32_bf16 v[6:9], v[162:165], v[236:239], v[6:9]
	v_mfma_f32_16x16x32_bf16 v[2:5], v[170:173], v[236:239], v[2:5]
	s_setprio 0
	s_barrier
	v_add_u32_e32 v141, s66, v138
	ds_read_b128 v[142:145], v141
	ds_read_b128 v[146:149], v141 offset:1024
	ds_read_b128 v[150:153], v141 offset:2048
	ds_read_b128 v[154:157], v141 offset:3072
	v_add_u32_e32 v141, s65, v138
	ds_read_b128 v[158:161], v141
	ds_read_b128 v[162:165], v141 offset:1024
	ds_read_b128 v[166:169], v141 offset:2048
	ds_read_b128 v[170:173], v141 offset:3072
	s_mov_b32 m0, s53
	v_lshl_add_u64 v[244:245], s[34:35], 0, v[136:137]
	ds_read_b128 v[174:177], v140 offset:32768
	ds_read_b128 v[178:181], v140 offset:33792
	ds_read_b128 v[182:185], v140 offset:34816
	ds_read_b128 v[202:205], v140 offset:35840
	ds_read_b128 v[206:209], v140 offset:36864
	ds_read_b128 v[210:213], v140 offset:37888
	ds_read_b128 v[232:235], v140 offset:38912
	ds_read_b128 v[236:239], v140 offset:39936
	global_load_lds_dwordx4 v[244:245], off
	v_lshl_add_u64 v[244:245], s[34:35], 0, v[132:133]
	s_mov_b32 m0, s54
	s_nop 0
	global_load_lds_dwordx4 v[244:245], off
	s_waitcnt vmcnt(8)
	s_waitcnt lgkmcnt(0)
	s_barrier
	s_setprio 1
	s_waitcnt lgkmcnt(0)
	v_mfma_f32_16x16x32_bf16 v[126:129], v[142:145], v[174:177], v[126:129]
	v_mfma_f32_16x16x32_bf16 v[122:125], v[150:153], v[174:177], v[122:125]
	v_mfma_f32_16x16x32_bf16 v[118:121], v[142:145], v[182:185], v[118:121]
	v_mfma_f32_16x16x32_bf16 v[114:117], v[150:153], v[182:185], v[114:117]
	v_mfma_f32_16x16x32_bf16 v[110:113], v[142:145], v[206:209], v[110:113]
	v_mfma_f32_16x16x32_bf16 v[106:109], v[150:153], v[206:209], v[106:109]
	v_mfma_f32_16x16x32_bf16 v[102:105], v[142:145], v[232:235], v[102:105]
	v_mfma_f32_16x16x32_bf16 v[98:101], v[150:153], v[232:235], v[98:101]
	s_setprio 0
	s_setprio 1
	v_mfma_f32_16x16x32_bf16 v[126:129], v[146:149], v[178:181], v[126:129]
	v_mfma_f32_16x16x32_bf16 v[122:125], v[154:157], v[178:181], v[122:125]
	v_mfma_f32_16x16x32_bf16 v[118:121], v[146:149], v[202:205], v[118:121]
	v_mfma_f32_16x16x32_bf16 v[114:117], v[154:157], v[202:205], v[114:117]
	v_mfma_f32_16x16x32_bf16 v[110:113], v[146:149], v[210:213], v[110:113]
	v_mfma_f32_16x16x32_bf16 v[106:109], v[154:157], v[210:213], v[106:109]
	v_mfma_f32_16x16x32_bf16 v[102:105], v[146:149], v[236:239], v[102:105]
	v_mfma_f32_16x16x32_bf16 v[98:101], v[154:157], v[236:239], v[98:101]
	s_setprio 0
	s_setprio 1
	v_mfma_f32_16x16x32_bf16 v[78:81], v[158:161], v[174:177], v[78:81]
	v_mfma_f32_16x16x32_bf16 v[70:73], v[166:169], v[174:177], v[70:73]
	v_mfma_f32_16x16x32_bf16 v[62:65], v[158:161], v[182:185], v[62:65]
	v_mfma_f32_16x16x32_bf16 v[54:57], v[166:169], v[182:185], v[54:57]
	v_mfma_f32_16x16x32_bf16 v[46:49], v[158:161], v[206:209], v[46:49]
	v_mfma_f32_16x16x32_bf16 v[42:45], v[166:169], v[206:209], v[42:45]
	v_mfma_f32_16x16x32_bf16 v[38:41], v[158:161], v[232:235], v[38:41]
	v_mfma_f32_16x16x32_bf16 v[34:37], v[166:169], v[232:235], v[34:37]
	s_setprio 0
	s_setprio 1
	v_mfma_f32_16x16x32_bf16 v[78:81], v[162:165], v[178:181], v[78:81]
	v_mfma_f32_16x16x32_bf16 v[70:73], v[170:173], v[178:181], v[70:73]
	v_mfma_f32_16x16x32_bf16 v[62:65], v[162:165], v[202:205], v[62:65]
	v_mfma_f32_16x16x32_bf16 v[54:57], v[170:173], v[202:205], v[54:57]
	v_mfma_f32_16x16x32_bf16 v[46:49], v[162:165], v[210:213], v[46:49]
	v_mfma_f32_16x16x32_bf16 v[42:45], v[170:173], v[210:213], v[42:45]
	v_mfma_f32_16x16x32_bf16 v[38:41], v[162:165], v[236:239], v[38:41]
	v_mfma_f32_16x16x32_bf16 v[34:37], v[170:173], v[236:239], v[34:37]
	s_setprio 0
	s_barrier
; #define PG8_STAGE(bufoff, gbase, voff) do { _Pragma("unroll") for (int _i = 0; _i < 2; ++_i) \
;         __builtin_amdgcn_global_load_lds((const unsigned*)((const char*)(gbase) + (voff)[_i]), (PG8_LAS unsigned*)(lds + (bufoff) + ldsw + _i * 8192), 16, 0, 0); } while (0)
; #define PG8_LDA(dst, b, h) do { _Pragma("unroll") for (int m = 0; m < 4; ++m) _Pragma("unroll") for (int k = 0; k < 2; ++k) dst[m][k] = *(const PG8_LAS bf16x8*)(lds + PG8_SA(b, h) + aoff + m * 2048 + k * 1024); } while (0)
; #define PG8_MMA(ai, bj, At, Bt) do { __builtin_amdgcn_s_setprio(1); _Pragma("unroll") for (int m = 0; m < 4; ++m) _Pragma("unroll") for (int n = 0; n < 2; ++n) _Pragma("unroll") for (int k = 0; k < 2; ++k) \
;         acc[ai][bj][m][n] = __builtin_amdgcn_mfma_f32_16x16x32_bf16(Bt[n][k], At[m][k], acc[ai][bj][m][n], 0, 0, 0); __builtin_amdgcn_s_setprio(0); } while (0)
; #define PG8_WAIT_V(n) asm volatile("s_waitcnt vmcnt(" #n ")" ::: "memory")
; #define PG8_WAIT_L(n) asm volatile("s_waitcnt lgkmcnt(" #n ")" ::: "memory")
; #define PG8_BAR __builtin_amdgcn_s_barrier()
; #define PG8_SCHED __builtin_amdgcn_sched_barrier(0)
; template <class Epi, class Sched, bool ALIGN_EPI = false, bool SP2 = false>
; __device__ __forceinline__ void gemm_phase(PG8_LAS unsigned char* lds, const Gemm g, const Sched& S, const Epi& E) {
;     ...
;             PG8_LDA(At, 1, 1); PG8_STAGE(PG8_SB(1, 0), b3, voffB); PG8_STAGE(PG8_SB(1, 1), b3 + hstepB, voffB); PG8_STAGE(PG8_SA(1, 0), a3, voffA);
;             PG8_WAIT_V(8); PG8_WAIT_L(0); PG8_BAR; PG8_MMA(1, 0, At, B0); PG8_MMA(1, 1, At, B1); PG8_BAR; PG8_SCHED;
	s_mov_b32 m0, s64
	v_lshl_add_u64 v[186:187], v[186:187], 0, s[96:97]
	ds_read_b128 v[174:177], v140 offset:49152
	ds_read_b128 v[178:181], v140 offset:50176
	ds_read_b128 v[182:185], v140 offset:51200
	ds_read_b128 v[202:205], v140 offset:52224
	ds_read_b128 v[206:209], v140 offset:53248
	ds_read_b128 v[210:213], v140 offset:54272
	ds_read_b128 v[232:235], v140 offset:55296
	ds_read_b128 v[236:239], v140 offset:56320
	global_load_lds_dwordx4 v[186:187], off
	v_lshl_add_u64 v[186:187], v[214:215], 0, s[96:97]
	s_mov_b32 m0, s63
	s_nop 0
	global_load_lds_dwordx4 v[186:187], off
	v_lshl_add_u64 v[186:187], s[30:31], 0, v[134:135]
	s_mov_b32 m0, s73
	s_nop 0
	global_load_lds_dwordx4 v[186:187], off
	v_lshl_add_u64 v[186:187], s[30:31], 0, v[130:131]
	s_mov_b32 m0, s72
	s_nop 0
	global_load_lds_dwordx4 v[186:187], off
	v_lshl_add_u64 v[186:187], v[240:241], 0, s[96:97]
	s_mov_b32 m0, s55
	s_nop 0
	global_load_lds_dwordx4 v[186:187], off
	v_lshl_add_u64 v[186:187], v[242:243], 0, s[96:97]
	s_mov_b32 m0, s56
	s_nop 0
	global_load_lds_dwordx4 v[186:187], off
	s_waitcnt vmcnt(8)
	s_waitcnt lgkmcnt(0)
	s_barrier
	s_setprio 1
	s_waitcnt lgkmcnt(0)
	v_mfma_f32_16x16x32_bf16 v[94:97], v[142:145], v[174:177], v[94:97]
	v_mfma_f32_16x16x32_bf16 v[90:93], v[150:153], v[174:177], v[90:93]
	v_mfma_f32_16x16x32_bf16 v[86:89], v[142:145], v[182:185], v[86:89]
	v_mfma_f32_16x16x32_bf16 v[82:85], v[150:153], v[182:185], v[82:85]
	v_mfma_f32_16x16x32_bf16 v[74:77], v[142:145], v[206:209], v[74:77]
	v_mfma_f32_16x16x32_bf16 v[66:69], v[150:153], v[206:209], v[66:69]
	v_mfma_f32_16x16x32_bf16 v[58:61], v[142:145], v[232:235], v[58:61]
	v_mfma_f32_16x16x32_bf16 v[50:53], v[150:153], v[232:235], v[50:53]
	s_setprio 0
	s_setprio 1
	v_mfma_f32_16x16x32_bf16 v[94:97], v[146:149], v[178:181], v[94:97]
	v_mfma_f32_16x16x32_bf16 v[90:93], v[154:157], v[178:181], v[90:93]
	v_mfma_f32_16x16x32_bf16 v[86:89], v[146:149], v[202:205], v[86:89]
	v_mfma_f32_16x16x32_bf16 v[82:85], v[154:157], v[202:205], v[82:85]
	v_mfma_f32_16x16x32_bf16 v[74:77], v[146:149], v[210:213], v[74:77]
	v_mfma_f32_16x16x32_bf16 v[66:69], v[154:157], v[210:213], v[66:69]
	v_mfma_f32_16x16x32_bf16 v[58:61], v[146:149], v[236:239], v[58:61]
	v_mfma_f32_16x16x32_bf16 v[50:53], v[154:157], v[236:239], v[50:53]
	s_setprio 0
	s_setprio 1
	v_mfma_f32_16x16x32_bf16 v[30:33], v[158:161], v[174:177], v[30:33]
	v_mfma_f32_16x16x32_bf16 v[26:29], v[166:169], v[174:177], v[26:29]
	v_mfma_f32_16x16x32_bf16 v[22:25], v[158:161], v[182:185], v[22:25]
	v_mfma_f32_16x16x32_bf16 v[18:21], v[166:169], v[182:185], v[18:21]
	v_mfma_f32_16x16x32_bf16 v[14:17], v[158:161], v[206:209], v[14:17]
	v_mfma_f32_16x16x32_bf16 v[10:13], v[166:169], v[206:209], v[10:13]
	v_mfma_f32_16x16x32_bf16 v[6:9], v[158:161], v[232:235], v[6:9]
	v_mfma_f32_16x16x32_bf16 v[2:5], v[166:169], v[232:235], v[2:5]
	s_setprio 0
	s_setprio 1
	v_mfma_f32_16x16x32_bf16 v[30:33], v[162:165], v[178:181], v[30:33]
	v_mfma_f32_16x16x32_bf16 v[26:29], v[170:173], v[178:181], v[26:29]
	v_mfma_f32_16x16x32_bf16 v[22:25], v[162:165], v[202:205], v[22:25]
	v_mfma_f32_16x16x32_bf16 v[18:21], v[170:173], v[202:205], v[18:21]
	v_mfma_f32_16x16x32_bf16 v[14:17], v[162:165], v[210:213], v[14:17]
	v_mfma_f32_16x16x32_bf16 v[10:13], v[170:173], v[210:213], v[10:13]
	v_mfma_f32_16x16x32_bf16 v[6:9], v[162:165], v[236:239], v[6:9]
	v_mfma_f32_16x16x32_bf16 v[2:5], v[170:173], v[236:239], v[2:5]
	s_setprio 0
	s_barrier
	s_movk_i32 s34, 0x100
	s_andn2_b64 vcc, exec, s[28:29]
	s_mov_b64 s[30:31], -1
	s_mov_b64 s[28:29], 0
	s_cbranch_vccz .LBB0_1176
	s_and_b64 vcc, exec, s[16:17]
	s_cbranch_vccz .LBB0_1179
	s_barrier

; #define PG8_STAGE(bufoff, gbase, voff) do { _Pragma("unroll") for (int _i = 0; _i < 2; ++_i) \
;         __builtin_amdgcn_global_load_lds((const unsigned*)((const char*)(gbase) + (voff)[_i]), (PG8_LAS unsigned*)(lds + (bufoff) + ldsw + _i * 8192), 16, 0, 0); } while (0)
; #define PG8_LDA(dst, b, h) do { _Pragma("unroll") for (int m = 0; m < 4; ++m) _Pragma("unroll") for (int k = 0; k < 2; ++k) dst[m][k] = *(const PG8_LAS bf16x8*)(lds + PG8_SA(b, h) + aoff + m * 2048 + k * 1024); } while (0)
; #define PG8_LDB(dst, b, h) do { _Pragma("unroll") for (int n = 0; n < 2; ++n) _Pragma("unroll") for (int k = 0; k < 2; ++k) dst[n][k] = *(const PG8_LAS bf16x8*)(lds + PG8_SB(b, h) + boff + n * 2048 + k * 1024); } while (0)
; #define PG8_MMA(ai, bj, At, Bt) do { __builtin_amdgcn_s_setprio(1); _Pragma("unroll") for (int m = 0; m < 4; ++m) _Pragma("unroll") for (int n = 0; n < 2; ++n) _Pragma("unroll") for (int k = 0; k < 2; ++k) \
;         acc[ai][bj][m][n] = __builtin_amdgcn_mfma_f32_16x16x32_bf16(Bt[n][k], At[m][k], acc[ai][bj][m][n], 0, 0, 0); __builtin_amdgcn_s_setprio(0); } while (0)
; #define PG8_WAIT_V(n) asm volatile("s_waitcnt vmcnt(" #n ")" ::: "memory")
; #define PG8_BAR __builtin_amdgcn_s_barrier()
; template <class Epi, class Sched, bool ALIGN_EPI = false, bool SP2 = false>
; __device__ __forceinline__ void gemm_phase(PG8_LAS unsigned char* lds, const Gemm g, const Sched& S, const Epi& E) {
;     ...
;         for (int t = 0; t < nt; t += 2) {
;             const bool last = (t == nt - 2);
;             const char* a1 = cA + (size_t)(t + 1) * kstep;
;             const char* a2 = last ? nA : cA + (size_t)(t + 2) * kstep; const char* b2 = last ? nB : cB + (size_t)(t + 2) * kstep;
;             const char* a3 = a2 + kstep; const char* b3 = b2 + kstep;
;             if (last && has_next) S.a_ready(nxt);
;             if constexpr (SP2) {
;             PG8_LDB(B0, 0, 0); PG8_LDB(B1, 0, 1); PG8_SCHED; PG8_LDA(At, 0, 0); PG8_STAGE(PG8_SA(1, 1), a1 + hstepA, voffA);
;             PG8_WAIT_V(8); PG8_WAIT_L(0); PG8_BAR; PG8_MMA(0, 0, At, B0); PG8_MMA(0, 1, At, B1); PG8_BAR; PG8_SCHED;
;             PG8_LDA(At, 0, 1); PG8_STAGE(PG8_SB(0, 0), b2, voffB); PG8_STAGE(PG8_SB(0, 1), b2 + hstepB, voffB); PG8_STAGE(PG8_SA(0, 0), a2, voffA);
;             PG8_WAIT_V(8); PG8_WAIT_L(0); PG8_BAR; PG8_MMA(1, 0, At, B0); PG8_MMA(1, 1, At, B1); PG8_BAR; PG8_SCHED;
.LBB0_1190:
	s_add_u32 s24, s22, 0xfffc0080
	s_addc_u32 s25, s23, -1
	s_add_i32 s51, 0, 0x10000
	s_cmp_eq_u32 s50, 12
	s_cselect_b32 s27, s44, s25
	s_cselect_b32 s26, s45, s24
	s_cselect_b32 s25, s46, s49
	s_cselect_b32 s24, s47, s48
	s_add_i32 s54, 0, 0x14000
	v_add_u32_e32 v142, s51, v168
	v_add_u32_e32 v166, s54, v168
	ds_read_b128 v[130:133], v142
	ds_read_b128 v[134:137], v142 offset:1024
	ds_read_b128 v[138:141], v142 offset:2048
	ds_read_b128 v[142:145], v142 offset:3072
	ds_read_b128 v[158:161], v166
	ds_read_b128 v[162:165], v166 offset:1024
	ds_read_b128 v[172:175], v166 offset:2048
	ds_read_b128 v[176:179], v166 offset:3072
	s_add_i32 m0, s7, 0xc000
	ds_read_b128 v[180:183], v171
	ds_read_b128 v[184:187], v171 offset:1024
	ds_read_b128 v[202:205], v171 offset:2048
	ds_read_b128 v[206:209], v171 offset:3072
	ds_read_b128 v[210:213], v171 offset:4096
	ds_read_b128 v[232:235], v171 offset:5120
	ds_read_b128 v[236:239], v171 offset:6144
	ds_read_b128 v[240:243], v171 offset:7168
	global_load_lds_dwordx4 v154, s[22:23]
	s_add_i32 m0, s7, 0xe000
	s_nop 0
	global_load_lds_dwordx4 v156, s[22:23]
	s_waitcnt vmcnt(8)
	s_waitcnt lgkmcnt(0)
	s_barrier
	s_setprio 1
	s_waitcnt lgkmcnt(0)
	v_mfma_f32_16x16x32_bf16 v[126:129], v[130:133], v[180:183], v[126:129]
	v_mfma_f32_16x16x32_bf16 v[118:121], v[138:141], v[180:183], v[118:121]
	v_mfma_f32_16x16x32_bf16 v[110:113], v[130:133], v[202:205], v[110:113]
	v_mfma_f32_16x16x32_bf16 v[102:105], v[138:141], v[202:205], v[102:105]
	v_mfma_f32_16x16x32_bf16 v[94:97], v[130:133], v[210:213], v[94:97]
	v_mfma_f32_16x16x32_bf16 v[86:89], v[138:141], v[210:213], v[86:89]
	v_mfma_f32_16x16x32_bf16 v[78:81], v[130:133], v[236:239], v[78:81]
	v_mfma_f32_16x16x32_bf16 v[70:73], v[138:141], v[236:239], v[70:73]
	s_setprio 0
	s_setprio 1
	v_mfma_f32_16x16x32_bf16 v[126:129], v[134:137], v[184:187], v[126:129]
	v_mfma_f32_16x16x32_bf16 v[118:121], v[142:145], v[184:187], v[118:121]
	v_mfma_f32_16x16x32_bf16 v[110:113], v[134:137], v[206:209], v[110:113]
	v_mfma_f32_16x16x32_bf16 v[102:105], v[142:145], v[206:209], v[102:105]
	v_mfma_f32_16x16x32_bf16 v[94:97], v[134:137], v[232:235], v[94:97]
	v_mfma_f32_16x16x32_bf16 v[86:89], v[142:145], v[232:235], v[86:89]
	v_mfma_f32_16x16x32_bf16 v[78:81], v[134:137], v[240:243], v[78:81]
	v_mfma_f32_16x16x32_bf16 v[70:73], v[142:145], v[240:243], v[70:73]
	s_setprio 0
	s_setprio 1
	v_mfma_f32_16x16x32_bf16 v[122:125], v[158:161], v[180:183], v[122:125]
	v_mfma_f32_16x16x32_bf16 v[114:117], v[172:175], v[180:183], v[114:117]
	v_mfma_f32_16x16x32_bf16 v[106:109], v[158:161], v[202:205], v[106:109]
	v_mfma_f32_16x16x32_bf16 v[98:101], v[172:175], v[202:205], v[98:101]
	v_mfma_f32_16x16x32_bf16 v[90:93], v[158:161], v[210:213], v[90:93]
	v_mfma_f32_16x16x32_bf16 v[82:85], v[172:175], v[210:213], v[82:85]
	v_mfma_f32_16x16x32_bf16 v[74:77], v[158:161], v[236:239], v[74:77]
	v_mfma_f32_16x16x32_bf16 v[66:69], v[172:175], v[236:239], v[66:69]
	s_setprio 0
	s_setprio 1
	v_mfma_f32_16x16x32_bf16 v[122:125], v[162:165], v[184:187], v[122:125]
	v_mfma_f32_16x16x32_bf16 v[114:117], v[176:179], v[184:187], v[114:117]
	v_mfma_f32_16x16x32_bf16 v[106:109], v[162:165], v[206:209], v[106:109]
	v_mfma_f32_16x16x32_bf16 v[98:101], v[176:179], v[206:209], v[98:101]
	v_mfma_f32_16x16x32_bf16 v[90:93], v[162:165], v[232:235], v[90:93]
	v_mfma_f32_16x16x32_bf16 v[82:85], v[176:179], v[232:235], v[82:85]
	v_mfma_f32_16x16x32_bf16 v[74:77], v[162:165], v[240:243], v[74:77]
	v_mfma_f32_16x16x32_bf16 v[66:69], v[176:179], v[240:243], v[66:69]
	s_setprio 0
	s_barrier
	s_add_i32 s51, s51, s30
	s_mov_b32 m0, s51
	ds_read_b128 v[180:183], v171 offset:16384
	ds_read_b128 v[184:187], v171 offset:17408
	ds_read_b128 v[202:205], v171 offset:18432
	ds_read_b128 v[206:209], v171 offset:19456
	ds_read_b128 v[210:213], v171 offset:20480
	ds_read_b128 v[232:235], v171 offset:21504
	ds_read_b128 v[236:239], v171 offset:22528
	ds_read_b128 v[240:243], v171 offset:23552
	s_add_u32 s60, s24, 0x80
	s_addc_u32 s61, s25, 0
	s_add_u32 s62, s26, 0x80
	s_addc_u32 s63, s27, 0
	global_load_lds_dwordx4 v150, s[24:25]
	s_add_i32 m0, s51, 0x2000
	s_add_u32 s52, s24, 0x40000
	s_addc_u32 s53, s25, 0
	s_add_i32 s51, s54, s30
	global_load_lds_dwordx4 v146, s[24:25]
	s_mov_b32 m0, s51
	s_nop 0
	global_load_lds_dwordx4 v150, s[52:53]
	s_add_i32 m0, s51, 0x2000
	s_nop 0
	global_load_lds_dwordx4 v146, s[52:53]
	s_mov_b32 m0, s7
	s_nop 0
	global_load_lds_dwordx4 v152, s[26:27]
	s_mov_b32 m0, s36
	s_nop 0
	global_load_lds_dwordx4 v148, s[26:27]
	s_waitcnt vmcnt(8)
	s_waitcnt lgkmcnt(0)
	s_barrier
; #define PG8_STAGE(bufoff, gbase, voff) do { _Pragma("unroll") for (int _i = 0; _i < 2; ++_i) \
;         __builtin_amdgcn_global_load_lds((const unsigned*)((const char*)(gbase) + (voff)[_i]), (PG8_LAS unsigned*)(lds + (bufoff) + ldsw + _i * 8192), 16, 0, 0); } while (0)
; #define PG8_LDA(dst, b, h) do { _Pragma("unroll") for (int m = 0; m < 4; ++m) _Pragma("unroll") for (int k = 0; k < 2; ++k) dst[m][k] = *(const PG8_LAS bf16x8*)(lds + PG8_SA(b, h) + aoff + m * 2048 + k * 1024); } while (0)
; #define PG8_LDB(dst, b, h) do { _Pragma("unroll") for (int n = 0; n < 2; ++n) _Pragma("unroll") for (int k = 0; k < 2; ++k) dst[n][k] = *(const PG8_LAS bf16x8*)(lds + PG8_SB(b, h) + boff + n * 2048 + k * 1024); } while (0)
; #define PG8_MMA(ai, bj, At, Bt) do { __builtin_amdgcn_s_setprio(1); _Pragma("unroll") for (int m = 0; m < 4; ++m) _Pragma("unroll") for (int n = 0; n < 2; ++n) _Pragma("unroll") for (int k = 0; k < 2; ++k) \
;         acc[ai][bj][m][n] = __builtin_amdgcn_mfma_f32_16x16x32_bf16(Bt[n][k], At[m][k], acc[ai][bj][m][n], 0, 0, 0); __builtin_amdgcn_s_setprio(0); } while (0)
; #define PG8_WAIT_V(n) asm volatile("s_waitcnt vmcnt(" #n ")" ::: "memory")
; #define PG8_WAIT_L(n) asm volatile("s_waitcnt lgkmcnt(" #n ")" ::: "memory")
; #define PG8_BAR __builtin_amdgcn_s_barrier()
; #define PG8_SCHED __builtin_amdgcn_sched_barrier(0)
; template <class Epi, class Sched, bool ALIGN_EPI = false, bool SP2 = false>
; __device__ __forceinline__ void gemm_phase(PG8_LAS unsigned char* lds, const Gemm g, const Sched& S, const Epi& E) {
;     ...
;             PG8_WAIT_V(8); PG8_WAIT_L(0); PG8_BAR; PG8_MMA(1, 0, At, B0); PG8_MMA(1, 1, At, B1); PG8_BAR; PG8_SCHED;
;             PG8_LDB(B0, 1, 0); PG8_LDB(B1, 1, 1); PG8_SCHED; PG8_LDA(At, 1, 0); PG8_STAGE(PG8_SA(0, 1), a2 + hstepA, voffA);
;             PG8_WAIT_V(8); PG8_WAIT_L(0); PG8_BAR; PG8_MMA(0, 0, At, B0); PG8_MMA(0, 1, At, B1); PG8_BAR; PG8_SCHED;
	s_setprio 1
	s_waitcnt lgkmcnt(0)
	v_mfma_f32_16x16x32_bf16 v[62:65], v[130:133], v[180:183], v[62:65]
	v_mfma_f32_16x16x32_bf16 v[54:57], v[138:141], v[180:183], v[54:57]
	v_mfma_f32_16x16x32_bf16 v[46:49], v[130:133], v[202:205], v[46:49]
	v_mfma_f32_16x16x32_bf16 v[38:41], v[138:141], v[202:205], v[38:41]
	v_mfma_f32_16x16x32_bf16 v[30:33], v[130:133], v[210:213], v[30:33]
	v_mfma_f32_16x16x32_bf16 v[22:25], v[138:141], v[210:213], v[22:25]
	v_mfma_f32_16x16x32_bf16 v[14:17], v[130:133], v[236:239], v[14:17]
	v_mfma_f32_16x16x32_bf16 v[6:9], v[138:141], v[236:239], v[6:9]
	s_setprio 0
	s_setprio 1
	v_mfma_f32_16x16x32_bf16 v[62:65], v[134:137], v[184:187], v[62:65]
	v_mfma_f32_16x16x32_bf16 v[54:57], v[142:145], v[184:187], v[54:57]
	v_mfma_f32_16x16x32_bf16 v[46:49], v[134:137], v[206:209], v[46:49]
	v_mfma_f32_16x16x32_bf16 v[38:41], v[142:145], v[206:209], v[38:41]
	v_mfma_f32_16x16x32_bf16 v[30:33], v[134:137], v[232:235], v[30:33]
	v_mfma_f32_16x16x32_bf16 v[22:25], v[142:145], v[232:235], v[22:25]
	v_mfma_f32_16x16x32_bf16 v[14:17], v[134:137], v[240:243], v[14:17]
	v_mfma_f32_16x16x32_bf16 v[6:9], v[142:145], v[240:243], v[6:9]
	s_setprio 0
	s_setprio 1
	v_mfma_f32_16x16x32_bf16 v[58:61], v[158:161], v[180:183], v[58:61]
	v_mfma_f32_16x16x32_bf16 v[50:53], v[172:175], v[180:183], v[50:53]
	v_mfma_f32_16x16x32_bf16 v[42:45], v[158:161], v[202:205], v[42:45]
	v_mfma_f32_16x16x32_bf16 v[34:37], v[172:175], v[202:205], v[34:37]
	v_mfma_f32_16x16x32_bf16 v[26:29], v[158:161], v[210:213], v[26:29]
	v_mfma_f32_16x16x32_bf16 v[18:21], v[172:175], v[210:213], v[18:21]
	v_mfma_f32_16x16x32_bf16 v[10:13], v[158:161], v[236:239], v[10:13]
	v_mfma_f32_16x16x32_bf16 v[2:5], v[172:175], v[236:239], v[2:5]
	s_setprio 0
	s_setprio 1
	v_mfma_f32_16x16x32_bf16 v[58:61], v[162:165], v[184:187], v[58:61]
	v_mfma_f32_16x16x32_bf16 v[50:53], v[176:179], v[184:187], v[50:53]
	v_mfma_f32_16x16x32_bf16 v[42:45], v[162:165], v[206:209], v[42:45]
	v_mfma_f32_16x16x32_bf16 v[34:37], v[176:179], v[206:209], v[34:37]
	v_mfma_f32_16x16x32_bf16 v[26:29], v[162:165], v[232:235], v[26:29]
	v_mfma_f32_16x16x32_bf16 v[18:21], v[176:179], v[232:235], v[18:21]
	v_mfma_f32_16x16x32_bf16 v[10:13], v[162:165], v[240:243], v[10:13]
	v_mfma_f32_16x16x32_bf16 v[2:5], v[176:179], v[240:243], v[2:5]
	s_setprio 0
	s_barrier
	s_add_i32 s51, 0, 0x18000
	s_add_i32 s52, 0, 0x1c000
	v_add_u32_e32 v142, s51, v168
	v_add_u32_e32 v176, s52, v168
	ds_read_b128 v[130:133], v142
	ds_read_b128 v[134:137], v142 offset:1024
	ds_read_b128 v[138:141], v142 offset:2048
	ds_read_b128 v[142:145], v142 offset:3072
	ds_read_b128 v[158:161], v176
	ds_read_b128 v[162:165], v176 offset:1024
	ds_read_b128 v[172:175], v176 offset:2048
	ds_read_b128 v[176:179], v176 offset:3072
	s_add_u32 s26, s26, 0x40000
	s_addc_u32 s27, s27, 0
	s_mov_b32 m0, s37
	ds_read_b128 v[180:183], v171 offset:32768
	ds_read_b128 v[184:187], v171 offset:33792
	ds_read_b128 v[202:205], v171 offset:34816
	ds_read_b128 v[206:209], v171 offset:35840
	ds_read_b128 v[210:213], v171 offset:36864
	ds_read_b128 v[232:235], v171 offset:37888
	ds_read_b128 v[236:239], v171 offset:38912
	ds_read_b128 v[240:243], v171 offset:39936
	global_load_lds_dwordx4 v152, s[26:27]
	s_mov_b32 m0, s38
	s_nop 0
	global_load_lds_dwordx4 v148, s[26:27]
	s_waitcnt vmcnt(8)
	s_waitcnt lgkmcnt(0)
	s_barrier
	s_setprio 1
	s_waitcnt lgkmcnt(0)
	v_mfma_f32_16x16x32_bf16 v[126:129], v[130:133], v[180:183], v[126:129]
	v_mfma_f32_16x16x32_bf16 v[118:121], v[138:141], v[180:183], v[118:121]
	v_mfma_f32_16x16x32_bf16 v[110:113], v[130:133], v[202:205], v[110:113]
	v_mfma_f32_16x16x32_bf16 v[102:105], v[138:141], v[202:205], v[102:105]
	v_mfma_f32_16x16x32_bf16 v[94:97], v[130:133], v[210:213], v[94:97]
	v_mfma_f32_16x16x32_bf16 v[86:89], v[138:141], v[210:213], v[86:89]
	v_mfma_f32_16x16x32_bf16 v[78:81], v[130:133], v[236:239], v[78:81]
	v_mfma_f32_16x16x32_bf16 v[70:73], v[138:141], v[236:239], v[70:73]
	s_setprio 0
	s_setprio 1
	v_mfma_f32_16x16x32_bf16 v[126:129], v[134:137], v[184:187], v[126:129]
	v_mfma_f32_16x16x32_bf16 v[118:121], v[142:145], v[184:187], v[118:121]
	v_mfma_f32_16x16x32_bf16 v[110:113], v[134:137], v[206:209], v[110:113]
	v_mfma_f32_16x16x32_bf16 v[102:105], v[142:145], v[206:209], v[102:105]
	v_mfma_f32_16x16x32_bf16 v[94:97], v[134:137], v[232:235], v[94:97]
	v_mfma_f32_16x16x32_bf16 v[86:89], v[142:145], v[232:235], v[86:89]
	v_mfma_f32_16x16x32_bf16 v[78:81], v[134:137], v[240:243], v[78:81]
	v_mfma_f32_16x16x32_bf16 v[70:73], v[142:145], v[240:243], v[70:73]
	s_setprio 0
	s_setprio 1
	v_mfma_f32_16x16x32_bf16 v[122:125], v[158:161], v[180:183], v[122:125]
	v_mfma_f32_16x16x32_bf16 v[114:117], v[172:175], v[180:183], v[114:117]
	v_mfma_f32_16x16x32_bf16 v[106:109], v[158:161], v[202:205], v[106:109]
	v_mfma_f32_16x16x32_bf16 v[98:101], v[172:175], v[202:205], v[98:101]
	v_mfma_f32_16x16x32_bf16 v[90:93], v[158:161], v[210:213], v[90:93]
	v_mfma_f32_16x16x32_bf16 v[82:85], v[172:175], v[210:213], v[82:85]
	v_mfma_f32_16x16x32_bf16 v[74:77], v[158:161], v[236:239], v[74:77]
	v_mfma_f32_16x16x32_bf16 v[66:69], v[172:175], v[236:239], v[66:69]
	s_setprio 0
	s_setprio 1
	v_mfma_f32_16x16x32_bf16 v[122:125], v[162:165], v[184:187], v[122:125]
	v_mfma_f32_16x16x32_bf16 v[114:117], v[176:179], v[184:187], v[114:117]
	v_mfma_f32_16x16x32_bf16 v[106:109], v[162:165], v[206:209], v[106:109]
	v_mfma_f32_16x16x32_bf16 v[98:101], v[176:179], v[206:209], v[98:101]
	v_mfma_f32_16x16x32_bf16 v[90:93], v[162:165], v[232:235], v[90:93]
	v_mfma_f32_16x16x32_bf16 v[82:85], v[176:179], v[232:235], v[82:85]
	v_mfma_f32_16x16x32_bf16 v[74:77], v[162:165], v[240:243], v[74:77]
	v_mfma_f32_16x16x32_bf16 v[66:69], v[176:179], v[240:243], v[66:69]
	s_setprio 0
	s_barrier
; #define PG8_STAGE(bufoff, gbase, voff) do { _Pragma("unroll") for (int _i = 0; _i < 2; ++_i) \
;         __builtin_amdgcn_global_load_lds((const unsigned*)((const char*)(gbase) + (voff)[_i]), (PG8_LAS unsigned*)(lds + (bufoff) + ldsw + _i * 8192), 16, 0, 0); } while (0)
; #define PG8_LDA(dst, b, h) do { _Pragma("unroll") for (int m = 0; m < 4; ++m) _Pragma("unroll") for (int k = 0; k < 2; ++k) dst[m][k] = *(const PG8_LAS bf16x8*)(lds + PG8_SA(b, h) + aoff + m * 2048 + k * 1024); } while (0)
; #define PG8_MMA(ai, bj, At, Bt) do { __builtin_amdgcn_s_setprio(1); _Pragma("unroll") for (int m = 0; m < 4; ++m) _Pragma("unroll") for (int n = 0; n < 2; ++n) _Pragma("unroll") for (int k = 0; k < 2; ++k) \
;         acc[ai][bj][m][n] = __builtin_amdgcn_mfma_f32_16x16x32_bf16(Bt[n][k], At[m][k], acc[ai][bj][m][n], 0, 0, 0); __builtin_amdgcn_s_setprio(0); } while (0)
; #define PG8_WAIT_V(n) asm volatile("s_waitcnt vmcnt(" #n ")" ::: "memory")
; #define PG8_WAIT_L(n) asm volatile("s_waitcnt lgkmcnt(" #n ")" ::: "memory")
; #define PG8_BAR __builtin_amdgcn_s_barrier()
; #define PG8_SCHED __builtin_amdgcn_sched_barrier(0)
; template <class Epi, class Sched, bool ALIGN_EPI = false, bool SP2 = false>
; __device__ __forceinline__ void gemm_phase(PG8_LAS unsigned char* lds, const Gemm g, const Sched& S, const Epi& E) {
;     ...
;             PG8_LDA(At, 1, 1); PG8_STAGE(PG8_SB(1, 0), b3, voffB); PG8_STAGE(PG8_SB(1, 1), b3 + hstepB, voffB); PG8_STAGE(PG8_SA(1, 0), a3, voffA);
;             PG8_WAIT_V(8); PG8_WAIT_L(0); PG8_BAR; PG8_MMA(1, 0, At, B0); PG8_MMA(1, 1, At, B1); PG8_BAR; PG8_SCHED;
	s_add_i32 s26, s51, s30
	s_mov_b32 m0, s26
	ds_read_b128 v[180:183], v171 offset:49152
	ds_read_b128 v[184:187], v171 offset:50176
	ds_read_b128 v[202:205], v171 offset:51200
	ds_read_b128 v[206:209], v171 offset:52224
	ds_read_b128 v[210:213], v171 offset:53248
	ds_read_b128 v[232:235], v171 offset:54272
	ds_read_b128 v[236:239], v171 offset:55296
	ds_read_b128 v[240:243], v171 offset:56320
	global_load_lds_dwordx4 v150, s[60:61]
	s_add_i32 m0, s26, 0x2000
	s_add_u32 s24, s24, 0x40080
	s_addc_u32 s25, s25, 0
	s_add_i32 s26, s52, s30
	global_load_lds_dwordx4 v146, s[60:61]
	s_mov_b32 m0, s26
	s_nop 0
	global_load_lds_dwordx4 v150, s[24:25]
	s_add_i32 m0, s26, 0x2000
	s_nop 0
	global_load_lds_dwordx4 v146, s[24:25]
	s_mov_b32 m0, s39
	s_nop 0
	global_load_lds_dwordx4 v152, s[62:63]
	s_mov_b32 m0, s40
	s_nop 0
	global_load_lds_dwordx4 v148, s[62:63]
	s_waitcnt vmcnt(8)
	s_waitcnt lgkmcnt(0)
	s_barrier
	s_setprio 1
	s_waitcnt lgkmcnt(0)
	v_mfma_f32_16x16x32_bf16 v[62:65], v[130:133], v[180:183], v[62:65]
	v_mfma_f32_16x16x32_bf16 v[54:57], v[138:141], v[180:183], v[54:57]
	v_mfma_f32_16x16x32_bf16 v[46:49], v[130:133], v[202:205], v[46:49]
	v_mfma_f32_16x16x32_bf16 v[38:41], v[138:141], v[202:205], v[38:41]
	v_mfma_f32_16x16x32_bf16 v[30:33], v[130:133], v[210:213], v[30:33]
	v_mfma_f32_16x16x32_bf16 v[22:25], v[138:141], v[210:213], v[22:25]
	v_mfma_f32_16x16x32_bf16 v[14:17], v[130:133], v[236:239], v[14:17]
	v_mfma_f32_16x16x32_bf16 v[6:9], v[138:141], v[236:239], v[6:9]
	s_setprio 0
	s_setprio 1
	v_mfma_f32_16x16x32_bf16 v[62:65], v[134:137], v[184:187], v[62:65]
	v_mfma_f32_16x16x32_bf16 v[54:57], v[142:145], v[184:187], v[54:57]
	v_mfma_f32_16x16x32_bf16 v[46:49], v[134:137], v[206:209], v[46:49]
	v_mfma_f32_16x16x32_bf16 v[38:41], v[142:145], v[206:209], v[38:41]
	v_mfma_f32_16x16x32_bf16 v[30:33], v[134:137], v[232:235], v[30:33]
	v_mfma_f32_16x16x32_bf16 v[22:25], v[142:145], v[232:235], v[22:25]
	v_mfma_f32_16x16x32_bf16 v[14:17], v[134:137], v[240:243], v[14:17]
	v_mfma_f32_16x16x32_bf16 v[6:9], v[142:145], v[240:243], v[6:9]
	s_setprio 0
	s_setprio 1
	v_mfma_f32_16x16x32_bf16 v[58:61], v[158:161], v[180:183], v[58:61]
	v_mfma_f32_16x16x32_bf16 v[50:53], v[172:175], v[180:183], v[50:53]
	v_mfma_f32_16x16x32_bf16 v[42:45], v[158:161], v[202:205], v[42:45]
	v_mfma_f32_16x16x32_bf16 v[34:37], v[172:175], v[202:205], v[34:37]
	v_mfma_f32_16x16x32_bf16 v[26:29], v[158:161], v[210:213], v[26:29]
	v_mfma_f32_16x16x32_bf16 v[18:21], v[172:175], v[210:213], v[18:21]
	v_mfma_f32_16x16x32_bf16 v[10:13], v[158:161], v[236:239], v[10:13]
	v_mfma_f32_16x16x32_bf16 v[2:5], v[172:175], v[236:239], v[2:5]
	s_setprio 0
	s_setprio 1
	v_mfma_f32_16x16x32_bf16 v[58:61], v[162:165], v[184:187], v[58:61]
	v_mfma_f32_16x16x32_bf16 v[50:53], v[176:179], v[184:187], v[50:53]
	v_mfma_f32_16x16x32_bf16 v[42:45], v[162:165], v[206:209], v[42:45]
	v_mfma_f32_16x16x32_bf16 v[34:37], v[176:179], v[206:209], v[34:37]
	v_mfma_f32_16x16x32_bf16 v[26:29], v[162:165], v[232:235], v[26:29]
	v_mfma_f32_16x16x32_bf16 v[18:21], v[176:179], v[232:235], v[18:21]
	v_mfma_f32_16x16x32_bf16 v[10:13], v[162:165], v[240:243], v[10:13]
	v_mfma_f32_16x16x32_bf16 v[2:5], v[176:179], v[240:243], v[2:5]
	s_setprio 0
	s_barrier
	s_add_i32 s50, s50, 2
	s_add_u32 s22, s22, 0x100
	s_addc_u32 s23, s23, 0
	s_add_u32 s48, s48, 0x100
	s_addc_u32 s49, s49, 0
	s_cmp_gt_u32 s50, 13
	s_cbranch_scc0 .LBB0_1190
	s_and_b64 vcc, exec, s[18:19]
	s_cbranch_vccz .LBB0_1193
	s_barrier

; #define PG8_STAGE(bufoff, gbase, voff) do { _Pragma("unroll") for (int _i = 0; _i < 2; ++_i) \
;         __builtin_amdgcn_global_load_lds((const unsigned*)((const char*)(gbase) + (voff)[_i]), (PG8_LAS unsigned*)(lds + (bufoff) + ldsw + _i * 8192), 16, 0, 0); } while (0)
; #define PG8_LDA(dst, b, h) do { _Pragma("unroll") for (int m = 0; m < 4; ++m) _Pragma("unroll") for (int k = 0; k < 2; ++k) dst[m][k] = *(const PG8_LAS bf16x8*)(lds + PG8_SA(b, h) + aoff + m * 2048 + k * 1024); } while (0)
; #define PG8_LDB(dst, b, h) do { _Pragma("unroll") for (int n = 0; n < 2; ++n) _Pragma("unroll") for (int k = 0; k < 2; ++k) dst[n][k] = *(const PG8_LAS bf16x8*)(lds + PG8_SB(b, h) + boff + n * 2048 + k * 1024); } while (0)
; #define PG8_MMA(ai, bj, At, Bt) do { __builtin_amdgcn_s_setprio(1); _Pragma("unroll") for (int m = 0; m < 4; ++m) _Pragma("unroll") for (int n = 0; n < 2; ++n) _Pragma("unroll") for (int k = 0; k < 2; ++k) \
;         acc[ai][bj][m][n] = __builtin_amdgcn_mfma_f32_16x16x32_bf16(Bt[n][k], At[m][k], acc[ai][bj][m][n], 0, 0, 0); __builtin_amdgcn_s_setprio(0); } while (0)
; #define PG8_WAIT_V(n) asm volatile("s_waitcnt vmcnt(" #n ")" ::: "memory")
; #define PG8_BAR __builtin_amdgcn_s_barrier()
; template <class Epi, class Sched, bool ALIGN_EPI = false, bool SP2 = false>
; __device__ __forceinline__ void gemm_phase(PG8_LAS unsigned char* lds, const Gemm g, const Sched& S, const Epi& E) {
;     ...
;         for (int t = 0; t < nt; t += 2) {
;             const bool last = (t == nt - 2);
;             const char* a1 = cA + (size_t)(t + 1) * kstep;
;             const char* a2 = last ? nA : cA + (size_t)(t + 2) * kstep; const char* b2 = last ? nB : cB + (size_t)(t + 2) * kstep;
;             const char* a3 = a2 + kstep; const char* b3 = b2 + kstep;
;             if (last && has_next) S.a_ready(nxt);
;             if constexpr (SP2) {
;             PG8_LDB(B0, 0, 0); PG8_LDB(B1, 0, 1); PG8_SCHED; PG8_LDA(At, 0, 0); PG8_STAGE(PG8_SA(1, 1), a1 + hstepA, voffA);
;             PG8_WAIT_V(8); PG8_WAIT_L(0); PG8_BAR; PG8_MMA(0, 0, At, B0); PG8_MMA(0, 1, At, B1); PG8_BAR; PG8_SCHED;
;             PG8_LDA(At, 0, 1); PG8_STAGE(PG8_SB(0, 0), b2, voffB); PG8_STAGE(PG8_SB(0, 1), b2 + hstepB, voffB); PG8_STAGE(PG8_SA(0, 0), a2, voffA);
;             PG8_WAIT_V(8); PG8_WAIT_L(0); PG8_BAR; PG8_MMA(1, 0, At, B0); PG8_MMA(1, 1, At, B1); PG8_BAR; PG8_SCHED;
.LBB0_1270:
	s_add_u32 s28, s26, 0xfffc0080
	s_addc_u32 s29, s27, -1
	s_add_i32 s52, 0, 0x10000
	s_cmp_eq_u32 s51, 12
	s_cselect_b32 s31, s17, s29
	s_cselect_b32 s30, s23, s28
	s_cselect_b32 s29, s15, s50
	s_cselect_b32 s28, s25, s49
	s_add_i32 s54, 0, 0x14000
	v_add_u32_e32 v142, s52, v186
	v_add_u32_e32 v172, s54, v186
	ds_read_b128 v[130:133], v142
	ds_read_b128 v[134:137], v142 offset:1024
	ds_read_b128 v[138:141], v142 offset:2048
	ds_read_b128 v[142:145], v142 offset:3072
	ds_read_b128 v[146:149], v172
	ds_read_b128 v[150:153], v172 offset:1024
	ds_read_b128 v[168:171], v172 offset:2048
	ds_read_b128 v[172:175], v172 offset:3072
	s_add_i32 m0, s39, 0xc000
	ds_read_b128 v[176:179], v200
	ds_read_b128 v[180:183], v200 offset:1024
	ds_read_b128 v[202:205], v200 offset:2048
	ds_read_b128 v[206:209], v200 offset:3072
	ds_read_b128 v[210:213], v200 offset:4096
	ds_read_b128 v[232:235], v200 offset:5120
	ds_read_b128 v[236:239], v200 offset:6144
	ds_read_b128 v[240:243], v200 offset:7168
	global_load_lds_dwordx4 v164, s[26:27]
	s_add_i32 m0, s39, 0xe000
	s_nop 0
	global_load_lds_dwordx4 v166, s[26:27]
	s_waitcnt vmcnt(8)
	s_waitcnt lgkmcnt(0)
	s_barrier
	s_setprio 1
	s_waitcnt lgkmcnt(0)
	v_mfma_f32_16x16x32_bf16 v[126:129], v[130:133], v[176:179], v[126:129]
	v_mfma_f32_16x16x32_bf16 v[122:125], v[138:141], v[176:179], v[122:125]
	v_mfma_f32_16x16x32_bf16 v[110:113], v[130:133], v[202:205], v[110:113]
	v_mfma_f32_16x16x32_bf16 v[106:109], v[138:141], v[202:205], v[106:109]
	v_mfma_f32_16x16x32_bf16 v[94:97], v[130:133], v[210:213], v[94:97]
	v_mfma_f32_16x16x32_bf16 v[90:93], v[138:141], v[210:213], v[90:93]
	v_mfma_f32_16x16x32_bf16 v[78:81], v[130:133], v[236:239], v[78:81]
	v_mfma_f32_16x16x32_bf16 v[74:77], v[138:141], v[236:239], v[74:77]
	s_setprio 0
	s_setprio 1
	v_mfma_f32_16x16x32_bf16 v[126:129], v[134:137], v[180:183], v[126:129]
	v_mfma_f32_16x16x32_bf16 v[122:125], v[142:145], v[180:183], v[122:125]
	v_mfma_f32_16x16x32_bf16 v[110:113], v[134:137], v[206:209], v[110:113]
	v_mfma_f32_16x16x32_bf16 v[106:109], v[142:145], v[206:209], v[106:109]
	v_mfma_f32_16x16x32_bf16 v[94:97], v[134:137], v[232:235], v[94:97]
	v_mfma_f32_16x16x32_bf16 v[90:93], v[142:145], v[232:235], v[90:93]
	v_mfma_f32_16x16x32_bf16 v[78:81], v[134:137], v[240:243], v[78:81]
	v_mfma_f32_16x16x32_bf16 v[74:77], v[142:145], v[240:243], v[74:77]
	s_setprio 0
	s_setprio 1
	v_mfma_f32_16x16x32_bf16 v[118:121], v[146:149], v[176:179], v[118:121]
	v_mfma_f32_16x16x32_bf16 v[114:117], v[168:171], v[176:179], v[114:117]
	v_mfma_f32_16x16x32_bf16 v[102:105], v[146:149], v[202:205], v[102:105]
	v_mfma_f32_16x16x32_bf16 v[98:101], v[168:171], v[202:205], v[98:101]
	v_mfma_f32_16x16x32_bf16 v[86:89], v[146:149], v[210:213], v[86:89]
	v_mfma_f32_16x16x32_bf16 v[82:85], v[168:171], v[210:213], v[82:85]
	v_mfma_f32_16x16x32_bf16 v[70:73], v[146:149], v[236:239], v[70:73]
	v_mfma_f32_16x16x32_bf16 v[66:69], v[168:171], v[236:239], v[66:69]
	s_setprio 0
	s_setprio 1
	v_mfma_f32_16x16x32_bf16 v[118:121], v[150:153], v[180:183], v[118:121]
	v_mfma_f32_16x16x32_bf16 v[114:117], v[172:175], v[180:183], v[114:117]
	v_mfma_f32_16x16x32_bf16 v[102:105], v[150:153], v[206:209], v[102:105]
	v_mfma_f32_16x16x32_bf16 v[98:101], v[172:175], v[206:209], v[98:101]
	v_mfma_f32_16x16x32_bf16 v[86:89], v[150:153], v[232:235], v[86:89]
	v_mfma_f32_16x16x32_bf16 v[82:85], v[172:175], v[232:235], v[82:85]
	v_mfma_f32_16x16x32_bf16 v[70:73], v[150:153], v[240:243], v[70:73]
	v_mfma_f32_16x16x32_bf16 v[66:69], v[172:175], v[240:243], v[66:69]
	s_setprio 0
	s_barrier
	s_add_i32 s52, s52, s38
	s_mov_b32 m0, s52
	ds_read_b128 v[176:179], v200 offset:16384
	ds_read_b128 v[180:183], v200 offset:17408
	ds_read_b128 v[202:205], v200 offset:18432
	ds_read_b128 v[206:209], v200 offset:19456
	ds_read_b128 v[210:213], v200 offset:20480
	ds_read_b128 v[232:235], v200 offset:21504
	ds_read_b128 v[236:239], v200 offset:22528
	ds_read_b128 v[240:243], v200 offset:23552
	s_add_u32 s60, s28, 0x80
	s_addc_u32 s61, s29, 0
	s_add_u32 s62, s30, 0x80
	s_addc_u32 s63, s31, 0
	global_load_lds_dwordx4 v156, s[28:29]
	s_add_i32 m0, s52, 0x2000
	s_add_u32 s52, s28, 0x40000
	s_addc_u32 s53, s29, 0
	s_add_i32 s54, s54, s38
	global_load_lds_dwordx4 v160, s[28:29]
	s_mov_b32 m0, s54
	s_nop 0
	global_load_lds_dwordx4 v156, s[52:53]
	s_add_i32 m0, s54, 0x2000
	s_nop 0
	global_load_lds_dwordx4 v160, s[52:53]
	s_mov_b32 m0, s39
	s_nop 0
	global_load_lds_dwordx4 v154, s[30:31]
	s_mov_b32 m0, s40
	s_nop 0
	global_load_lds_dwordx4 v158, s[30:31]
	s_waitcnt vmcnt(8)
	s_waitcnt lgkmcnt(0)
	s_barrier
; #define PG8_STAGE(bufoff, gbase, voff) do { _Pragma("unroll") for (int _i = 0; _i < 2; ++_i) \
;         __builtin_amdgcn_global_load_lds((const unsigned*)((const char*)(gbase) + (voff)[_i]), (PG8_LAS unsigned*)(lds + (bufoff) + ldsw + _i * 8192), 16, 0, 0); } while (0)
; #define PG8_LDA(dst, b, h) do { _Pragma("unroll") for (int m = 0; m < 4; ++m) _Pragma("unroll") for (int k = 0; k < 2; ++k) dst[m][k] = *(const PG8_LAS bf16x8*)(lds + PG8_SA(b, h) + aoff + m * 2048 + k * 1024); } while (0)
; #define PG8_LDB(dst, b, h) do { _Pragma("unroll") for (int n = 0; n < 2; ++n) _Pragma("unroll") for (int k = 0; k < 2; ++k) dst[n][k] = *(const PG8_LAS bf16x8*)(lds + PG8_SB(b, h) + boff + n * 2048 + k * 1024); } while (0)
; #define PG8_MMA(ai, bj, At, Bt) do { __builtin_amdgcn_s_setprio(1); _Pragma("unroll") for (int m = 0; m < 4; ++m) _Pragma("unroll") for (int n = 0; n < 2; ++n) _Pragma("unroll") for (int k = 0; k < 2; ++k) \
;         acc[ai][bj][m][n] = __builtin_amdgcn_mfma_f32_16x16x32_bf16(Bt[n][k], At[m][k], acc[ai][bj][m][n], 0, 0, 0); __builtin_amdgcn_s_setprio(0); } while (0)
; #define PG8_WAIT_V(n) asm volatile("s_waitcnt vmcnt(" #n ")" ::: "memory")
; #define PG8_WAIT_L(n) asm volatile("s_waitcnt lgkmcnt(" #n ")" ::: "memory")
; #define PG8_BAR __builtin_amdgcn_s_barrier()
; #define PG8_SCHED __builtin_amdgcn_sched_barrier(0)
; template <class Epi, class Sched, bool ALIGN_EPI = false, bool SP2 = false>
; __device__ __forceinline__ void gemm_phase(PG8_LAS unsigned char* lds, const Gemm g, const Sched& S, const Epi& E) {
;     ...
;             PG8_WAIT_V(8); PG8_WAIT_L(0); PG8_BAR; PG8_MMA(1, 0, At, B0); PG8_MMA(1, 1, At, B1); PG8_BAR; PG8_SCHED;
;             PG8_LDB(B0, 1, 0); PG8_LDB(B1, 1, 1); PG8_SCHED; PG8_LDA(At, 1, 0); PG8_STAGE(PG8_SA(0, 1), a2 + hstepA, voffA);
;             PG8_WAIT_V(8); PG8_WAIT_L(0); PG8_BAR; PG8_MMA(0, 0, At, B0); PG8_MMA(0, 1, At, B1); PG8_BAR; PG8_SCHED;
	s_setprio 1
	s_waitcnt lgkmcnt(0)
	v_mfma_f32_16x16x32_bf16 v[62:65], v[130:133], v[176:179], v[62:65]
	v_mfma_f32_16x16x32_bf16 v[58:61], v[138:141], v[176:179], v[58:61]
	v_mfma_f32_16x16x32_bf16 v[46:49], v[130:133], v[202:205], v[46:49]
	v_mfma_f32_16x16x32_bf16 v[42:45], v[138:141], v[202:205], v[42:45]
	v_mfma_f32_16x16x32_bf16 v[30:33], v[130:133], v[210:213], v[30:33]
	v_mfma_f32_16x16x32_bf16 v[26:29], v[138:141], v[210:213], v[26:29]
	v_mfma_f32_16x16x32_bf16 v[14:17], v[130:133], v[236:239], v[14:17]
	v_mfma_f32_16x16x32_bf16 v[10:13], v[138:141], v[236:239], v[10:13]
	s_setprio 0
	s_setprio 1
	v_mfma_f32_16x16x32_bf16 v[62:65], v[134:137], v[180:183], v[62:65]
	v_mfma_f32_16x16x32_bf16 v[58:61], v[142:145], v[180:183], v[58:61]
	v_mfma_f32_16x16x32_bf16 v[46:49], v[134:137], v[206:209], v[46:49]
	v_mfma_f32_16x16x32_bf16 v[42:45], v[142:145], v[206:209], v[42:45]
	v_mfma_f32_16x16x32_bf16 v[30:33], v[134:137], v[232:235], v[30:33]
	v_mfma_f32_16x16x32_bf16 v[26:29], v[142:145], v[232:235], v[26:29]
	v_mfma_f32_16x16x32_bf16 v[14:17], v[134:137], v[240:243], v[14:17]
	v_mfma_f32_16x16x32_bf16 v[10:13], v[142:145], v[240:243], v[10:13]
	s_setprio 0
	s_setprio 1
	v_mfma_f32_16x16x32_bf16 v[54:57], v[146:149], v[176:179], v[54:57]
	v_mfma_f32_16x16x32_bf16 v[50:53], v[168:171], v[176:179], v[50:53]
	v_mfma_f32_16x16x32_bf16 v[38:41], v[146:149], v[202:205], v[38:41]
	v_mfma_f32_16x16x32_bf16 v[34:37], v[168:171], v[202:205], v[34:37]
	v_mfma_f32_16x16x32_bf16 v[22:25], v[146:149], v[210:213], v[22:25]
	v_mfma_f32_16x16x32_bf16 v[18:21], v[168:171], v[210:213], v[18:21]
	v_mfma_f32_16x16x32_bf16 v[6:9], v[146:149], v[236:239], v[6:9]
	v_mfma_f32_16x16x32_bf16 v[2:5], v[168:171], v[236:239], v[2:5]
	s_setprio 0
	s_setprio 1
	v_mfma_f32_16x16x32_bf16 v[54:57], v[150:153], v[180:183], v[54:57]
	v_mfma_f32_16x16x32_bf16 v[50:53], v[172:175], v[180:183], v[50:53]
	v_mfma_f32_16x16x32_bf16 v[38:41], v[150:153], v[206:209], v[38:41]
	v_mfma_f32_16x16x32_bf16 v[34:37], v[172:175], v[206:209], v[34:37]
	v_mfma_f32_16x16x32_bf16 v[22:25], v[150:153], v[232:235], v[22:25]
	v_mfma_f32_16x16x32_bf16 v[18:21], v[172:175], v[232:235], v[18:21]
	v_mfma_f32_16x16x32_bf16 v[6:9], v[150:153], v[240:243], v[6:9]
	v_mfma_f32_16x16x32_bf16 v[2:5], v[172:175], v[240:243], v[2:5]
	s_setprio 0
	s_barrier
	s_add_i32 s52, 0, 0x18000
	s_add_i32 s53, 0, 0x1c000
	v_add_u32_e32 v142, s52, v186
	v_add_u32_e32 v172, s53, v186
	ds_read_b128 v[130:133], v142
	ds_read_b128 v[134:137], v142 offset:1024
	ds_read_b128 v[138:141], v142 offset:2048
	ds_read_b128 v[142:145], v142 offset:3072
	ds_read_b128 v[146:149], v172
	ds_read_b128 v[150:153], v172 offset:1024
	ds_read_b128 v[168:171], v172 offset:2048
	ds_read_b128 v[172:175], v172 offset:3072
	s_add_u32 s30, s30, 0x40000
	s_addc_u32 s31, s31, 0
	s_mov_b32 m0, s41
	ds_read_b128 v[176:179], v200 offset:32768
	ds_read_b128 v[180:183], v200 offset:33792
	ds_read_b128 v[202:205], v200 offset:34816
	ds_read_b128 v[206:209], v200 offset:35840
	ds_read_b128 v[210:213], v200 offset:36864
	ds_read_b128 v[232:235], v200 offset:37888
	ds_read_b128 v[236:239], v200 offset:38912
	ds_read_b128 v[240:243], v200 offset:39936
	global_load_lds_dwordx4 v154, s[30:31]
	s_mov_b32 m0, s42
	s_nop 0
	global_load_lds_dwordx4 v158, s[30:31]
	s_waitcnt vmcnt(8)
	s_waitcnt lgkmcnt(0)
	s_barrier
	s_setprio 1
	s_waitcnt lgkmcnt(0)
	v_mfma_f32_16x16x32_bf16 v[126:129], v[130:133], v[176:179], v[126:129]
	v_mfma_f32_16x16x32_bf16 v[122:125], v[138:141], v[176:179], v[122:125]
	v_mfma_f32_16x16x32_bf16 v[110:113], v[130:133], v[202:205], v[110:113]
	v_mfma_f32_16x16x32_bf16 v[106:109], v[138:141], v[202:205], v[106:109]
	v_mfma_f32_16x16x32_bf16 v[94:97], v[130:133], v[210:213], v[94:97]
	v_mfma_f32_16x16x32_bf16 v[90:93], v[138:141], v[210:213], v[90:93]
	v_mfma_f32_16x16x32_bf16 v[78:81], v[130:133], v[236:239], v[78:81]
	v_mfma_f32_16x16x32_bf16 v[74:77], v[138:141], v[236:239], v[74:77]
	s_setprio 0
	s_setprio 1
	v_mfma_f32_16x16x32_bf16 v[126:129], v[134:137], v[180:183], v[126:129]
	v_mfma_f32_16x16x32_bf16 v[122:125], v[142:145], v[180:183], v[122:125]
	v_mfma_f32_16x16x32_bf16 v[110:113], v[134:137], v[206:209], v[110:113]
	v_mfma_f32_16x16x32_bf16 v[106:109], v[142:145], v[206:209], v[106:109]
	v_mfma_f32_16x16x32_bf16 v[94:97], v[134:137], v[232:235], v[94:97]
	v_mfma_f32_16x16x32_bf16 v[90:93], v[142:145], v[232:235], v[90:93]
	v_mfma_f32_16x16x32_bf16 v[78:81], v[134:137], v[240:243], v[78:81]
	v_mfma_f32_16x16x32_bf16 v[74:77], v[142:145], v[240:243], v[74:77]
	s_setprio 0
	s_setprio 1
	v_mfma_f32_16x16x32_bf16 v[118:121], v[146:149], v[176:179], v[118:121]
	v_mfma_f32_16x16x32_bf16 v[114:117], v[168:171], v[176:179], v[114:117]
	v_mfma_f32_16x16x32_bf16 v[102:105], v[146:149], v[202:205], v[102:105]
	v_mfma_f32_16x16x32_bf16 v[98:101], v[168:171], v[202:205], v[98:101]
	v_mfma_f32_16x16x32_bf16 v[86:89], v[146:149], v[210:213], v[86:89]
	v_mfma_f32_16x16x32_bf16 v[82:85], v[168:171], v[210:213], v[82:85]
	v_mfma_f32_16x16x32_bf16 v[70:73], v[146:149], v[236:239], v[70:73]
	v_mfma_f32_16x16x32_bf16 v[66:69], v[168:171], v[236:239], v[66:69]
	s_setprio 0
	s_setprio 1
	v_mfma_f32_16x16x32_bf16 v[118:121], v[150:153], v[180:183], v[118:121]
	v_mfma_f32_16x16x32_bf16 v[114:117], v[172:175], v[180:183], v[114:117]
	v_mfma_f32_16x16x32_bf16 v[102:105], v[150:153], v[206:209], v[102:105]
	v_mfma_f32_16x16x32_bf16 v[98:101], v[172:175], v[206:209], v[98:101]
	v_mfma_f32_16x16x32_bf16 v[86:89], v[150:153], v[232:235], v[86:89]
	v_mfma_f32_16x16x32_bf16 v[82:85], v[172:175], v[232:235], v[82:85]
	v_mfma_f32_16x16x32_bf16 v[70:73], v[150:153], v[240:243], v[70:73]
	v_mfma_f32_16x16x32_bf16 v[66:69], v[172:175], v[240:243], v[66:69]
	s_setprio 0
	s_barrier
; #define PG8_STAGE(bufoff, gbase, voff) do { _Pragma("unroll") for (int _i = 0; _i < 2; ++_i) \
;         __builtin_amdgcn_global_load_lds((const unsigned*)((const char*)(gbase) + (voff)[_i]), (PG8_LAS unsigned*)(lds + (bufoff) + ldsw + _i * 8192), 16, 0, 0); } while (0)
; #define PG8_LDA(dst, b, h) do { _Pragma("unroll") for (int m = 0; m < 4; ++m) _Pragma("unroll") for (int k = 0; k < 2; ++k) dst[m][k] = *(const PG8_LAS bf16x8*)(lds + PG8_SA(b, h) + aoff + m * 2048 + k * 1024); } while (0)
; #define PG8_MMA(ai, bj, At, Bt) do { __builtin_amdgcn_s_setprio(1); _Pragma("unroll") for (int m = 0; m < 4; ++m) _Pragma("unroll") for (int n = 0; n < 2; ++n) _Pragma("unroll") for (int k = 0; k < 2; ++k) \
;         acc[ai][bj][m][n] = __builtin_amdgcn_mfma_f32_16x16x32_bf16(Bt[n][k], At[m][k], acc[ai][bj][m][n], 0, 0, 0); __builtin_amdgcn_s_setprio(0); } while (0)
; #define PG8_WAIT_V(n) asm volatile("s_waitcnt vmcnt(" #n ")" ::: "memory")
; #define PG8_WAIT_L(n) asm volatile("s_waitcnt lgkmcnt(" #n ")" ::: "memory")
; #define PG8_BAR __builtin_amdgcn_s_barrier()
; #define PG8_SCHED __builtin_amdgcn_sched_barrier(0)
; template <class Epi, class Sched, bool ALIGN_EPI = false, bool SP2 = false>
; __device__ __forceinline__ void gemm_phase(PG8_LAS unsigned char* lds, const Gemm g, const Sched& S, const Epi& E) {
;     ...
;             PG8_LDA(At, 1, 1); PG8_STAGE(PG8_SB(1, 0), b3, voffB); PG8_STAGE(PG8_SB(1, 1), b3 + hstepB, voffB); PG8_STAGE(PG8_SA(1, 0), a3, voffA);
;             PG8_WAIT_V(8); PG8_WAIT_L(0); PG8_BAR; PG8_MMA(1, 0, At, B0); PG8_MMA(1, 1, At, B1); PG8_BAR; PG8_SCHED;
	s_add_i32 s30, s52, s38
	s_mov_b32 m0, s30
	ds_read_b128 v[176:179], v200 offset:49152
	ds_read_b128 v[180:183], v200 offset:50176
	ds_read_b128 v[202:205], v200 offset:51200
	ds_read_b128 v[206:209], v200 offset:52224
	ds_read_b128 v[210:213], v200 offset:53248
	ds_read_b128 v[232:235], v200 offset:54272
	ds_read_b128 v[236:239], v200 offset:55296
	ds_read_b128 v[240:243], v200 offset:56320
	global_load_lds_dwordx4 v156, s[60:61]
	s_add_i32 m0, s30, 0x2000
	s_add_u32 s28, s28, 0x40080
	s_addc_u32 s29, s29, 0
	s_add_i32 s30, s53, s38
	global_load_lds_dwordx4 v160, s[60:61]
	s_mov_b32 m0, s30
	s_nop 0
	global_load_lds_dwordx4 v156, s[28:29]
	s_add_i32 m0, s30, 0x2000
	s_nop 0
	global_load_lds_dwordx4 v160, s[28:29]
	s_mov_b32 m0, s44
	s_nop 0
	global_load_lds_dwordx4 v154, s[62:63]
	s_mov_b32 m0, s45
	s_nop 0
	global_load_lds_dwordx4 v158, s[62:63]
	s_waitcnt vmcnt(8)
	s_waitcnt lgkmcnt(0)
	s_barrier
	s_setprio 1
	s_waitcnt lgkmcnt(0)
	v_mfma_f32_16x16x32_bf16 v[62:65], v[130:133], v[176:179], v[62:65]
	v_mfma_f32_16x16x32_bf16 v[58:61], v[138:141], v[176:179], v[58:61]
	v_mfma_f32_16x16x32_bf16 v[46:49], v[130:133], v[202:205], v[46:49]
	v_mfma_f32_16x16x32_bf16 v[42:45], v[138:141], v[202:205], v[42:45]
	v_mfma_f32_16x16x32_bf16 v[30:33], v[130:133], v[210:213], v[30:33]
	v_mfma_f32_16x16x32_bf16 v[26:29], v[138:141], v[210:213], v[26:29]
	v_mfma_f32_16x16x32_bf16 v[14:17], v[130:133], v[236:239], v[14:17]
	v_mfma_f32_16x16x32_bf16 v[10:13], v[138:141], v[236:239], v[10:13]
	s_setprio 0
	s_setprio 1
	v_mfma_f32_16x16x32_bf16 v[62:65], v[134:137], v[180:183], v[62:65]
	v_mfma_f32_16x16x32_bf16 v[58:61], v[142:145], v[180:183], v[58:61]
	v_mfma_f32_16x16x32_bf16 v[46:49], v[134:137], v[206:209], v[46:49]
	v_mfma_f32_16x16x32_bf16 v[42:45], v[142:145], v[206:209], v[42:45]
	v_mfma_f32_16x16x32_bf16 v[30:33], v[134:137], v[232:235], v[30:33]
	v_mfma_f32_16x16x32_bf16 v[26:29], v[142:145], v[232:235], v[26:29]
	v_mfma_f32_16x16x32_bf16 v[14:17], v[134:137], v[240:243], v[14:17]
	v_mfma_f32_16x16x32_bf16 v[10:13], v[142:145], v[240:243], v[10:13]
	s_setprio 0
	s_setprio 1
	v_mfma_f32_16x16x32_bf16 v[54:57], v[146:149], v[176:179], v[54:57]
	v_mfma_f32_16x16x32_bf16 v[50:53], v[168:171], v[176:179], v[50:53]
	v_mfma_f32_16x16x32_bf16 v[38:41], v[146:149], v[202:205], v[38:41]
	v_mfma_f32_16x16x32_bf16 v[34:37], v[168:171], v[202:205], v[34:37]
	v_mfma_f32_16x16x32_bf16 v[22:25], v[146:149], v[210:213], v[22:25]
	v_mfma_f32_16x16x32_bf16 v[18:21], v[168:171], v[210:213], v[18:21]
	v_mfma_f32_16x16x32_bf16 v[6:9], v[146:149], v[236:239], v[6:9]
	v_mfma_f32_16x16x32_bf16 v[2:5], v[168:171], v[236:239], v[2:5]
	s_setprio 0
	s_setprio 1
	v_mfma_f32_16x16x32_bf16 v[54:57], v[150:153], v[180:183], v[54:57]
	v_mfma_f32_16x16x32_bf16 v[50:53], v[172:175], v[180:183], v[50:53]
	v_mfma_f32_16x16x32_bf16 v[38:41], v[150:153], v[206:209], v[38:41]
	v_mfma_f32_16x16x32_bf16 v[34:37], v[172:175], v[206:209], v[34:37]
	v_mfma_f32_16x16x32_bf16 v[22:25], v[150:153], v[232:235], v[22:25]
	v_mfma_f32_16x16x32_bf16 v[18:21], v[172:175], v[232:235], v[18:21]
	v_mfma_f32_16x16x32_bf16 v[6:9], v[150:153], v[240:243], v[6:9]
	v_mfma_f32_16x16x32_bf16 v[2:5], v[172:175], v[240:243], v[2:5]
	s_setprio 0
	s_barrier
	s_add_i32 s51, s51, 2
	s_add_u32 s26, s26, 0x100
	s_addc_u32 s27, s27, 0
	s_add_u32 s49, s49, 0x100
	s_addc_u32 s50, s50, 0
	s_cmp_gt_u32 s51, 13
	s_cbranch_scc0 .LBB0_1270
	s_and_b64 vcc, exec, s[12:13]
	s_cbranch_vccz .LBB0_1273
	s_barrier

; #define PG8_STAGE(bufoff, gbase, voff) do { _Pragma("unroll") for (int _i = 0; _i < 2; ++_i) \
;         __builtin_amdgcn_global_load_lds((const unsigned*)((const char*)(gbase) + (voff)[_i]), (PG8_LAS unsigned*)(lds + (bufoff) + ldsw + _i * 8192), 16, 0, 0); } while (0)
; #define PG8_LDA(dst, b, h) do { _Pragma("unroll") for (int m = 0; m < 4; ++m) _Pragma("unroll") for (int k = 0; k < 2; ++k) dst[m][k] = *(const PG8_LAS bf16x8*)(lds + PG8_SA(b, h) + aoff + m * 2048 + k * 1024); } while (0)
; #define PG8_LDB(dst, b, h) do { _Pragma("unroll") for (int n = 0; n < 2; ++n) _Pragma("unroll") for (int k = 0; k < 2; ++k) dst[n][k] = *(const PG8_LAS bf16x8*)(lds + PG8_SB(b, h) + boff + n * 2048 + k * 1024); } while (0)
; #define PG8_MMA(ai, bj, At, Bt) do { __builtin_amdgcn_s_setprio(1); _Pragma("unroll") for (int m = 0; m < 4; ++m) _Pragma("unroll") for (int n = 0; n < 2; ++n) _Pragma("unroll") for (int k = 0; k < 2; ++k) \
;         acc[ai][bj][m][n] = __builtin_amdgcn_mfma_f32_16x16x32_bf16(Bt[n][k], At[m][k], acc[ai][bj][m][n], 0, 0, 0); __builtin_amdgcn_s_setprio(0); } while (0)
; #define PG8_WAIT_V(n) asm volatile("s_waitcnt vmcnt(" #n ")" ::: "memory")
; #define PG8_BAR __builtin_amdgcn_s_barrier()
; template <class Epi, class Sched, bool ALIGN_EPI = false, bool SP2 = false>
; __device__ __forceinline__ void gemm_phase(PG8_LAS unsigned char* lds, const Gemm g, const Sched& S, const Epi& E) {
;     ...
;         for (int t = 0; t < nt; t += 2) {
;             const bool last = (t == nt - 2);
;             const char* a1 = cA + (size_t)(t + 1) * kstep;
;             const char* a2 = last ? nA : cA + (size_t)(t + 2) * kstep; const char* b2 = last ? nB : cB + (size_t)(t + 2) * kstep;
;             const char* a3 = a2 + kstep; const char* b3 = b2 + kstep;
;             if (last && has_next) S.a_ready(nxt);
;             if constexpr (SP2) {
;             PG8_LDB(B0, 0, 0); PG8_LDB(B1, 0, 1); PG8_SCHED; PG8_LDA(At, 0, 0); PG8_STAGE(PG8_SA(1, 1), a1 + hstepA, voffA);
;             PG8_WAIT_V(8); PG8_WAIT_L(0); PG8_BAR; PG8_MMA(0, 0, At, B0); PG8_MMA(0, 1, At, B1); PG8_BAR; PG8_SCHED;
;             PG8_LDA(At, 0, 1); PG8_STAGE(PG8_SB(0, 0), b2, voffB); PG8_STAGE(PG8_SB(0, 1), b2 + hstepB, voffB); PG8_STAGE(PG8_SA(0, 0), a2, voffA);
;             PG8_WAIT_V(8); PG8_WAIT_L(0); PG8_BAR; PG8_MMA(1, 0, At, B0); PG8_MMA(1, 1, At, B1); PG8_BAR; PG8_SCHED;
.LBB0_1354:
	s_add_u32 s24, s22, 0xfffc0080
	s_addc_u32 s25, s23, -1
	s_add_i32 s49, 0, 0x10000
	s_cmp_eq_u32 s48, 12
	s_cselect_b32 s27, s15, s25
	s_cselect_b32 s26, s21, s24
	v_add_u32_e32 v142, s49, v145
	s_cselect_b32 s25, s13, s47
	s_cselect_b32 s24, s45, s46
	s_add_i32 s52, 0, 0x14000
	ds_read_b128 v[150:153], v142
	ds_read_b128 v[154:157], v142 offset:1024
	ds_read_b128 v[158:161], v142 offset:2048
	ds_read_b128 v[162:165], v142 offset:3072
	v_add_u32_e32 v142, s52, v145
	ds_read_b128 v[166:169], v142
	ds_read_b128 v[170:173], v142 offset:1024
	ds_read_b128 v[174:177], v142 offset:2048
	ds_read_b128 v[178:181], v142 offset:3072
	s_add_i32 m0, s36, 0xc000
	ds_read_b128 v[182:185], v148
	ds_read_b128 v[202:205], v148 offset:1024
	ds_read_b128 v[206:209], v148 offset:2048
	ds_read_b128 v[210:213], v148 offset:3072
	ds_read_b128 v[232:235], v148 offset:4096
	ds_read_b128 v[236:239], v148 offset:5120
	ds_read_b128 v[240:243], v148 offset:6144
	ds_read_b128 v[244:247], v148 offset:7168
	global_load_lds_dwordx4 v138, s[22:23]
	s_add_i32 m0, s36, 0xe000
	s_nop 0
	global_load_lds_dwordx4 v140, s[22:23]
	s_waitcnt vmcnt(8)
	s_waitcnt lgkmcnt(0)
	s_barrier
	s_setprio 1
	s_waitcnt lgkmcnt(0)
	v_mfma_f32_16x16x32_bf16 v[126:129], v[150:153], v[182:185], v[126:129]
	v_mfma_f32_16x16x32_bf16 v[122:125], v[158:161], v[182:185], v[122:125]
	v_mfma_f32_16x16x32_bf16 v[114:117], v[150:153], v[206:209], v[114:117]
	v_mfma_f32_16x16x32_bf16 v[106:109], v[158:161], v[206:209], v[106:109]
	v_mfma_f32_16x16x32_bf16 v[98:101], v[150:153], v[232:235], v[98:101]
	v_mfma_f32_16x16x32_bf16 v[90:93], v[158:161], v[232:235], v[90:93]
	v_mfma_f32_16x16x32_bf16 v[78:81], v[150:153], v[240:243], v[78:81]
	v_mfma_f32_16x16x32_bf16 v[74:77], v[158:161], v[240:243], v[74:77]
	s_setprio 0
	s_setprio 1
	v_mfma_f32_16x16x32_bf16 v[126:129], v[154:157], v[202:205], v[126:129]
	v_mfma_f32_16x16x32_bf16 v[122:125], v[162:165], v[202:205], v[122:125]
	v_mfma_f32_16x16x32_bf16 v[114:117], v[154:157], v[210:213], v[114:117]
	v_mfma_f32_16x16x32_bf16 v[106:109], v[162:165], v[210:213], v[106:109]
	v_mfma_f32_16x16x32_bf16 v[98:101], v[154:157], v[236:239], v[98:101]
	v_mfma_f32_16x16x32_bf16 v[90:93], v[162:165], v[236:239], v[90:93]
	v_mfma_f32_16x16x32_bf16 v[78:81], v[154:157], v[244:247], v[78:81]
	v_mfma_f32_16x16x32_bf16 v[74:77], v[162:165], v[244:247], v[74:77]
	s_setprio 0
	s_setprio 1
	v_mfma_f32_16x16x32_bf16 v[118:121], v[166:169], v[182:185], v[118:121]
	v_mfma_f32_16x16x32_bf16 v[110:113], v[174:177], v[182:185], v[110:113]
	v_mfma_f32_16x16x32_bf16 v[102:105], v[166:169], v[206:209], v[102:105]
	v_mfma_f32_16x16x32_bf16 v[94:97], v[174:177], v[206:209], v[94:97]
	v_mfma_f32_16x16x32_bf16 v[86:89], v[166:169], v[232:235], v[86:89]
	v_mfma_f32_16x16x32_bf16 v[82:85], v[174:177], v[232:235], v[82:85]
	v_mfma_f32_16x16x32_bf16 v[70:73], v[166:169], v[240:243], v[70:73]
	v_mfma_f32_16x16x32_bf16 v[66:69], v[174:177], v[240:243], v[66:69]
	s_setprio 0
	s_setprio 1
	v_mfma_f32_16x16x32_bf16 v[118:121], v[170:173], v[202:205], v[118:121]
	v_mfma_f32_16x16x32_bf16 v[110:113], v[178:181], v[202:205], v[110:113]
	v_mfma_f32_16x16x32_bf16 v[102:105], v[170:173], v[210:213], v[102:105]
	v_mfma_f32_16x16x32_bf16 v[94:97], v[178:181], v[210:213], v[94:97]
	v_mfma_f32_16x16x32_bf16 v[86:89], v[170:173], v[236:239], v[86:89]
	v_mfma_f32_16x16x32_bf16 v[82:85], v[178:181], v[236:239], v[82:85]
	v_mfma_f32_16x16x32_bf16 v[70:73], v[170:173], v[244:247], v[70:73]
	v_mfma_f32_16x16x32_bf16 v[66:69], v[178:181], v[244:247], v[66:69]
	s_setprio 0
	s_barrier
	s_add_i32 s49, s49, s34
	s_mov_b32 m0, s49
	ds_read_b128 v[182:185], v148 offset:16384
	ds_read_b128 v[202:205], v148 offset:17408
	ds_read_b128 v[206:209], v148 offset:18432
	ds_read_b128 v[210:213], v148 offset:19456
	ds_read_b128 v[232:235], v148 offset:20480
	ds_read_b128 v[236:239], v148 offset:21504
	ds_read_b128 v[240:243], v148 offset:22528
	ds_read_b128 v[244:247], v148 offset:23552
	s_add_u32 s60, s24, 0x80
	s_addc_u32 s61, s25, 0
	s_add_u32 s62, s26, 0x80
	s_addc_u32 s63, s27, 0
	global_load_lds_dwordx4 v134, s[24:25]
	s_add_i32 m0, s49, 0x2000
	s_add_u32 s50, s24, 0x40000
	s_addc_u32 s51, s25, 0
	s_add_i32 s49, s52, s34
	global_load_lds_dwordx4 v130, s[24:25]
	s_mov_b32 m0, s49
	s_nop 0
	global_load_lds_dwordx4 v134, s[50:51]
	s_add_i32 m0, s49, 0x2000
	s_nop 0
	global_load_lds_dwordx4 v130, s[50:51]
	s_mov_b32 m0, s36
	s_nop 0
	global_load_lds_dwordx4 v136, s[26:27]
	s_mov_b32 m0, s37
	s_nop 0
	global_load_lds_dwordx4 v132, s[26:27]
	s_waitcnt vmcnt(8)
	s_waitcnt lgkmcnt(0)
	s_barrier
; #define PG8_STAGE(bufoff, gbase, voff) do { _Pragma("unroll") for (int _i = 0; _i < 2; ++_i) \
;         __builtin_amdgcn_global_load_lds((const unsigned*)((const char*)(gbase) + (voff)[_i]), (PG8_LAS unsigned*)(lds + (bufoff) + ldsw + _i * 8192), 16, 0, 0); } while (0)
; #define PG8_LDA(dst, b, h) do { _Pragma("unroll") for (int m = 0; m < 4; ++m) _Pragma("unroll") for (int k = 0; k < 2; ++k) dst[m][k] = *(const PG8_LAS bf16x8*)(lds + PG8_SA(b, h) + aoff + m * 2048 + k * 1024); } while (0)
; #define PG8_LDB(dst, b, h) do { _Pragma("unroll") for (int n = 0; n < 2; ++n) _Pragma("unroll") for (int k = 0; k < 2; ++k) dst[n][k] = *(const PG8_LAS bf16x8*)(lds + PG8_SB(b, h) + boff + n * 2048 + k * 1024); } while (0)
; #define PG8_MMA(ai, bj, At, Bt) do { __builtin_amdgcn_s_setprio(1); _Pragma("unroll") for (int m = 0; m < 4; ++m) _Pragma("unroll") for (int n = 0; n < 2; ++n) _Pragma("unroll") for (int k = 0; k < 2; ++k) \
;         acc[ai][bj][m][n] = __builtin_amdgcn_mfma_f32_16x16x32_bf16(Bt[n][k], At[m][k], acc[ai][bj][m][n], 0, 0, 0); __builtin_amdgcn_s_setprio(0); } while (0)
; #define PG8_WAIT_V(n) asm volatile("s_waitcnt vmcnt(" #n ")" ::: "memory")
; #define PG8_WAIT_L(n) asm volatile("s_waitcnt lgkmcnt(" #n ")" ::: "memory")
; #define PG8_BAR __builtin_amdgcn_s_barrier()
; #define PG8_SCHED __builtin_amdgcn_sched_barrier(0)
; template <class Epi, class Sched, bool ALIGN_EPI = false, bool SP2 = false>
; __device__ __forceinline__ void gemm_phase(PG8_LAS unsigned char* lds, const Gemm g, const Sched& S, const Epi& E) {
;     ...
;             PG8_WAIT_V(8); PG8_WAIT_L(0); PG8_BAR; PG8_MMA(1, 0, At, B0); PG8_MMA(1, 1, At, B1); PG8_BAR; PG8_SCHED;
;             PG8_LDB(B0, 1, 0); PG8_LDB(B1, 1, 1); PG8_SCHED; PG8_LDA(At, 1, 0); PG8_STAGE(PG8_SA(0, 1), a2 + hstepA, voffA);
;             PG8_WAIT_V(8); PG8_WAIT_L(0); PG8_BAR; PG8_MMA(0, 0, At, B0); PG8_MMA(0, 1, At, B1); PG8_BAR; PG8_SCHED;
	s_setprio 1
	s_waitcnt lgkmcnt(0)
	v_mfma_f32_16x16x32_bf16 v[62:65], v[150:153], v[182:185], v[62:65]
	v_mfma_f32_16x16x32_bf16 v[58:61], v[158:161], v[182:185], v[58:61]
	v_mfma_f32_16x16x32_bf16 v[46:49], v[150:153], v[206:209], v[46:49]
	v_mfma_f32_16x16x32_bf16 v[42:45], v[158:161], v[206:209], v[42:45]
	v_mfma_f32_16x16x32_bf16 v[30:33], v[150:153], v[232:235], v[30:33]
	v_mfma_f32_16x16x32_bf16 v[26:29], v[158:161], v[232:235], v[26:29]
	v_mfma_f32_16x16x32_bf16 v[14:17], v[150:153], v[240:243], v[14:17]
	v_mfma_f32_16x16x32_bf16 v[10:13], v[158:161], v[240:243], v[10:13]
	s_setprio 0
	s_setprio 1
	v_mfma_f32_16x16x32_bf16 v[62:65], v[154:157], v[202:205], v[62:65]
	v_mfma_f32_16x16x32_bf16 v[58:61], v[162:165], v[202:205], v[58:61]
	v_mfma_f32_16x16x32_bf16 v[46:49], v[154:157], v[210:213], v[46:49]
	v_mfma_f32_16x16x32_bf16 v[42:45], v[162:165], v[210:213], v[42:45]
	v_mfma_f32_16x16x32_bf16 v[30:33], v[154:157], v[236:239], v[30:33]
	v_mfma_f32_16x16x32_bf16 v[26:29], v[162:165], v[236:239], v[26:29]
	v_mfma_f32_16x16x32_bf16 v[14:17], v[154:157], v[244:247], v[14:17]
	v_mfma_f32_16x16x32_bf16 v[10:13], v[162:165], v[244:247], v[10:13]
	s_setprio 0
	s_setprio 1
	v_mfma_f32_16x16x32_bf16 v[54:57], v[166:169], v[182:185], v[54:57]
	v_mfma_f32_16x16x32_bf16 v[50:53], v[174:177], v[182:185], v[50:53]
	v_mfma_f32_16x16x32_bf16 v[38:41], v[166:169], v[206:209], v[38:41]
	v_mfma_f32_16x16x32_bf16 v[34:37], v[174:177], v[206:209], v[34:37]
	v_mfma_f32_16x16x32_bf16 v[22:25], v[166:169], v[232:235], v[22:25]
	v_mfma_f32_16x16x32_bf16 v[18:21], v[174:177], v[232:235], v[18:21]
	v_mfma_f32_16x16x32_bf16 v[6:9], v[166:169], v[240:243], v[6:9]
	v_mfma_f32_16x16x32_bf16 v[2:5], v[174:177], v[240:243], v[2:5]
	s_setprio 0
	s_setprio 1
	v_mfma_f32_16x16x32_bf16 v[54:57], v[170:173], v[202:205], v[54:57]
	v_mfma_f32_16x16x32_bf16 v[50:53], v[178:181], v[202:205], v[50:53]
	v_mfma_f32_16x16x32_bf16 v[38:41], v[170:173], v[210:213], v[38:41]
	v_mfma_f32_16x16x32_bf16 v[34:37], v[178:181], v[210:213], v[34:37]
	v_mfma_f32_16x16x32_bf16 v[22:25], v[170:173], v[236:239], v[22:25]
	v_mfma_f32_16x16x32_bf16 v[18:21], v[178:181], v[236:239], v[18:21]
	v_mfma_f32_16x16x32_bf16 v[6:9], v[170:173], v[244:247], v[6:9]
	v_mfma_f32_16x16x32_bf16 v[2:5], v[178:181], v[244:247], v[2:5]
	s_setprio 0
	s_barrier
	s_add_i32 s49, 0, 0x18000
	v_add_u32_e32 v144, s49, v145
	s_add_i32 s50, 0, 0x1c000
	ds_read_b128 v[150:153], v144
	ds_read_b128 v[154:157], v144 offset:1024
	ds_read_b128 v[158:161], v144 offset:2048
	ds_read_b128 v[162:165], v144 offset:3072
	v_add_u32_e32 v144, s50, v145
	ds_read_b128 v[166:169], v144
	ds_read_b128 v[170:173], v144 offset:1024
	ds_read_b128 v[174:177], v144 offset:2048
	ds_read_b128 v[178:181], v144 offset:3072
	s_add_u32 s26, s26, 0x40000
	s_addc_u32 s27, s27, 0
	s_mov_b32 m0, s38
	ds_read_b128 v[182:185], v148 offset:32768
	ds_read_b128 v[202:205], v148 offset:33792
	ds_read_b128 v[206:209], v148 offset:34816
	ds_read_b128 v[210:213], v148 offset:35840
	ds_read_b128 v[232:235], v148 offset:36864
	ds_read_b128 v[236:239], v148 offset:37888
	ds_read_b128 v[240:243], v148 offset:38912
	ds_read_b128 v[244:247], v148 offset:39936
	global_load_lds_dwordx4 v136, s[26:27]
	s_mov_b32 m0, s39
	s_nop 0
	global_load_lds_dwordx4 v132, s[26:27]
	s_waitcnt vmcnt(8)
	s_waitcnt lgkmcnt(0)
	s_barrier
	s_setprio 1
	s_waitcnt lgkmcnt(0)
	v_mfma_f32_16x16x32_bf16 v[126:129], v[150:153], v[182:185], v[126:129]
	v_mfma_f32_16x16x32_bf16 v[122:125], v[158:161], v[182:185], v[122:125]
	v_mfma_f32_16x16x32_bf16 v[114:117], v[150:153], v[206:209], v[114:117]
	v_mfma_f32_16x16x32_bf16 v[106:109], v[158:161], v[206:209], v[106:109]
	v_mfma_f32_16x16x32_bf16 v[98:101], v[150:153], v[232:235], v[98:101]
	v_mfma_f32_16x16x32_bf16 v[90:93], v[158:161], v[232:235], v[90:93]
	v_mfma_f32_16x16x32_bf16 v[78:81], v[150:153], v[240:243], v[78:81]
	v_mfma_f32_16x16x32_bf16 v[74:77], v[158:161], v[240:243], v[74:77]
	s_setprio 0
	s_setprio 1
	v_mfma_f32_16x16x32_bf16 v[126:129], v[154:157], v[202:205], v[126:129]
	v_mfma_f32_16x16x32_bf16 v[122:125], v[162:165], v[202:205], v[122:125]
	v_mfma_f32_16x16x32_bf16 v[114:117], v[154:157], v[210:213], v[114:117]
	v_mfma_f32_16x16x32_bf16 v[106:109], v[162:165], v[210:213], v[106:109]
	v_mfma_f32_16x16x32_bf16 v[98:101], v[154:157], v[236:239], v[98:101]
	v_mfma_f32_16x16x32_bf16 v[90:93], v[162:165], v[236:239], v[90:93]
	v_mfma_f32_16x16x32_bf16 v[78:81], v[154:157], v[244:247], v[78:81]
	v_mfma_f32_16x16x32_bf16 v[74:77], v[162:165], v[244:247], v[74:77]
	s_setprio 0
	s_setprio 1
	v_mfma_f32_16x16x32_bf16 v[118:121], v[166:169], v[182:185], v[118:121]
	v_mfma_f32_16x16x32_bf16 v[110:113], v[174:177], v[182:185], v[110:113]
	v_mfma_f32_16x16x32_bf16 v[102:105], v[166:169], v[206:209], v[102:105]
	v_mfma_f32_16x16x32_bf16 v[94:97], v[174:177], v[206:209], v[94:97]
	v_mfma_f32_16x16x32_bf16 v[86:89], v[166:169], v[232:235], v[86:89]
	v_mfma_f32_16x16x32_bf16 v[82:85], v[174:177], v[232:235], v[82:85]
	v_mfma_f32_16x16x32_bf16 v[70:73], v[166:169], v[240:243], v[70:73]
	v_mfma_f32_16x16x32_bf16 v[66:69], v[174:177], v[240:243], v[66:69]
	s_setprio 0
	s_setprio 1
	v_mfma_f32_16x16x32_bf16 v[118:121], v[170:173], v[202:205], v[118:121]
	v_mfma_f32_16x16x32_bf16 v[110:113], v[178:181], v[202:205], v[110:113]
	v_mfma_f32_16x16x32_bf16 v[102:105], v[170:173], v[210:213], v[102:105]
	v_mfma_f32_16x16x32_bf16 v[94:97], v[178:181], v[210:213], v[94:97]
	v_mfma_f32_16x16x32_bf16 v[86:89], v[170:173], v[236:239], v[86:89]
	v_mfma_f32_16x16x32_bf16 v[82:85], v[178:181], v[236:239], v[82:85]
	v_mfma_f32_16x16x32_bf16 v[70:73], v[170:173], v[244:247], v[70:73]
	v_mfma_f32_16x16x32_bf16 v[66:69], v[178:181], v[244:247], v[66:69]
	s_setprio 0
	s_barrier
; #define PG8_STAGE(bufoff, gbase, voff) do { _Pragma("unroll") for (int _i = 0; _i < 2; ++_i) \
;         __builtin_amdgcn_global_load_lds((const unsigned*)((const char*)(gbase) + (voff)[_i]), (PG8_LAS unsigned*)(lds + (bufoff) + ldsw + _i * 8192), 16, 0, 0); } while (0)
; #define PG8_LDA(dst, b, h) do { _Pragma("unroll") for (int m = 0; m < 4; ++m) _Pragma("unroll") for (int k = 0; k < 2; ++k) dst[m][k] = *(const PG8_LAS bf16x8*)(lds + PG8_SA(b, h) + aoff + m * 2048 + k * 1024); } while (0)
; #define PG8_MMA(ai, bj, At, Bt) do { __builtin_amdgcn_s_setprio(1); _Pragma("unroll") for (int m = 0; m < 4; ++m) _Pragma("unroll") for (int n = 0; n < 2; ++n) _Pragma("unroll") for (int k = 0; k < 2; ++k) \
;         acc[ai][bj][m][n] = __builtin_amdgcn_mfma_f32_16x16x32_bf16(Bt[n][k], At[m][k], acc[ai][bj][m][n], 0, 0, 0); __builtin_amdgcn_s_setprio(0); } while (0)
; #define PG8_WAIT_V(n) asm volatile("s_waitcnt vmcnt(" #n ")" ::: "memory")
; #define PG8_WAIT_L(n) asm volatile("s_waitcnt lgkmcnt(" #n ")" ::: "memory")
; #define PG8_BAR __builtin_amdgcn_s_barrier()
; #define PG8_SCHED __builtin_amdgcn_sched_barrier(0)
; template <class Epi, class Sched, bool ALIGN_EPI = false, bool SP2 = false>
; __device__ __forceinline__ void gemm_phase(PG8_LAS unsigned char* lds, const Gemm g, const Sched& S, const Epi& E) {
;     ...
;             PG8_LDA(At, 1, 1); PG8_STAGE(PG8_SB(1, 0), b3, voffB); PG8_STAGE(PG8_SB(1, 1), b3 + hstepB, voffB); PG8_STAGE(PG8_SA(1, 0), a3, voffA);
;             PG8_WAIT_V(8); PG8_WAIT_L(0); PG8_BAR; PG8_MMA(1, 0, At, B0); PG8_MMA(1, 1, At, B1); PG8_BAR; PG8_SCHED;
	s_add_i32 s26, s49, s34
	s_mov_b32 m0, s26
	ds_read_b128 v[182:185], v148 offset:49152
	ds_read_b128 v[202:205], v148 offset:50176
	ds_read_b128 v[206:209], v148 offset:51200
	ds_read_b128 v[210:213], v148 offset:52224
	ds_read_b128 v[232:235], v148 offset:53248
	ds_read_b128 v[236:239], v148 offset:54272
	ds_read_b128 v[240:243], v148 offset:55296
	ds_read_b128 v[244:247], v148 offset:56320
	global_load_lds_dwordx4 v134, s[60:61]
	s_add_i32 m0, s26, 0x2000
	s_add_u32 s24, s24, 0x40080
	s_addc_u32 s25, s25, 0
	s_add_i32 s26, s50, s34
	global_load_lds_dwordx4 v130, s[60:61]
	s_mov_b32 m0, s26
	s_nop 0
	global_load_lds_dwordx4 v134, s[24:25]
	s_add_i32 m0, s26, 0x2000
	s_nop 0
	global_load_lds_dwordx4 v130, s[24:25]
	s_mov_b32 m0, s40
	s_nop 0
	global_load_lds_dwordx4 v136, s[62:63]
	s_mov_b32 m0, s41
	s_nop 0
	global_load_lds_dwordx4 v132, s[62:63]
	s_waitcnt vmcnt(8)
	s_waitcnt lgkmcnt(0)
	s_barrier
	s_setprio 1
	s_waitcnt lgkmcnt(0)
	v_mfma_f32_16x16x32_bf16 v[62:65], v[150:153], v[182:185], v[62:65]
	v_mfma_f32_16x16x32_bf16 v[58:61], v[158:161], v[182:185], v[58:61]
	v_mfma_f32_16x16x32_bf16 v[46:49], v[150:153], v[206:209], v[46:49]
	v_mfma_f32_16x16x32_bf16 v[42:45], v[158:161], v[206:209], v[42:45]
	v_mfma_f32_16x16x32_bf16 v[30:33], v[150:153], v[232:235], v[30:33]
	v_mfma_f32_16x16x32_bf16 v[26:29], v[158:161], v[232:235], v[26:29]
	v_mfma_f32_16x16x32_bf16 v[14:17], v[150:153], v[240:243], v[14:17]
	v_mfma_f32_16x16x32_bf16 v[10:13], v[158:161], v[240:243], v[10:13]
	s_setprio 0
	s_setprio 1
	v_mfma_f32_16x16x32_bf16 v[62:65], v[154:157], v[202:205], v[62:65]
	v_mfma_f32_16x16x32_bf16 v[58:61], v[162:165], v[202:205], v[58:61]
	v_mfma_f32_16x16x32_bf16 v[46:49], v[154:157], v[210:213], v[46:49]
	v_mfma_f32_16x16x32_bf16 v[42:45], v[162:165], v[210:213], v[42:45]
	v_mfma_f32_16x16x32_bf16 v[30:33], v[154:157], v[236:239], v[30:33]
	v_mfma_f32_16x16x32_bf16 v[26:29], v[162:165], v[236:239], v[26:29]
	v_mfma_f32_16x16x32_bf16 v[14:17], v[154:157], v[244:247], v[14:17]
	v_mfma_f32_16x16x32_bf16 v[10:13], v[162:165], v[244:247], v[10:13]
	s_setprio 0
	s_setprio 1
	v_mfma_f32_16x16x32_bf16 v[54:57], v[166:169], v[182:185], v[54:57]
	v_mfma_f32_16x16x32_bf16 v[50:53], v[174:177], v[182:185], v[50:53]
	v_mfma_f32_16x16x32_bf16 v[38:41], v[166:169], v[206:209], v[38:41]
	v_mfma_f32_16x16x32_bf16 v[34:37], v[174:177], v[206:209], v[34:37]
	v_mfma_f32_16x16x32_bf16 v[22:25], v[166:169], v[232:235], v[22:25]
	v_mfma_f32_16x16x32_bf16 v[18:21], v[174:177], v[232:235], v[18:21]
	v_mfma_f32_16x16x32_bf16 v[6:9], v[166:169], v[240:243], v[6:9]
	v_mfma_f32_16x16x32_bf16 v[2:5], v[174:177], v[240:243], v[2:5]
	s_setprio 0
	s_setprio 1
	v_mfma_f32_16x16x32_bf16 v[54:57], v[170:173], v[202:205], v[54:57]
	v_mfma_f32_16x16x32_bf16 v[50:53], v[178:181], v[202:205], v[50:53]
	v_mfma_f32_16x16x32_bf16 v[38:41], v[170:173], v[210:213], v[38:41]
	v_mfma_f32_16x16x32_bf16 v[34:37], v[178:181], v[210:213], v[34:37]
	v_mfma_f32_16x16x32_bf16 v[22:25], v[170:173], v[236:239], v[22:25]
	v_mfma_f32_16x16x32_bf16 v[18:21], v[178:181], v[236:239], v[18:21]
	v_mfma_f32_16x16x32_bf16 v[6:9], v[170:173], v[244:247], v[6:9]
	v_mfma_f32_16x16x32_bf16 v[2:5], v[178:181], v[244:247], v[2:5]
	s_setprio 0
	s_barrier
	s_add_i32 s48, s48, 2
	s_add_u32 s22, s22, 0x100
	s_addc_u32 s23, s23, 0
	s_add_u32 s46, s46, 0x100
	s_addc_u32 s47, s47, 0
	s_cmp_gt_u32 s48, 13
	s_cbranch_scc0 .LBB0_1354
	s_and_b64 vcc, exec, s[10:11]
	s_cbranch_vccz .LBB0_1357
	s_barrier

; #define PG8_STAGE(bufoff, gbase, voff) do { _Pragma("unroll") for (int _i = 0; _i < 2; ++_i) \
;         __builtin_amdgcn_global_load_lds((const unsigned*)((const char*)(gbase) + (voff)[_i]), (PG8_LAS unsigned*)(lds + (bufoff) + ldsw + _i * 8192), 16, 0, 0); } while (0)
; #define PG8_LDA(dst, b, h) do { _Pragma("unroll") for (int m = 0; m < 4; ++m) _Pragma("unroll") for (int k = 0; k < 2; ++k) dst[m][k] = *(const PG8_LAS bf16x8*)(lds + PG8_SA(b, h) + aoff + m * 2048 + k * 1024); } while (0)
; #define PG8_LDB(dst, b, h) do { _Pragma("unroll") for (int n = 0; n < 2; ++n) _Pragma("unroll") for (int k = 0; k < 2; ++k) dst[n][k] = *(const PG8_LAS bf16x8*)(lds + PG8_SB(b, h) + boff + n * 2048 + k * 1024); } while (0)
; #define PG8_MMA(ai, bj, At, Bt) do { __builtin_amdgcn_s_setprio(1); _Pragma("unroll") for (int m = 0; m < 4; ++m) _Pragma("unroll") for (int n = 0; n < 2; ++n) _Pragma("unroll") for (int k = 0; k < 2; ++k) \
;         acc[ai][bj][m][n] = __builtin_amdgcn_mfma_f32_16x16x32_bf16(Bt[n][k], At[m][k], acc[ai][bj][m][n], 0, 0, 0); __builtin_amdgcn_s_setprio(0); } while (0)
; #define PG8_WAIT_V(n) asm volatile("s_waitcnt vmcnt(" #n ")" ::: "memory")
; #define PG8_BAR __builtin_amdgcn_s_barrier()
; template <class Epi, class Sched, bool ALIGN_EPI = false, bool SP2 = false>
; __device__ __forceinline__ void gemm_phase(PG8_LAS unsigned char* lds, const Gemm g, const Sched& S, const Epi& E) {
;     ...
;         for (int t = 0; t < nt; t += 2) {
;             const bool last = (t == nt - 2);
;             const char* a1 = cA + (size_t)(t + 1) * kstep;
;             const char* a2 = last ? nA : cA + (size_t)(t + 2) * kstep; const char* b2 = last ? nB : cB + (size_t)(t + 2) * kstep;
;             const char* a3 = a2 + kstep; const char* b3 = b2 + kstep;
;             if (last && has_next) S.a_ready(nxt);
;             if constexpr (SP2) {
;             PG8_LDB(B0, 0, 0); PG8_LDB(B1, 0, 1); PG8_SCHED; PG8_LDA(At, 0, 0); PG8_STAGE(PG8_SA(1, 1), a1 + hstepA, voffA);
;             PG8_WAIT_V(8); PG8_WAIT_L(0); PG8_BAR; PG8_MMA(0, 0, At, B0); PG8_MMA(0, 1, At, B1); PG8_BAR; PG8_SCHED;
;             PG8_LDA(At, 0, 1); PG8_STAGE(PG8_SB(0, 0), b2, voffB); PG8_STAGE(PG8_SB(0, 1), b2 + hstepB, voffB); PG8_STAGE(PG8_SA(0, 0), a2, voffA);
;             PG8_WAIT_V(8); PG8_WAIT_L(0); PG8_BAR; PG8_MMA(1, 0, At, B0); PG8_MMA(1, 1, At, B1); PG8_BAR; PG8_SCHED;
.LBB0_1438:
	s_add_u32 s20, s18, 0x100
	s_addc_u32 s21, s19, 0
	s_add_i32 s50, 0, 0x10000
	s_cmp_eq_u32 s49, 40
	s_cselect_b32 s25, s9, s21
	s_cselect_b32 s24, s8, s20
	s_cselect_b32 s23, s17, s48
	s_cselect_b32 s22, s16, s47
	s_add_i32 s51, 0, 0x14000
	v_add_u32_e32 v142, s50, v186
	v_add_u32_e32 v172, s51, v186
	ds_read_b128 v[130:133], v142
	ds_read_b128 v[134:137], v142 offset:1024
	ds_read_b128 v[138:141], v142 offset:2048
	ds_read_b128 v[142:145], v142 offset:3072
	ds_read_b128 v[146:149], v172
	ds_read_b128 v[150:153], v172 offset:1024
	ds_read_b128 v[168:171], v172 offset:2048
	ds_read_b128 v[172:175], v172 offset:3072
	s_add_i32 m0, s31, 0xc000
	ds_read_b128 v[176:179], v200
	ds_read_b128 v[180:183], v200 offset:1024
	ds_read_b128 v[202:205], v200 offset:2048
	ds_read_b128 v[206:209], v200 offset:3072
	ds_read_b128 v[210:213], v200 offset:4096
	ds_read_b128 v[232:235], v200 offset:5120
	ds_read_b128 v[236:239], v200 offset:6144
	ds_read_b128 v[240:243], v200 offset:7168
	global_load_lds_dwordx4 v164, s[18:19]
	s_add_i32 m0, s31, 0xe000
	s_nop 0
	global_load_lds_dwordx4 v166, s[18:19]
	s_waitcnt vmcnt(8)
	s_waitcnt lgkmcnt(0)
	s_barrier
	s_setprio 1
	s_waitcnt lgkmcnt(0)
	v_mfma_f32_16x16x32_bf16 v[126:129], v[130:133], v[176:179], v[126:129]
	v_mfma_f32_16x16x32_bf16 v[122:125], v[138:141], v[176:179], v[122:125]
	v_mfma_f32_16x16x32_bf16 v[110:113], v[130:133], v[202:205], v[110:113]
	v_mfma_f32_16x16x32_bf16 v[106:109], v[138:141], v[202:205], v[106:109]
	v_mfma_f32_16x16x32_bf16 v[94:97], v[130:133], v[210:213], v[94:97]
	v_mfma_f32_16x16x32_bf16 v[90:93], v[138:141], v[210:213], v[90:93]
	v_mfma_f32_16x16x32_bf16 v[78:81], v[130:133], v[236:239], v[78:81]
	v_mfma_f32_16x16x32_bf16 v[74:77], v[138:141], v[236:239], v[74:77]
	s_setprio 0
	s_setprio 1
	v_mfma_f32_16x16x32_bf16 v[126:129], v[134:137], v[180:183], v[126:129]
	v_mfma_f32_16x16x32_bf16 v[122:125], v[142:145], v[180:183], v[122:125]
	v_mfma_f32_16x16x32_bf16 v[110:113], v[134:137], v[206:209], v[110:113]
	v_mfma_f32_16x16x32_bf16 v[106:109], v[142:145], v[206:209], v[106:109]
	v_mfma_f32_16x16x32_bf16 v[94:97], v[134:137], v[232:235], v[94:97]
	v_mfma_f32_16x16x32_bf16 v[90:93], v[142:145], v[232:235], v[90:93]
	v_mfma_f32_16x16x32_bf16 v[78:81], v[134:137], v[240:243], v[78:81]
	v_mfma_f32_16x16x32_bf16 v[74:77], v[142:145], v[240:243], v[74:77]
	s_setprio 0
	s_setprio 1
	v_mfma_f32_16x16x32_bf16 v[118:121], v[146:149], v[176:179], v[118:121]
	v_mfma_f32_16x16x32_bf16 v[114:117], v[168:171], v[176:179], v[114:117]
	v_mfma_f32_16x16x32_bf16 v[102:105], v[146:149], v[202:205], v[102:105]
	v_mfma_f32_16x16x32_bf16 v[98:101], v[168:171], v[202:205], v[98:101]
	v_mfma_f32_16x16x32_bf16 v[86:89], v[146:149], v[210:213], v[86:89]
	v_mfma_f32_16x16x32_bf16 v[82:85], v[168:171], v[210:213], v[82:85]
	v_mfma_f32_16x16x32_bf16 v[70:73], v[146:149], v[236:239], v[70:73]
	v_mfma_f32_16x16x32_bf16 v[66:69], v[168:171], v[236:239], v[66:69]
	s_setprio 0
	s_setprio 1
	v_mfma_f32_16x16x32_bf16 v[118:121], v[150:153], v[180:183], v[118:121]
	v_mfma_f32_16x16x32_bf16 v[114:117], v[172:175], v[180:183], v[114:117]
	v_mfma_f32_16x16x32_bf16 v[102:105], v[150:153], v[206:209], v[102:105]
	v_mfma_f32_16x16x32_bf16 v[98:101], v[172:175], v[206:209], v[98:101]
	v_mfma_f32_16x16x32_bf16 v[86:89], v[150:153], v[232:235], v[86:89]
	v_mfma_f32_16x16x32_bf16 v[82:85], v[172:175], v[232:235], v[82:85]
	v_mfma_f32_16x16x32_bf16 v[70:73], v[150:153], v[240:243], v[70:73]
	v_mfma_f32_16x16x32_bf16 v[66:69], v[172:175], v[240:243], v[66:69]
	s_setprio 0
	s_barrier
	s_add_i32 s18, s50, s30
	s_mov_b32 m0, s18
	ds_read_b128 v[176:179], v200 offset:16384
	ds_read_b128 v[180:183], v200 offset:17408
	ds_read_b128 v[202:205], v200 offset:18432
	ds_read_b128 v[206:209], v200 offset:19456
	ds_read_b128 v[210:213], v200 offset:20480
	ds_read_b128 v[232:235], v200 offset:21504
	ds_read_b128 v[236:239], v200 offset:22528
	ds_read_b128 v[240:243], v200 offset:23552
	s_add_u32 s60, s22, 0x80
	s_addc_u32 s61, s23, 0
	s_add_u32 s62, s24, 0x80
	s_addc_u32 s63, s25, 0
	global_load_lds_dwordx4 v156, s[22:23]
	s_add_i32 m0, s18, 0x2000
	s_add_u32 s18, s22, 0xb0000
	s_addc_u32 s19, s23, 0
	s_add_i32 s50, s51, s30
	global_load_lds_dwordx4 v160, s[22:23]
	s_mov_b32 m0, s50
	s_nop 0
	global_load_lds_dwordx4 v156, s[18:19]
	s_add_i32 m0, s50, 0x2000
	s_nop 0
	global_load_lds_dwordx4 v160, s[18:19]
	s_mov_b32 m0, s31
	s_nop 0
	global_load_lds_dwordx4 v154, s[24:25]
	s_mov_b32 m0, s34
	s_nop 0
	global_load_lds_dwordx4 v158, s[24:25]
	s_waitcnt vmcnt(8)
	s_waitcnt lgkmcnt(0)
	s_barrier
; #define PG8_STAGE(bufoff, gbase, voff) do { _Pragma("unroll") for (int _i = 0; _i < 2; ++_i) \
;         __builtin_amdgcn_global_load_lds((const unsigned*)((const char*)(gbase) + (voff)[_i]), (PG8_LAS unsigned*)(lds + (bufoff) + ldsw + _i * 8192), 16, 0, 0); } while (0)
; #define PG8_LDA(dst, b, h) do { _Pragma("unroll") for (int m = 0; m < 4; ++m) _Pragma("unroll") for (int k = 0; k < 2; ++k) dst[m][k] = *(const PG8_LAS bf16x8*)(lds + PG8_SA(b, h) + aoff + m * 2048 + k * 1024); } while (0)
; #define PG8_LDB(dst, b, h) do { _Pragma("unroll") for (int n = 0; n < 2; ++n) _Pragma("unroll") for (int k = 0; k < 2; ++k) dst[n][k] = *(const PG8_LAS bf16x8*)(lds + PG8_SB(b, h) + boff + n * 2048 + k * 1024); } while (0)
; #define PG8_MMA(ai, bj, At, Bt) do { __builtin_amdgcn_s_setprio(1); _Pragma("unroll") for (int m = 0; m < 4; ++m) _Pragma("unroll") for (int n = 0; n < 2; ++n) _Pragma("unroll") for (int k = 0; k < 2; ++k) \
;         acc[ai][bj][m][n] = __builtin_amdgcn_mfma_f32_16x16x32_bf16(Bt[n][k], At[m][k], acc[ai][bj][m][n], 0, 0, 0); __builtin_amdgcn_s_setprio(0); } while (0)
; #define PG8_WAIT_V(n) asm volatile("s_waitcnt vmcnt(" #n ")" ::: "memory")
; #define PG8_WAIT_L(n) asm volatile("s_waitcnt lgkmcnt(" #n ")" ::: "memory")
; #define PG8_BAR __builtin_amdgcn_s_barrier()
; #define PG8_SCHED __builtin_amdgcn_sched_barrier(0)
; template <class Epi, class Sched, bool ALIGN_EPI = false, bool SP2 = false>
; __device__ __forceinline__ void gemm_phase(PG8_LAS unsigned char* lds, const Gemm g, const Sched& S, const Epi& E) {
;     ...
;             PG8_WAIT_V(8); PG8_WAIT_L(0); PG8_BAR; PG8_MMA(1, 0, At, B0); PG8_MMA(1, 1, At, B1); PG8_BAR; PG8_SCHED;
;             PG8_LDB(B0, 1, 0); PG8_LDB(B1, 1, 1); PG8_SCHED; PG8_LDA(At, 1, 0); PG8_STAGE(PG8_SA(0, 1), a2 + hstepA, voffA);
;             PG8_WAIT_V(8); PG8_WAIT_L(0); PG8_BAR; PG8_MMA(0, 0, At, B0); PG8_MMA(0, 1, At, B1); PG8_BAR; PG8_SCHED;
	s_setprio 1
	s_waitcnt lgkmcnt(0)
	v_mfma_f32_16x16x32_bf16 v[62:65], v[130:133], v[176:179], v[62:65]
	v_mfma_f32_16x16x32_bf16 v[58:61], v[138:141], v[176:179], v[58:61]
	v_mfma_f32_16x16x32_bf16 v[46:49], v[130:133], v[202:205], v[46:49]
	v_mfma_f32_16x16x32_bf16 v[42:45], v[138:141], v[202:205], v[42:45]
	v_mfma_f32_16x16x32_bf16 v[30:33], v[130:133], v[210:213], v[30:33]
	v_mfma_f32_16x16x32_bf16 v[26:29], v[138:141], v[210:213], v[26:29]
	v_mfma_f32_16x16x32_bf16 v[14:17], v[130:133], v[236:239], v[14:17]
	v_mfma_f32_16x16x32_bf16 v[10:13], v[138:141], v[236:239], v[10:13]
	s_setprio 0
	s_setprio 1
	v_mfma_f32_16x16x32_bf16 v[62:65], v[134:137], v[180:183], v[62:65]
	v_mfma_f32_16x16x32_bf16 v[58:61], v[142:145], v[180:183], v[58:61]
	v_mfma_f32_16x16x32_bf16 v[46:49], v[134:137], v[206:209], v[46:49]
	v_mfma_f32_16x16x32_bf16 v[42:45], v[142:145], v[206:209], v[42:45]
	v_mfma_f32_16x16x32_bf16 v[30:33], v[134:137], v[232:235], v[30:33]
	v_mfma_f32_16x16x32_bf16 v[26:29], v[142:145], v[232:235], v[26:29]
	v_mfma_f32_16x16x32_bf16 v[14:17], v[134:137], v[240:243], v[14:17]
	v_mfma_f32_16x16x32_bf16 v[10:13], v[142:145], v[240:243], v[10:13]
	s_setprio 0
	s_setprio 1
	v_mfma_f32_16x16x32_bf16 v[54:57], v[146:149], v[176:179], v[54:57]
	v_mfma_f32_16x16x32_bf16 v[50:53], v[168:171], v[176:179], v[50:53]
	v_mfma_f32_16x16x32_bf16 v[38:41], v[146:149], v[202:205], v[38:41]
	v_mfma_f32_16x16x32_bf16 v[34:37], v[168:171], v[202:205], v[34:37]
	v_mfma_f32_16x16x32_bf16 v[22:25], v[146:149], v[210:213], v[22:25]
	v_mfma_f32_16x16x32_bf16 v[18:21], v[168:171], v[210:213], v[18:21]
	v_mfma_f32_16x16x32_bf16 v[6:9], v[146:149], v[236:239], v[6:9]
	v_mfma_f32_16x16x32_bf16 v[2:5], v[168:171], v[236:239], v[2:5]
	s_setprio 0
	s_setprio 1
	v_mfma_f32_16x16x32_bf16 v[54:57], v[150:153], v[180:183], v[54:57]
	v_mfma_f32_16x16x32_bf16 v[50:53], v[172:175], v[180:183], v[50:53]
	v_mfma_f32_16x16x32_bf16 v[38:41], v[150:153], v[206:209], v[38:41]
	v_mfma_f32_16x16x32_bf16 v[34:37], v[172:175], v[206:209], v[34:37]
	v_mfma_f32_16x16x32_bf16 v[22:25], v[150:153], v[232:235], v[22:25]
	v_mfma_f32_16x16x32_bf16 v[18:21], v[172:175], v[232:235], v[18:21]
	v_mfma_f32_16x16x32_bf16 v[6:9], v[150:153], v[240:243], v[6:9]
	v_mfma_f32_16x16x32_bf16 v[2:5], v[172:175], v[240:243], v[2:5]
	s_setprio 0
	s_barrier
	s_add_i32 s50, 0, 0x18000
	s_add_i32 s51, 0, 0x1c000
	v_add_u32_e32 v142, s50, v186
	v_add_u32_e32 v172, s51, v186
	ds_read_b128 v[130:133], v142
	ds_read_b128 v[134:137], v142 offset:1024
	ds_read_b128 v[138:141], v142 offset:2048
	ds_read_b128 v[142:145], v142 offset:3072
	ds_read_b128 v[146:149], v172
	ds_read_b128 v[150:153], v172 offset:1024
	ds_read_b128 v[168:171], v172 offset:2048
	ds_read_b128 v[172:175], v172 offset:3072
	s_add_u32 s18, s24, 0xb0000
	s_addc_u32 s19, s25, 0
	s_mov_b32 m0, s35
	ds_read_b128 v[176:179], v200 offset:32768
	ds_read_b128 v[180:183], v200 offset:33792
	ds_read_b128 v[202:205], v200 offset:34816
	ds_read_b128 v[206:209], v200 offset:35840
	ds_read_b128 v[210:213], v200 offset:36864
	ds_read_b128 v[232:235], v200 offset:37888
	ds_read_b128 v[236:239], v200 offset:38912
	ds_read_b128 v[240:243], v200 offset:39936
	global_load_lds_dwordx4 v154, s[18:19]
	s_mov_b32 m0, s36
	s_nop 0
	global_load_lds_dwordx4 v158, s[18:19]
	s_waitcnt vmcnt(8)
	s_waitcnt lgkmcnt(0)
	s_barrier
	s_setprio 1
	s_waitcnt lgkmcnt(0)
	v_mfma_f32_16x16x32_bf16 v[126:129], v[130:133], v[176:179], v[126:129]
	v_mfma_f32_16x16x32_bf16 v[122:125], v[138:141], v[176:179], v[122:125]
	v_mfma_f32_16x16x32_bf16 v[110:113], v[130:133], v[202:205], v[110:113]
	v_mfma_f32_16x16x32_bf16 v[106:109], v[138:141], v[202:205], v[106:109]
	v_mfma_f32_16x16x32_bf16 v[94:97], v[130:133], v[210:213], v[94:97]
	v_mfma_f32_16x16x32_bf16 v[90:93], v[138:141], v[210:213], v[90:93]
	v_mfma_f32_16x16x32_bf16 v[78:81], v[130:133], v[236:239], v[78:81]
	v_mfma_f32_16x16x32_bf16 v[74:77], v[138:141], v[236:239], v[74:77]
	s_setprio 0
	s_setprio 1
	v_mfma_f32_16x16x32_bf16 v[126:129], v[134:137], v[180:183], v[126:129]
	v_mfma_f32_16x16x32_bf16 v[122:125], v[142:145], v[180:183], v[122:125]
	v_mfma_f32_16x16x32_bf16 v[110:113], v[134:137], v[206:209], v[110:113]
	v_mfma_f32_16x16x32_bf16 v[106:109], v[142:145], v[206:209], v[106:109]
	v_mfma_f32_16x16x32_bf16 v[94:97], v[134:137], v[232:235], v[94:97]
	v_mfma_f32_16x16x32_bf16 v[90:93], v[142:145], v[232:235], v[90:93]
	v_mfma_f32_16x16x32_bf16 v[78:81], v[134:137], v[240:243], v[78:81]
	v_mfma_f32_16x16x32_bf16 v[74:77], v[142:145], v[240:243], v[74:77]
	s_setprio 0
	s_setprio 1
	v_mfma_f32_16x16x32_bf16 v[118:121], v[146:149], v[176:179], v[118:121]
	v_mfma_f32_16x16x32_bf16 v[114:117], v[168:171], v[176:179], v[114:117]
	v_mfma_f32_16x16x32_bf16 v[102:105], v[146:149], v[202:205], v[102:105]
	v_mfma_f32_16x16x32_bf16 v[98:101], v[168:171], v[202:205], v[98:101]
	v_mfma_f32_16x16x32_bf16 v[86:89], v[146:149], v[210:213], v[86:89]
	v_mfma_f32_16x16x32_bf16 v[82:85], v[168:171], v[210:213], v[82:85]
	v_mfma_f32_16x16x32_bf16 v[70:73], v[146:149], v[236:239], v[70:73]
	v_mfma_f32_16x16x32_bf16 v[66:69], v[168:171], v[236:239], v[66:69]
	s_setprio 0
	s_setprio 1
	v_mfma_f32_16x16x32_bf16 v[118:121], v[150:153], v[180:183], v[118:121]
	v_mfma_f32_16x16x32_bf16 v[114:117], v[172:175], v[180:183], v[114:117]
	v_mfma_f32_16x16x32_bf16 v[102:105], v[150:153], v[206:209], v[102:105]
	v_mfma_f32_16x16x32_bf16 v[98:101], v[172:175], v[206:209], v[98:101]
	v_mfma_f32_16x16x32_bf16 v[86:89], v[150:153], v[232:235], v[86:89]
	v_mfma_f32_16x16x32_bf16 v[82:85], v[172:175], v[232:235], v[82:85]
	v_mfma_f32_16x16x32_bf16 v[70:73], v[150:153], v[240:243], v[70:73]
	v_mfma_f32_16x16x32_bf16 v[66:69], v[172:175], v[240:243], v[66:69]
	s_setprio 0
	s_barrier
; #define PG8_STAGE(bufoff, gbase, voff) do { _Pragma("unroll") for (int _i = 0; _i < 2; ++_i) \
;         __builtin_amdgcn_global_load_lds((const unsigned*)((const char*)(gbase) + (voff)[_i]), (PG8_LAS unsigned*)(lds + (bufoff) + ldsw + _i * 8192), 16, 0, 0); } while (0)
; #define PG8_LDA(dst, b, h) do { _Pragma("unroll") for (int m = 0; m < 4; ++m) _Pragma("unroll") for (int k = 0; k < 2; ++k) dst[m][k] = *(const PG8_LAS bf16x8*)(lds + PG8_SA(b, h) + aoff + m * 2048 + k * 1024); } while (0)
; #define PG8_MMA(ai, bj, At, Bt) do { __builtin_amdgcn_s_setprio(1); _Pragma("unroll") for (int m = 0; m < 4; ++m) _Pragma("unroll") for (int n = 0; n < 2; ++n) _Pragma("unroll") for (int k = 0; k < 2; ++k) \
;         acc[ai][bj][m][n] = __builtin_amdgcn_mfma_f32_16x16x32_bf16(Bt[n][k], At[m][k], acc[ai][bj][m][n], 0, 0, 0); __builtin_amdgcn_s_setprio(0); } while (0)
; #define PG8_WAIT_V(n) asm volatile("s_waitcnt vmcnt(" #n ")" ::: "memory")
; #define PG8_WAIT_L(n) asm volatile("s_waitcnt lgkmcnt(" #n ")" ::: "memory")
; #define PG8_BAR __builtin_amdgcn_s_barrier()
; #define PG8_SCHED __builtin_amdgcn_sched_barrier(0)
; template <class Epi, class Sched, bool ALIGN_EPI = false, bool SP2 = false>
; __device__ __forceinline__ void gemm_phase(PG8_LAS unsigned char* lds, const Gemm g, const Sched& S, const Epi& E) {
;     ...
;             PG8_LDA(At, 1, 1); PG8_STAGE(PG8_SB(1, 0), b3, voffB); PG8_STAGE(PG8_SB(1, 1), b3 + hstepB, voffB); PG8_STAGE(PG8_SA(1, 0), a3, voffA);
;             PG8_WAIT_V(8); PG8_WAIT_L(0); PG8_BAR; PG8_MMA(1, 0, At, B0); PG8_MMA(1, 1, At, B1); PG8_BAR; PG8_SCHED;
	s_add_i32 s18, s50, s30
	s_mov_b32 m0, s18
	ds_read_b128 v[176:179], v200 offset:49152
	ds_read_b128 v[180:183], v200 offset:50176
	ds_read_b128 v[202:205], v200 offset:51200
	ds_read_b128 v[206:209], v200 offset:52224
	ds_read_b128 v[210:213], v200 offset:53248
	ds_read_b128 v[232:235], v200 offset:54272
	ds_read_b128 v[236:239], v200 offset:55296
	ds_read_b128 v[240:243], v200 offset:56320
	global_load_lds_dwordx4 v156, s[60:61]
	s_add_i32 m0, s18, 0x2000
	s_add_u32 s18, s22, 0xb0080
	s_addc_u32 s19, s23, 0
	s_add_i32 s22, s51, s30
	global_load_lds_dwordx4 v160, s[60:61]
	s_mov_b32 m0, s22
	s_nop 0
	global_load_lds_dwordx4 v156, s[18:19]
	s_add_i32 m0, s22, 0x2000
	s_nop 0
	global_load_lds_dwordx4 v160, s[18:19]
	s_mov_b32 m0, s38
	s_nop 0
	global_load_lds_dwordx4 v154, s[62:63]
	s_mov_b32 m0, s39
	s_nop 0
	global_load_lds_dwordx4 v158, s[62:63]
	s_waitcnt vmcnt(8)
	s_waitcnt lgkmcnt(0)
	s_barrier
	s_setprio 1
	s_waitcnt lgkmcnt(0)
	v_mfma_f32_16x16x32_bf16 v[62:65], v[130:133], v[176:179], v[62:65]
	v_mfma_f32_16x16x32_bf16 v[58:61], v[138:141], v[176:179], v[58:61]
	v_mfma_f32_16x16x32_bf16 v[46:49], v[130:133], v[202:205], v[46:49]
	v_mfma_f32_16x16x32_bf16 v[42:45], v[138:141], v[202:205], v[42:45]
	v_mfma_f32_16x16x32_bf16 v[30:33], v[130:133], v[210:213], v[30:33]
	v_mfma_f32_16x16x32_bf16 v[26:29], v[138:141], v[210:213], v[26:29]
	v_mfma_f32_16x16x32_bf16 v[14:17], v[130:133], v[236:239], v[14:17]
	v_mfma_f32_16x16x32_bf16 v[10:13], v[138:141], v[236:239], v[10:13]
	s_setprio 0
	s_setprio 1
	v_mfma_f32_16x16x32_bf16 v[62:65], v[134:137], v[180:183], v[62:65]
	v_mfma_f32_16x16x32_bf16 v[58:61], v[142:145], v[180:183], v[58:61]
	v_mfma_f32_16x16x32_bf16 v[46:49], v[134:137], v[206:209], v[46:49]
	v_mfma_f32_16x16x32_bf16 v[42:45], v[142:145], v[206:209], v[42:45]
	v_mfma_f32_16x16x32_bf16 v[30:33], v[134:137], v[232:235], v[30:33]
	v_mfma_f32_16x16x32_bf16 v[26:29], v[142:145], v[232:235], v[26:29]
	v_mfma_f32_16x16x32_bf16 v[14:17], v[134:137], v[240:243], v[14:17]
	v_mfma_f32_16x16x32_bf16 v[10:13], v[142:145], v[240:243], v[10:13]
	s_setprio 0
	s_setprio 1
	v_mfma_f32_16x16x32_bf16 v[54:57], v[146:149], v[176:179], v[54:57]
	v_mfma_f32_16x16x32_bf16 v[50:53], v[168:171], v[176:179], v[50:53]
	v_mfma_f32_16x16x32_bf16 v[38:41], v[146:149], v[202:205], v[38:41]
	v_mfma_f32_16x16x32_bf16 v[34:37], v[168:171], v[202:205], v[34:37]
	v_mfma_f32_16x16x32_bf16 v[22:25], v[146:149], v[210:213], v[22:25]
	v_mfma_f32_16x16x32_bf16 v[18:21], v[168:171], v[210:213], v[18:21]
	v_mfma_f32_16x16x32_bf16 v[6:9], v[146:149], v[236:239], v[6:9]
	v_mfma_f32_16x16x32_bf16 v[2:5], v[168:171], v[236:239], v[2:5]
	s_setprio 0
	s_setprio 1
	v_mfma_f32_16x16x32_bf16 v[54:57], v[150:153], v[180:183], v[54:57]
	v_mfma_f32_16x16x32_bf16 v[50:53], v[172:175], v[180:183], v[50:53]
	v_mfma_f32_16x16x32_bf16 v[38:41], v[150:153], v[206:209], v[38:41]
	v_mfma_f32_16x16x32_bf16 v[34:37], v[172:175], v[206:209], v[34:37]
	v_mfma_f32_16x16x32_bf16 v[22:25], v[150:153], v[232:235], v[22:25]
	v_mfma_f32_16x16x32_bf16 v[18:21], v[172:175], v[232:235], v[18:21]
	v_mfma_f32_16x16x32_bf16 v[6:9], v[150:153], v[240:243], v[6:9]
	v_mfma_f32_16x16x32_bf16 v[2:5], v[172:175], v[240:243], v[2:5]
	s_setprio 0
	s_barrier
	s_add_i32 s49, s49, 2
	s_add_u32 s47, s47, 0x100
	s_addc_u32 s48, s48, 0
	s_cmp_gt_u32 s49, 41
	s_mov_b64 s[18:19], s[20:21]
	s_cbranch_scc0 .LBB0_1438
	s_and_b64 vcc, exec, s[14:15]
	s_cbranch_vccz .LBB0_1441
	s_barrier
